# speedup vs baseline: 1.0885x; 1.0061x over previous
; #define LDA8(dst, b, h)                                                                                               \
;   _Pragma("unroll") for (int m = 0; m < 4; ++m) _Pragma("unroll") for (int k = 0; k < 2; ++k)                         \
;     dst[m][k] = *(const bf16x8*)(SA8(b, h) + la + m * 2048 + k * 1024)
; #define LDB8(dst, b, h)                                                                                               \
;   _Pragma("unroll") for (int n = 0; n < 2; ++n) _Pragma("unroll") for (int k = 0; k < 2; ++k)                         \
;     dst[n][k] = *(const bf16x8*)(SB8(b, h) + lb + n * 2048 + k * 1024)
; #define WAITL8(n) asm volatile("s_waitcnt lgkmcnt(" #n ")" ::: "memory")
; #define BAR8 __builtin_amdgcn_s_barrier()
; #define SCHED8 __builtin_amdgcn_sched_barrier(0)
; template <class Epi>
; DEV void gemm_tile8(char* shm, const u16* __restrict__ A, const u16* __restrict__ Bt, int K, int brow, int bcol, Epi& epi) {
;     ...
;     LDB8(B0, 0, 0); SCHED8; LDA8(At, 0, 0); STAGE8(SA8(1, 1), A, brow + HALF, t + 1);
;     WAITL8(8); BAR8; WAITL8(0); MMA8(0, 0, At, B0); BAR8; SCHED8;
;     LDB8(B1, 0, 1); STAGE8(SB8(0, 0), Bt, bcol, t + 2);
;     BAR8; WAITL8(0); MMA8(0, 1, At, B1); BAR8;
;     LDA8(At, 0, 1); STAGE8(SA8(0, 0), A, brow, t + 2);
;     BAR8; WAITL8(0); MMA8(1, 0, At, B0); BAR8; SCHED8;
.LBB0_389:
	v_or_b32_e32 v134, 0x10000, v133
	v_add_u32_e32 v136, 0x10800, v133
	v_add_u32_e32 v135, 0x10400, v133
	ds_read_b128 v[144:147], v134
	ds_read_b128 v[148:151], v135
	v_add_u32_e32 v137, 0x10c00, v133
	ds_read_b128 v[152:155], v136
	ds_read_b128 v[156:159], v137
	v_lshl_add_u64 v[228:229], s[10:11], 0, v[130:131]
	s_add_i32 s95, s7, 0xc000
	v_lshl_add_u64 v[138:139], v[228:229], 0, vcc
	s_mov_b32 m0, s95
	s_add_i32 s27, s7, 0xe000
	ds_read_b128 v[160:163], v132
	ds_read_b128 v[164:167], v132 offset:1024
	ds_read_b128 v[168:171], v132 offset:2048
	ds_read_b128 v[172:175], v132 offset:3072
	ds_read_b128 v[176:179], v132 offset:4096
	ds_read_b128 v[180:183], v132 offset:5120
	ds_read_b128 v[184:187], v132 offset:6144
	ds_read_b128 v[188:191], v132 offset:7168
	global_load_lds_dwordx4 v[138:139], off
	v_lshl_add_u64 v[138:139], v[228:229], 0, s[14:15]
	s_mov_b32 m0, s27
	s_nop 0
	global_load_lds_dwordx4 v[138:139], off
	s_waitcnt lgkmcnt(8)
	s_barrier
	s_waitcnt lgkmcnt(0)
	s_setprio 1
	s_waitcnt lgkmcnt(0)
	v_mfma_f32_16x16x32_bf16 v[124:127], v[144:147], v[160:163], v[124:127]
	v_mfma_f32_16x16x32_bf16 v[120:123], v[152:155], v[160:163], v[120:123]
	v_mfma_f32_16x16x32_bf16 v[116:119], v[144:147], v[168:171], v[116:119]
	v_mfma_f32_16x16x32_bf16 v[112:115], v[152:155], v[168:171], v[112:115]
	v_mfma_f32_16x16x32_bf16 v[108:111], v[144:147], v[176:179], v[108:111]
	v_mfma_f32_16x16x32_bf16 v[104:107], v[152:155], v[176:179], v[104:107]
	v_mfma_f32_16x16x32_bf16 v[100:103], v[144:147], v[184:187], v[100:103]
	v_mfma_f32_16x16x32_bf16 v[96:99], v[152:155], v[184:187], v[96:99]
	v_mfma_f32_16x16x32_bf16 v[124:127], v[148:151], v[164:167], v[124:127]
	v_mfma_f32_16x16x32_bf16 v[120:123], v[156:159], v[164:167], v[120:123]
	v_mfma_f32_16x16x32_bf16 v[116:119], v[148:151], v[172:175], v[116:119]
	v_mfma_f32_16x16x32_bf16 v[112:115], v[156:159], v[172:175], v[112:115]
	v_mfma_f32_16x16x32_bf16 v[108:111], v[148:151], v[180:183], v[108:111]
	v_mfma_f32_16x16x32_bf16 v[104:107], v[156:159], v[180:183], v[104:107]
	v_mfma_f32_16x16x32_bf16 v[100:103], v[148:151], v[188:191], v[100:103]
	v_mfma_f32_16x16x32_bf16 v[96:99], v[156:159], v[188:191], v[96:99]
	s_setprio 0
	s_barrier
	v_lshl_add_u64 v[230:231], s[24:25], 0, v[130:131]
	s_mov_b64 s[96:97], 0x1f80100
	s_mov_b32 m0, s55
	v_or_b32_e32 v138, 0x14000, v133
	v_add_u32_e32 v140, 0x14800, v133
	v_lshl_add_u64 v[220:221], v[230:231], 0, s[96:97]
	s_mov_b64 s[96:97], 0x1fa0100
	v_add_u32_e32 v139, 0x14400, v133
	ds_read_b128 v[204:207], v138
	ds_read_b128 v[208:211], v139
	v_add_u32_e32 v142, 0x14c00, v133
	ds_read_b128 v[212:215], v140
	ds_read_b128 v[216:219], v142
	global_load_lds_dwordx4 v[220:221], off
	v_lshl_add_u64 v[220:221], v[230:231], 0, s[96:97]
	s_mov_b32 m0, s70
	s_nop 0
	global_load_lds_dwordx4 v[220:221], off
	s_barrier
	s_waitcnt lgkmcnt(0)
	s_setprio 1
	s_waitcnt lgkmcnt(0)
	v_mfma_f32_16x16x32_bf16 v[92:95], v[204:207], v[160:163], v[92:95]
	v_mfma_f32_16x16x32_bf16 v[88:91], v[212:215], v[160:163], v[88:91]
	v_mfma_f32_16x16x32_bf16 v[84:87], v[204:207], v[168:171], v[84:87]
	v_mfma_f32_16x16x32_bf16 v[80:83], v[212:215], v[168:171], v[80:83]
	v_mfma_f32_16x16x32_bf16 v[76:79], v[204:207], v[176:179], v[76:79]
	v_mfma_f32_16x16x32_bf16 v[72:75], v[212:215], v[176:179], v[72:75]
	v_mfma_f32_16x16x32_bf16 v[68:71], v[204:207], v[184:187], v[68:71]
	v_mfma_f32_16x16x32_bf16 v[64:67], v[212:215], v[184:187], v[64:67]
	v_mfma_f32_16x16x32_bf16 v[92:95], v[208:211], v[164:167], v[92:95]
	v_mfma_f32_16x16x32_bf16 v[88:91], v[216:219], v[164:167], v[88:91]
	v_mfma_f32_16x16x32_bf16 v[84:87], v[208:211], v[172:175], v[84:87]
	v_mfma_f32_16x16x32_bf16 v[80:83], v[216:219], v[172:175], v[80:83]
	v_mfma_f32_16x16x32_bf16 v[76:79], v[208:211], v[180:183], v[76:79]
	v_mfma_f32_16x16x32_bf16 v[72:75], v[216:219], v[180:183], v[72:75]
	v_mfma_f32_16x16x32_bf16 v[68:71], v[208:211], v[188:191], v[68:71]
	v_mfma_f32_16x16x32_bf16 v[64:67], v[216:219], v[188:191], v[64:67]
	s_setprio 0
	s_mov_b32 m0, s7
	v_lshl_add_u64 v[220:221], v[228:229], 0, s[2:3]
	s_barrier
	ds_read_b128 v[160:163], v132 offset:16384
	ds_read_b128 v[164:167], v132 offset:17408
	ds_read_b128 v[168:171], v132 offset:18432
	ds_read_b128 v[172:175], v132 offset:19456
	ds_read_b128 v[176:179], v132 offset:20480
	ds_read_b128 v[180:183], v132 offset:21504
	ds_read_b128 v[184:187], v132 offset:22528
	ds_read_b128 v[188:191], v132 offset:23552
	global_load_lds_dwordx4 v[220:221], off
	v_lshl_add_u64 v[220:221], v[228:229], 0, s[74:75]
	s_mov_b32 m0, s71
	s_nop 0
	global_load_lds_dwordx4 v[220:221], off
	s_barrier
	s_waitcnt lgkmcnt(0)
	s_setprio 1
	s_waitcnt lgkmcnt(0)
	v_mfma_f32_16x16x32_bf16 v[60:63], v[144:147], v[160:163], v[60:63]
	v_mfma_f32_16x16x32_bf16 v[56:59], v[152:155], v[160:163], v[56:59]
	v_mfma_f32_16x16x32_bf16 v[52:55], v[144:147], v[168:171], v[52:55]
	v_mfma_f32_16x16x32_bf16 v[48:51], v[152:155], v[168:171], v[48:51]
	v_mfma_f32_16x16x32_bf16 v[44:47], v[144:147], v[176:179], v[44:47]
	v_mfma_f32_16x16x32_bf16 v[40:43], v[152:155], v[176:179], v[40:43]
	v_mfma_f32_16x16x32_bf16 v[36:39], v[144:147], v[184:187], v[36:39]
	v_mfma_f32_16x16x32_bf16 v[32:35], v[152:155], v[184:187], v[32:35]
	v_mfma_f32_16x16x32_bf16 v[60:63], v[148:151], v[164:167], v[60:63]
	v_mfma_f32_16x16x32_bf16 v[56:59], v[156:159], v[164:167], v[56:59]
	v_mfma_f32_16x16x32_bf16 v[52:55], v[148:151], v[172:175], v[52:55]
	v_mfma_f32_16x16x32_bf16 v[48:51], v[156:159], v[172:175], v[48:51]
	v_mfma_f32_16x16x32_bf16 v[44:47], v[148:151], v[180:183], v[44:47]
	v_mfma_f32_16x16x32_bf16 v[40:43], v[156:159], v[180:183], v[40:43]
	v_mfma_f32_16x16x32_bf16 v[36:39], v[148:151], v[188:191], v[36:39]
	v_mfma_f32_16x16x32_bf16 v[32:35], v[156:159], v[188:191], v[32:35]
	s_setprio 0
	s_barrier
; #define LDA8(dst, b, h)                                                                                               \
;   _Pragma("unroll") for (int m = 0; m < 4; ++m) _Pragma("unroll") for (int k = 0; k < 2; ++k)                         \
;     dst[m][k] = *(const bf16x8*)(SA8(b, h) + la + m * 2048 + k * 1024)
; #define LDB8(dst, b, h)                                                                                               \
;   _Pragma("unroll") for (int n = 0; n < 2; ++n) _Pragma("unroll") for (int k = 0; k < 2; ++k)                         \
;     dst[n][k] = *(const bf16x8*)(SB8(b, h) + lb + n * 2048 + k * 1024)
; #define WAITV8(n) asm volatile("s_waitcnt vmcnt(" #n ")" ::: "memory")
; #define WAITL8(n) asm volatile("s_waitcnt lgkmcnt(" #n ")" ::: "memory")
; #define BAR8 __builtin_amdgcn_s_barrier()
; #define SCHED8 __builtin_amdgcn_sched_barrier(0)
; template <class Epi>
; DEV void gemm_tile8(char* shm, const u16* __restrict__ A, const u16* __restrict__ Bt, int K, int brow, int bcol, Epi& epi) {
;     ...
;     STAGE8(SB8(0, 1), Bt, bcol + HALF, t + 2);
;     WAITV8(6); BAR8; MMA8(1, 1, At, B1); BAR8;
;     LDB8(B0, 1, 0); SCHED8; LDA8(At, 1, 0); STAGE8(SA8(0, 1), A, brow + HALF, t + 2);
;     WAITL8(8); BAR8; WAITL8(0); MMA8(0, 0, At, B0); BAR8; SCHED8;
;     LDB8(B1, 1, 1); STAGE8(SB8(1, 0), Bt, bcol, t + 3);
;     BAR8; WAITL8(0); MMA8(0, 1, At, B1); BAR8;
	s_mov_b64 s[96:97], 0x1fc0100
	s_mov_b32 m0, s72
	v_lshl_add_u64 v[144:145], v[230:231], 0, s[96:97]
	s_mov_b64 s[96:97], 0x1fe0100
	global_load_lds_dwordx4 v[144:145], off
	v_lshl_add_u64 v[144:145], v[230:231], 0, s[96:97]
	s_mov_b32 m0, s73
	s_nop 0
	global_load_lds_dwordx4 v[144:145], off
	s_waitcnt vmcnt(6)
	s_barrier
	s_setprio 1
	v_mfma_f32_16x16x32_bf16 v[28:31], v[204:207], v[160:163], v[28:31]
	v_mfma_f32_16x16x32_bf16 v[24:27], v[212:215], v[160:163], v[24:27]
	v_mfma_f32_16x16x32_bf16 v[20:23], v[204:207], v[168:171], v[20:23]
	v_mfma_f32_16x16x32_bf16 v[16:19], v[212:215], v[168:171], v[16:19]
	v_mfma_f32_16x16x32_bf16 v[12:15], v[204:207], v[176:179], v[12:15]
	v_mfma_f32_16x16x32_bf16 v[8:11], v[212:215], v[176:179], v[8:11]
	v_mfma_f32_16x16x32_bf16 v[4:7], v[204:207], v[184:187], v[4:7]
	v_mfma_f32_16x16x32_bf16 v[0:3], v[212:215], v[184:187], v[0:3]
	v_mfma_f32_16x16x32_bf16 v[28:31], v[208:211], v[164:167], v[28:31]
	v_mfma_f32_16x16x32_bf16 v[24:27], v[216:219], v[164:167], v[24:27]
	v_mfma_f32_16x16x32_bf16 v[20:23], v[208:211], v[172:175], v[20:23]
	v_mfma_f32_16x16x32_bf16 v[16:19], v[216:219], v[172:175], v[16:19]
	v_mfma_f32_16x16x32_bf16 v[12:15], v[208:211], v[180:183], v[12:15]
	v_mfma_f32_16x16x32_bf16 v[8:11], v[216:219], v[180:183], v[8:11]
	v_mfma_f32_16x16x32_bf16 v[4:7], v[208:211], v[188:191], v[4:7]
	v_mfma_f32_16x16x32_bf16 v[0:3], v[216:219], v[188:191], v[0:3]
	s_setprio 0
	v_or_b32_e32 v143, 0x18000, v133
	v_add_u32_e32 v145, 0x18800, v133
	s_barrier
	v_add_u32_e32 v144, 0x18400, v133
	ds_read_b128 v[152:155], v143
	ds_read_b128 v[156:159], v144
	v_add_u32_e32 v146, 0x18c00, v133
	ds_read_b128 v[160:163], v145
	ds_read_b128 v[164:167], v146
	s_mov_b32 m0, s81
	v_lshl_add_u64 v[148:149], v[228:229], 0, s[18:19]
	ds_read_b128 v[168:171], v132 offset:32768
	ds_read_b128 v[172:175], v132 offset:33792
	ds_read_b128 v[176:179], v132 offset:34816
	ds_read_b128 v[180:183], v132 offset:35840
	ds_read_b128 v[184:187], v132 offset:36864
	ds_read_b128 v[188:191], v132 offset:37888
	ds_read_b128 v[204:207], v132 offset:38912
	ds_read_b128 v[208:211], v132 offset:39936
	global_load_lds_dwordx4 v[148:149], off
	v_lshl_add_u64 v[148:149], v[228:229], 0, s[22:23]
	s_mov_b32 m0, s84
	s_nop 0
	global_load_lds_dwordx4 v[148:149], off
	s_waitcnt lgkmcnt(8)
	s_barrier
	s_waitcnt lgkmcnt(0)
	s_setprio 1
	s_waitcnt lgkmcnt(0)
	v_mfma_f32_16x16x32_bf16 v[124:127], v[152:155], v[168:171], v[124:127]
	v_mfma_f32_16x16x32_bf16 v[120:123], v[160:163], v[168:171], v[120:123]
	v_mfma_f32_16x16x32_bf16 v[116:119], v[152:155], v[176:179], v[116:119]
	v_mfma_f32_16x16x32_bf16 v[112:115], v[160:163], v[176:179], v[112:115]
	v_mfma_f32_16x16x32_bf16 v[108:111], v[152:155], v[184:187], v[108:111]
	v_mfma_f32_16x16x32_bf16 v[104:107], v[160:163], v[184:187], v[104:107]
	v_mfma_f32_16x16x32_bf16 v[100:103], v[152:155], v[204:207], v[100:103]
	v_mfma_f32_16x16x32_bf16 v[96:99], v[160:163], v[204:207], v[96:99]
	v_mfma_f32_16x16x32_bf16 v[124:127], v[156:159], v[172:175], v[124:127]
	v_mfma_f32_16x16x32_bf16 v[120:123], v[164:167], v[172:175], v[120:123]
	v_mfma_f32_16x16x32_bf16 v[116:119], v[156:159], v[180:183], v[116:119]
	v_mfma_f32_16x16x32_bf16 v[112:115], v[164:167], v[180:183], v[112:115]
	v_mfma_f32_16x16x32_bf16 v[108:111], v[156:159], v[188:191], v[108:111]
	v_mfma_f32_16x16x32_bf16 v[104:107], v[164:167], v[188:191], v[104:107]
	v_mfma_f32_16x16x32_bf16 v[100:103], v[156:159], v[208:211], v[100:103]
	v_mfma_f32_16x16x32_bf16 v[96:99], v[164:167], v[208:211], v[96:99]
	s_setprio 0
	s_barrier
	s_mov_b64 s[96:97], 0x1f80180
	s_mov_b32 m0, s85
	v_or_b32_e32 v147, 0x1c000, v133
	v_add_u32_e32 v149, 0x1c800, v133
	v_lshl_add_u64 v[232:233], v[230:231], 0, s[96:97]
	s_mov_b64 s[96:97], 0x1fa0180
	v_add_u32_e32 v148, 0x1c400, v133
	ds_read_b128 v[212:215], v147
	ds_read_b128 v[216:219], v148
	v_add_u32_e32 v150, 0x1cc00, v133
	ds_read_b128 v[220:223], v149
	ds_read_b128 v[224:227], v150
	global_load_lds_dwordx4 v[232:233], off
	v_lshl_add_u64 v[232:233], v[230:231], 0, s[96:97]
	s_mov_b32 m0, s90
	s_nop 0
	global_load_lds_dwordx4 v[232:233], off
	s_barrier
	s_waitcnt lgkmcnt(0)
	s_setprio 1
	s_waitcnt lgkmcnt(0)
	v_mfma_f32_16x16x32_bf16 v[92:95], v[212:215], v[168:171], v[92:95]
	v_mfma_f32_16x16x32_bf16 v[88:91], v[220:223], v[168:171], v[88:91]
	v_mfma_f32_16x16x32_bf16 v[84:87], v[212:215], v[176:179], v[84:87]
	v_mfma_f32_16x16x32_bf16 v[80:83], v[220:223], v[176:179], v[80:83]
	v_mfma_f32_16x16x32_bf16 v[76:79], v[212:215], v[184:187], v[76:79]
	v_mfma_f32_16x16x32_bf16 v[72:75], v[220:223], v[184:187], v[72:75]
	v_mfma_f32_16x16x32_bf16 v[68:71], v[212:215], v[204:207], v[68:71]
	v_mfma_f32_16x16x32_bf16 v[64:67], v[220:223], v[204:207], v[64:67]
	v_mfma_f32_16x16x32_bf16 v[92:95], v[216:219], v[172:175], v[92:95]
	v_mfma_f32_16x16x32_bf16 v[88:91], v[224:227], v[172:175], v[88:91]
	v_mfma_f32_16x16x32_bf16 v[84:87], v[216:219], v[180:183], v[84:87]
	v_mfma_f32_16x16x32_bf16 v[80:83], v[224:227], v[180:183], v[80:83]
	v_mfma_f32_16x16x32_bf16 v[76:79], v[216:219], v[188:191], v[76:79]
	v_mfma_f32_16x16x32_bf16 v[72:75], v[224:227], v[188:191], v[72:75]
	v_mfma_f32_16x16x32_bf16 v[68:71], v[216:219], v[208:211], v[68:71]
	v_mfma_f32_16x16x32_bf16 v[64:67], v[224:227], v[208:211], v[64:67]
	s_setprio 0
	s_mov_b32 m0, s91
	v_lshl_add_u64 v[232:233], v[228:229], 0, s[64:65]
	s_barrier
; #define LDA8(dst, b, h)                                                                                               \
;   _Pragma("unroll") for (int m = 0; m < 4; ++m) _Pragma("unroll") for (int k = 0; k < 2; ++k)                         \
;     dst[m][k] = *(const bf16x8*)(SA8(b, h) + la + m * 2048 + k * 1024)
; #define LDB8(dst, b, h)                                                                                               \
;   _Pragma("unroll") for (int n = 0; n < 2; ++n) _Pragma("unroll") for (int k = 0; k < 2; ++k)                         \
;     dst[n][k] = *(const bf16x8*)(SB8(b, h) + lb + n * 2048 + k * 1024)
; #define WAITV8(n) asm volatile("s_waitcnt vmcnt(" #n ")" ::: "memory")
; #define WAITL8(n) asm volatile("s_waitcnt lgkmcnt(" #n ")" ::: "memory")
; #define BAR8 __builtin_amdgcn_s_barrier()
; #define SCHED8 __builtin_amdgcn_sched_barrier(0)
; template <class Epi>
; DEV void gemm_tile8(char* shm, const u16* __restrict__ A, const u16* __restrict__ Bt, int K, int brow, int bcol, Epi& epi) {
;     ...
;     LDA8(At, 1, 1); STAGE8(SA8(1, 0), A, brow, t + 3);
;     BAR8; WAITL8(0); MMA8(1, 0, At, B0); BAR8; SCHED8;
;     STAGE8(SB8(1, 1), Bt, bcol + HALF, t + 3);
;     WAITV8(6); BAR8; MMA8(1, 1, At, B1); BAR8;
;   }
;   { LDB8(B0, 0, 0); LDA8(At, 0, 0); STAGE8(SA8(1, 1), A, brow + HALF, nt - 1);
;     BAR8; WAITL8(0); MMA8(0, 0, At, B0); BAR8;
;     LDB8(B1, 0, 1); BAR8; WAITL8(0); MMA8(0, 1, At, B1); BAR8;
	ds_read_b128 v[168:171], v132 offset:49152
	ds_read_b128 v[172:175], v132 offset:50176
	ds_read_b128 v[176:179], v132 offset:51200
	ds_read_b128 v[180:183], v132 offset:52224
	ds_read_b128 v[184:187], v132 offset:53248
	ds_read_b128 v[188:191], v132 offset:54272
	ds_read_b128 v[204:207], v132 offset:55296
	ds_read_b128 v[208:211], v132 offset:56320
	global_load_lds_dwordx4 v[232:233], off
	v_lshl_add_u64 v[228:229], v[228:229], 0, s[82:83]
	s_mov_b32 m0, s92
	s_nop 0
	global_load_lds_dwordx4 v[228:229], off
	s_barrier
	s_waitcnt lgkmcnt(0)
	s_setprio 1
	s_waitcnt lgkmcnt(0)
	v_mfma_f32_16x16x32_bf16 v[60:63], v[152:155], v[168:171], v[60:63]
	v_mfma_f32_16x16x32_bf16 v[56:59], v[160:163], v[168:171], v[56:59]
	v_mfma_f32_16x16x32_bf16 v[52:55], v[152:155], v[176:179], v[52:55]
	v_mfma_f32_16x16x32_bf16 v[48:51], v[160:163], v[176:179], v[48:51]
	v_mfma_f32_16x16x32_bf16 v[44:47], v[152:155], v[184:187], v[44:47]
	v_mfma_f32_16x16x32_bf16 v[40:43], v[160:163], v[184:187], v[40:43]
	v_mfma_f32_16x16x32_bf16 v[36:39], v[152:155], v[204:207], v[36:39]
	v_mfma_f32_16x16x32_bf16 v[32:35], v[160:163], v[204:207], v[32:35]
	v_mfma_f32_16x16x32_bf16 v[60:63], v[156:159], v[172:175], v[60:63]
	v_mfma_f32_16x16x32_bf16 v[56:59], v[164:167], v[172:175], v[56:59]
	v_mfma_f32_16x16x32_bf16 v[52:55], v[156:159], v[180:183], v[52:55]
	v_mfma_f32_16x16x32_bf16 v[48:51], v[164:167], v[180:183], v[48:51]
	v_mfma_f32_16x16x32_bf16 v[44:47], v[156:159], v[188:191], v[44:47]
	v_mfma_f32_16x16x32_bf16 v[40:43], v[164:167], v[188:191], v[40:43]
	v_mfma_f32_16x16x32_bf16 v[36:39], v[156:159], v[208:211], v[36:39]
	v_mfma_f32_16x16x32_bf16 v[32:35], v[164:167], v[208:211], v[32:35]
	s_setprio 0
	s_barrier
	s_mov_b64 s[96:97], 0x1fc0180
	s_mov_b32 m0, s93
	v_lshl_add_u64 v[152:153], v[230:231], 0, s[96:97]
	s_mov_b64 s[96:97], 0x1fe0180
	global_load_lds_dwordx4 v[152:153], off
	v_lshl_add_u64 v[152:153], v[230:231], 0, s[96:97]
	s_mov_b32 m0, s94
	s_nop 0
	global_load_lds_dwordx4 v[152:153], off
	s_waitcnt vmcnt(6)
	s_barrier
	s_setprio 1
	v_mfma_f32_16x16x32_bf16 v[28:31], v[212:215], v[168:171], v[28:31]
	v_mfma_f32_16x16x32_bf16 v[24:27], v[220:223], v[168:171], v[24:27]
	v_mfma_f32_16x16x32_bf16 v[20:23], v[212:215], v[176:179], v[20:23]
	v_mfma_f32_16x16x32_bf16 v[16:19], v[220:223], v[176:179], v[16:19]
	v_mfma_f32_16x16x32_bf16 v[12:15], v[212:215], v[184:187], v[12:15]
	v_mfma_f32_16x16x32_bf16 v[8:11], v[220:223], v[184:187], v[8:11]
	v_mfma_f32_16x16x32_bf16 v[4:7], v[212:215], v[204:207], v[4:7]
	v_mfma_f32_16x16x32_bf16 v[0:3], v[220:223], v[204:207], v[0:3]
	v_mfma_f32_16x16x32_bf16 v[28:31], v[216:219], v[172:175], v[28:31]
	v_mfma_f32_16x16x32_bf16 v[24:27], v[224:227], v[172:175], v[24:27]
	v_mfma_f32_16x16x32_bf16 v[20:23], v[216:219], v[180:183], v[20:23]
	v_mfma_f32_16x16x32_bf16 v[16:19], v[224:227], v[180:183], v[16:19]
	v_mfma_f32_16x16x32_bf16 v[12:15], v[216:219], v[188:191], v[12:15]
	v_mfma_f32_16x16x32_bf16 v[8:11], v[224:227], v[188:191], v[8:11]
	v_mfma_f32_16x16x32_bf16 v[4:7], v[216:219], v[208:211], v[4:7]
	v_mfma_f32_16x16x32_bf16 v[0:3], v[224:227], v[208:211], v[0:3]
	s_setprio 0
	s_add_i32 s26, s26, 2
	s_add_u32 s10, s10, 0x100
	s_addc_u32 s11, s11, 0
	s_add_u32 s24, s24, 0x100
	s_addc_u32 s25, s25, 0
	s_cmp_lt_u32 s26, 12
	s_barrier
	s_cbranch_scc1 .LBB0_389
	s_mov_b64 s[10:11], 0x780
	s_mov_b32 m0, s95
	v_lshl_add_u64 v[130:131], v[128:129], 0, s[10:11]
	s_mov_b64 s[10:11], 0x20780
	ds_read_b128 v[152:155], v134
	ds_read_b128 v[156:159], v135
	ds_read_b128 v[160:163], v136
	ds_read_b128 v[134:137], v137
	ds_read_b128 v[164:167], v132
	ds_read_b128 v[168:171], v132 offset:1024
	ds_read_b128 v[172:175], v132 offset:2048
	ds_read_b128 v[176:179], v132 offset:3072
	ds_read_b128 v[180:183], v132 offset:4096
	ds_read_b128 v[184:187], v132 offset:5120
	ds_read_b128 v[188:191], v132 offset:6144
	ds_read_b128 v[204:207], v132 offset:7168
	global_load_lds_dwordx4 v[130:131], off
	v_lshl_add_u64 v[128:129], v[128:129], 0, s[10:11]
	s_mov_b32 m0, s27
	s_nop 0
	global_load_lds_dwordx4 v[128:129], off
	s_barrier
	s_waitcnt lgkmcnt(0)
	s_setprio 1
	s_waitcnt lgkmcnt(0)
	v_mfma_f32_16x16x32_bf16 v[124:127], v[152:155], v[164:167], v[124:127]
	v_mfma_f32_16x16x32_bf16 v[120:123], v[160:163], v[164:167], v[120:123]
	v_mfma_f32_16x16x32_bf16 v[116:119], v[152:155], v[172:175], v[116:119]
	v_mfma_f32_16x16x32_bf16 v[112:115], v[160:163], v[172:175], v[112:115]
	v_mfma_f32_16x16x32_bf16 v[108:111], v[152:155], v[180:183], v[108:111]
	v_mfma_f32_16x16x32_bf16 v[104:107], v[160:163], v[180:183], v[104:107]
	v_mfma_f32_16x16x32_bf16 v[100:103], v[152:155], v[188:191], v[100:103]
	v_mfma_f32_16x16x32_bf16 v[96:99], v[160:163], v[188:191], v[96:99]
	v_mfma_f32_16x16x32_bf16 v[124:127], v[156:159], v[168:171], v[124:127]
	v_mfma_f32_16x16x32_bf16 v[120:123], v[134:137], v[168:171], v[120:123]
	v_mfma_f32_16x16x32_bf16 v[116:119], v[156:159], v[176:179], v[116:119]
	v_mfma_f32_16x16x32_bf16 v[112:115], v[134:137], v[176:179], v[112:115]
	v_mfma_f32_16x16x32_bf16 v[108:111], v[156:159], v[184:187], v[108:111]
	v_mfma_f32_16x16x32_bf16 v[104:107], v[134:137], v[184:187], v[104:107]
	v_mfma_f32_16x16x32_bf16 v[100:103], v[156:159], v[204:207], v[100:103]
	v_mfma_f32_16x16x32_bf16 v[96:99], v[134:137], v[204:207], v[96:99]
	s_setprio 0
	s_barrier
	ds_read_b128 v[128:131], v138
	ds_read_b128 v[208:211], v139
	ds_read_b128 v[212:215], v140
	ds_read_b128 v[216:219], v142
	s_barrier
; #define LDA8(dst, b, h)                                                                                               \
;   _Pragma("unroll") for (int m = 0; m < 4; ++m) _Pragma("unroll") for (int k = 0; k < 2; ++k)                         \
;     dst[m][k] = *(const bf16x8*)(SA8(b, h) + la + m * 2048 + k * 1024)
; #define LDB8(dst, b, h)                                                                                               \
;   _Pragma("unroll") for (int n = 0; n < 2; ++n) _Pragma("unroll") for (int k = 0; k < 2; ++k)                         \
;     dst[n][k] = *(const bf16x8*)(SB8(b, h) + lb + n * 2048 + k * 1024)
; #define WAITV8(n) asm volatile("s_waitcnt vmcnt(" #n ")" ::: "memory")
; #define WAITL8(n) asm volatile("s_waitcnt lgkmcnt(" #n ")" ::: "memory")
; #define BAR8 __builtin_amdgcn_s_barrier()
; template <class Epi>
; DEV void gemm_tile8(char* shm, const u16* __restrict__ A, const u16* __restrict__ Bt, int K, int brow, int bcol, Epi& epi) {
;     ...
;     LDB8(B1, 0, 1); BAR8; WAITL8(0); MMA8(0, 1, At, B1); BAR8;
;     LDA8(At, 0, 1); WAITV8(4); BAR8; WAITL8(0); MMA8(1, 0, At, B0); MMA8(1, 1, At, B1); BAR8; }
;   { LDB8(B0, 1, 0); LDA8(At, 1, 0); WAITV8(2); BAR8; WAITL8(0); MMA8(0, 0, At, B0); BAR8;
	s_waitcnt lgkmcnt(0)
	s_setprio 1
	s_waitcnt lgkmcnt(3)
	v_mfma_f32_16x16x32_bf16 v[92:95], v[128:131], v[164:167], v[92:95]
	s_waitcnt lgkmcnt(1)
	v_mfma_f32_16x16x32_bf16 v[88:91], v[212:215], v[164:167], v[88:91]
	v_mfma_f32_16x16x32_bf16 v[84:87], v[128:131], v[172:175], v[84:87]
	v_mfma_f32_16x16x32_bf16 v[80:83], v[212:215], v[172:175], v[80:83]
	v_mfma_f32_16x16x32_bf16 v[76:79], v[128:131], v[180:183], v[76:79]
	v_mfma_f32_16x16x32_bf16 v[72:75], v[212:215], v[180:183], v[72:75]
	v_mfma_f32_16x16x32_bf16 v[68:71], v[128:131], v[188:191], v[68:71]
	v_mfma_f32_16x16x32_bf16 v[64:67], v[212:215], v[188:191], v[64:67]
	v_mfma_f32_16x16x32_bf16 v[220:223], v[208:211], v[168:171], v[92:95]
	s_waitcnt lgkmcnt(0)
	v_mfma_f32_16x16x32_bf16 v[164:167], v[216:219], v[168:171], v[88:91]
	v_mfma_f32_16x16x32_bf16 v[168:171], v[208:211], v[176:179], v[84:87]
	v_mfma_f32_16x16x32_bf16 v[172:175], v[216:219], v[176:179], v[80:83]
	v_mfma_f32_16x16x32_bf16 v[176:179], v[208:211], v[184:187], v[76:79]
	v_mfma_f32_16x16x32_bf16 v[180:183], v[216:219], v[184:187], v[72:75]
	v_mfma_f32_16x16x32_bf16 v[184:187], v[208:211], v[204:207], v[68:71]
	v_mfma_f32_16x16x32_bf16 v[188:191], v[216:219], v[204:207], v[64:67]
	s_setprio 0
	s_barrier
	s_nop 0
	ds_read_b128 v[64:67], v132 offset:16384
	ds_read_b128 v[68:71], v132 offset:17408
	ds_read_b128 v[72:75], v132 offset:18432
	ds_read_b128 v[76:79], v132 offset:19456
	ds_read_b128 v[80:83], v132 offset:20480
	ds_read_b128 v[84:87], v132 offset:21504
	ds_read_b128 v[88:91], v132 offset:22528
	ds_read_b128 v[92:95], v132 offset:23552
	s_waitcnt vmcnt(4)
	s_barrier
	s_waitcnt lgkmcnt(0)
	s_setprio 1
	s_waitcnt lgkmcnt(7)
	v_mfma_f32_16x16x32_bf16 v[60:63], v[152:155], v[64:67], v[60:63]
	v_mfma_f32_16x16x32_bf16 v[56:59], v[160:163], v[64:67], v[56:59]
	s_waitcnt lgkmcnt(5)
	v_mfma_f32_16x16x32_bf16 v[52:55], v[152:155], v[72:75], v[52:55]
	v_mfma_f32_16x16x32_bf16 v[48:51], v[160:163], v[72:75], v[48:51]
	s_waitcnt lgkmcnt(3)
	v_mfma_f32_16x16x32_bf16 v[44:47], v[152:155], v[80:83], v[44:47]
	v_mfma_f32_16x16x32_bf16 v[40:43], v[160:163], v[80:83], v[40:43]
	s_waitcnt lgkmcnt(1)
	v_mfma_f32_16x16x32_bf16 v[36:39], v[152:155], v[88:91], v[36:39]
	v_mfma_f32_16x16x32_bf16 v[32:35], v[160:163], v[88:91], v[32:35]
	v_mfma_f32_16x16x32_bf16 v[60:63], v[156:159], v[68:71], v[60:63]
	v_mfma_f32_16x16x32_bf16 v[56:59], v[134:137], v[68:71], v[56:59]
	v_mfma_f32_16x16x32_bf16 v[52:55], v[156:159], v[76:79], v[52:55]
	v_mfma_f32_16x16x32_bf16 v[48:51], v[134:137], v[76:79], v[48:51]
	v_mfma_f32_16x16x32_bf16 v[44:47], v[156:159], v[84:87], v[44:47]
	v_mfma_f32_16x16x32_bf16 v[40:43], v[134:137], v[84:87], v[40:43]
	s_waitcnt lgkmcnt(0)
	v_mfma_f32_16x16x32_bf16 v[36:39], v[156:159], v[92:95], v[36:39]
	v_mfma_f32_16x16x32_bf16 v[32:35], v[134:137], v[92:95], v[32:35]
	s_setprio 0
	s_setprio 1
	v_mfma_f32_16x16x32_bf16 v[28:31], v[128:131], v[64:67], v[28:31]
	v_mfma_f32_16x16x32_bf16 v[24:27], v[212:215], v[64:67], v[24:27]
	v_mfma_f32_16x16x32_bf16 v[20:23], v[128:131], v[72:75], v[20:23]
	v_mfma_f32_16x16x32_bf16 v[16:19], v[212:215], v[72:75], v[16:19]
	v_mfma_f32_16x16x32_bf16 v[12:15], v[128:131], v[80:83], v[12:15]
	v_mfma_f32_16x16x32_bf16 v[8:11], v[212:215], v[80:83], v[8:11]
	v_mfma_f32_16x16x32_bf16 v[4:7], v[128:131], v[88:91], v[4:7]
	v_mfma_f32_16x16x32_bf16 v[0:3], v[212:215], v[88:91], v[0:3]
	v_mfma_f32_16x16x32_bf16 v[134:137], v[208:211], v[68:71], v[28:31]
	v_mfma_f32_16x16x32_bf16 v[152:155], v[216:219], v[68:71], v[24:27]
	v_mfma_f32_16x16x32_bf16 v[156:159], v[208:211], v[76:79], v[20:23]
	v_mfma_f32_16x16x32_bf16 v[160:163], v[216:219], v[76:79], v[16:19]
	v_mfma_f32_16x16x32_bf16 v[204:207], v[208:211], v[84:87], v[12:15]
	v_mfma_f32_16x16x32_bf16 v[224:227], v[216:219], v[84:87], v[8:11]
	v_mfma_f32_16x16x32_bf16 v[128:131], v[208:211], v[92:95], v[4:7]
	v_mfma_f32_16x16x32_bf16 v[208:211], v[216:219], v[92:95], v[0:3]
	s_setprio 0
	s_barrier
	ds_read_b128 v[24:27], v143
	ds_read_b128 v[28:31], v144
	ds_read_b128 v[142:145], v145
	ds_read_b128 v[212:215], v146
	ds_read_b128 v[0:3], v132 offset:32768
	ds_read_b128 v[4:7], v132 offset:33792
	ds_read_b128 v[8:11], v132 offset:34816
	ds_read_b128 v[12:15], v132 offset:35840
	ds_read_b128 v[16:19], v132 offset:36864
	ds_read_b128 v[20:23], v132 offset:37888
	ds_read_b128 v[216:219], v132 offset:38912
	ds_read_b128 v[228:231], v132 offset:39936
	s_waitcnt vmcnt(2)
	s_barrier
; #define LDA8(dst, b, h)                                                                                               \
;   _Pragma("unroll") for (int m = 0; m < 4; ++m) _Pragma("unroll") for (int k = 0; k < 2; ++k)                         \
;     dst[m][k] = *(const bf16x8*)(SA8(b, h) + la + m * 2048 + k * 1024)
; #define LDB8(dst, b, h)                                                                                               \
;   _Pragma("unroll") for (int n = 0; n < 2; ++n) _Pragma("unroll") for (int k = 0; k < 2; ++k)                         \
;     dst[n][k] = *(const bf16x8*)(SB8(b, h) + lb + n * 2048 + k * 1024)
; #define WAITV8(n) asm volatile("s_waitcnt vmcnt(" #n ")" ::: "memory")
; #define WAITL8(n) asm volatile("s_waitcnt lgkmcnt(" #n ")" ::: "memory")
; #define BAR8 __builtin_amdgcn_s_barrier()
; template <class Epi>
; DEV void gemm_tile8(char* shm, const u16* __restrict__ A, const u16* __restrict__ Bt, int K, int brow, int bcol, Epi& epi) {
;     ...
;   { LDB8(B0, 1, 0); LDA8(At, 1, 0); WAITV8(2); BAR8; WAITL8(0); MMA8(0, 0, At, B0); BAR8;
;     LDB8(B1, 1, 1); WAITV8(0); BAR8; WAITL8(0); MMA8(0, 1, At, B1); BAR8;
;     LDA8(At, 1, 1); BAR8; WAITL8(0); MMA8(1, 0, At, B0); MMA8(1, 1, At, B1); BAR8; }
;   if (wrs == 0) BAR8;
	s_waitcnt lgkmcnt(0)
	s_setprio 1
	s_waitcnt lgkmcnt(7)
	v_mfma_f32_16x16x32_bf16 v[64:67], v[24:27], v[0:3], v[124:127]
	s_waitcnt lgkmcnt(6)
	v_mfma_f32_16x16x32_bf16 v[72:75], v[28:31], v[4:7], v[64:67]
	v_mfma_f32_16x16x32_bf16 v[64:67], v[142:145], v[0:3], v[120:123]
	s_waitcnt lgkmcnt(5)
	v_mfma_f32_16x16x32_bf16 v[68:71], v[24:27], v[8:11], v[116:119]
	v_mfma_f32_16x16x32_bf16 v[76:79], v[142:145], v[8:11], v[112:115]
	s_waitcnt lgkmcnt(3)
	v_mfma_f32_16x16x32_bf16 v[80:83], v[24:27], v[16:19], v[108:111]
	v_mfma_f32_16x16x32_bf16 v[84:87], v[142:145], v[16:19], v[104:107]
	s_waitcnt lgkmcnt(1)
	v_mfma_f32_16x16x32_bf16 v[88:91], v[24:27], v[216:219], v[100:103]
	v_mfma_f32_16x16x32_bf16 v[92:95], v[142:145], v[216:219], v[96:99]
	v_mfma_f32_16x16x32_bf16 v[64:67], v[212:215], v[4:7], v[64:67]
	v_mfma_f32_16x16x32_bf16 v[68:71], v[28:31], v[12:15], v[68:71]
	v_mfma_f32_16x16x32_bf16 v[76:79], v[212:215], v[12:15], v[76:79]
	v_mfma_f32_16x16x32_bf16 v[80:83], v[28:31], v[20:23], v[80:83]
	v_mfma_f32_16x16x32_bf16 v[84:87], v[212:215], v[20:23], v[84:87]
	s_waitcnt lgkmcnt(0)
	v_mfma_f32_16x16x32_bf16 v[88:91], v[28:31], v[228:231], v[88:91]
	v_mfma_f32_16x16x32_bf16 v[92:95], v[212:215], v[228:231], v[92:95]
	s_setprio 0
	s_barrier
	ds_read_b128 v[232:235], v147
	ds_read_b128 v[236:239], v148
	ds_read_b128 v[146:149], v149
	ds_read_b128 v[240:243], v150
	s_waitcnt vmcnt(0)
	s_barrier
	s_waitcnt lgkmcnt(0)
	s_setprio 1
	s_waitcnt lgkmcnt(3)
	v_mfma_f32_16x16x32_bf16 v[96:99], v[232:235], v[0:3], v[220:223]
	s_waitcnt lgkmcnt(1)
	v_mfma_f32_16x16x32_bf16 v[0:3], v[146:149], v[0:3], v[164:167]
	v_mfma_f32_16x16x32_bf16 v[104:107], v[236:239], v[4:7], v[96:99]
	s_waitcnt lgkmcnt(0)
	v_mfma_f32_16x16x32_bf16 v[96:99], v[240:243], v[4:7], v[0:3]
	v_mfma_f32_16x16x32_bf16 v[0:3], v[232:235], v[8:11], v[168:171]
	v_mfma_f32_16x16x32_bf16 v[100:103], v[236:239], v[12:15], v[0:3]
	v_mfma_f32_16x16x32_bf16 v[0:3], v[146:149], v[8:11], v[172:175]
	v_mfma_f32_16x16x32_bf16 v[108:111], v[240:243], v[12:15], v[0:3]
	v_mfma_f32_16x16x32_bf16 v[0:3], v[232:235], v[16:19], v[176:179]
	v_mfma_f32_16x16x32_bf16 v[112:115], v[236:239], v[20:23], v[0:3]
	v_mfma_f32_16x16x32_bf16 v[0:3], v[146:149], v[16:19], v[180:183]
	v_mfma_f32_16x16x32_bf16 v[116:119], v[240:243], v[20:23], v[0:3]
	v_mfma_f32_16x16x32_bf16 v[0:3], v[232:235], v[216:219], v[184:187]
	v_mfma_f32_16x16x32_bf16 v[120:123], v[236:239], v[228:231], v[0:3]
	v_mfma_f32_16x16x32_bf16 v[0:3], v[146:149], v[216:219], v[188:191]
	v_mfma_f32_16x16x32_bf16 v[124:127], v[240:243], v[228:231], v[0:3]
	s_setprio 0
	s_barrier
	ds_read_b128 v[164:167], v132 offset:49152
	ds_read_b128 v[168:171], v132 offset:50176
	ds_read_b128 v[172:175], v132 offset:51200
	ds_read_b128 v[176:179], v132 offset:52224
	ds_read_b128 v[180:183], v132 offset:53248
	ds_read_b128 v[184:187], v132 offset:54272
	ds_read_b128 v[188:191], v132 offset:55296
	ds_read_b128 v[216:219], v132 offset:56320
	s_barrier
	s_waitcnt lgkmcnt(0)
	s_setprio 1
	s_waitcnt lgkmcnt(7)
	v_mfma_f32_16x16x32_bf16 v[0:3], v[24:27], v[164:167], v[60:63]
	s_waitcnt lgkmcnt(5)
	v_mfma_f32_16x16x32_bf16 v[8:11], v[24:27], v[172:175], v[52:55]
	s_waitcnt lgkmcnt(3)
	v_mfma_f32_16x16x32_bf16 v[16:19], v[24:27], v[180:183], v[44:47]
	s_waitcnt lgkmcnt(1)
	v_mfma_f32_16x16x32_bf16 v[24:27], v[24:27], v[188:191], v[36:39]
	v_mfma_f32_16x16x32_bf16 v[0:3], v[28:31], v[168:171], v[0:3]
	v_mfma_f32_16x16x32_bf16 v[4:7], v[142:145], v[164:167], v[56:59]
	v_mfma_f32_16x16x32_bf16 v[8:11], v[28:31], v[176:179], v[8:11]
	v_mfma_f32_16x16x32_bf16 v[12:15], v[142:145], v[172:175], v[48:51]
	v_mfma_f32_16x16x32_bf16 v[16:19], v[28:31], v[184:187], v[16:19]
	v_mfma_f32_16x16x32_bf16 v[20:23], v[142:145], v[180:183], v[40:43]
	s_waitcnt lgkmcnt(0)
	v_mfma_f32_16x16x32_bf16 v[24:27], v[28:31], v[216:219], v[24:27]
	v_mfma_f32_16x16x32_bf16 v[28:31], v[142:145], v[188:191], v[32:35]
	v_mfma_f32_16x16x32_bf16 v[4:7], v[212:215], v[168:171], v[4:7]
	v_mfma_f32_16x16x32_bf16 v[12:15], v[212:215], v[176:179], v[12:15]
	v_mfma_f32_16x16x32_bf16 v[20:23], v[212:215], v[184:187], v[20:23]
	v_mfma_f32_16x16x32_bf16 v[28:31], v[212:215], v[216:219], v[28:31]
	s_setprio 0
	s_setprio 1
	v_mfma_f32_16x16x32_bf16 v[32:35], v[232:235], v[164:167], v[134:137]
	v_mfma_f32_16x16x32_bf16 v[36:39], v[146:149], v[164:167], v[152:155]
	v_mfma_f32_16x16x32_bf16 v[40:43], v[232:235], v[172:175], v[156:159]
	v_mfma_f32_16x16x32_bf16 v[44:47], v[146:149], v[172:175], v[160:163]
	v_mfma_f32_16x16x32_bf16 v[48:51], v[232:235], v[180:183], v[204:207]
	v_mfma_f32_16x16x32_bf16 v[52:55], v[146:149], v[180:183], v[224:227]
	v_mfma_f32_16x16x32_bf16 v[56:59], v[232:235], v[188:191], v[128:131]
	v_mfma_f32_16x16x32_bf16 v[60:63], v[146:149], v[188:191], v[208:211]
	v_mfma_f32_16x16x32_bf16 v[32:35], v[236:239], v[168:171], v[32:35]
	v_mfma_f32_16x16x32_bf16 v[36:39], v[240:243], v[168:171], v[36:39]
	v_mfma_f32_16x16x32_bf16 v[40:43], v[236:239], v[176:179], v[40:43]
	v_mfma_f32_16x16x32_bf16 v[44:47], v[240:243], v[176:179], v[44:47]
	v_mfma_f32_16x16x32_bf16 v[48:51], v[236:239], v[184:187], v[48:51]
	v_mfma_f32_16x16x32_bf16 v[52:55], v[240:243], v[184:187], v[52:55]
	v_mfma_f32_16x16x32_bf16 v[56:59], v[236:239], v[216:219], v[56:59]
	v_mfma_f32_16x16x32_bf16 v[60:63], v[240:243], v[216:219], v[60:63]
	s_setprio 0
	s_cmp_lg_u32 s54, 0
	s_barrier
	s_cbranch_scc1 .LBB0_392
	s_barrier

; #define LDA8(dst, b, h)                                                                                               \
;   _Pragma("unroll") for (int m = 0; m < 4; ++m) _Pragma("unroll") for (int k = 0; k < 2; ++k)                         \
;     dst[m][k] = *(const bf16x8*)(SA8(b, h) + la + m * 2048 + k * 1024)
; #define LDB8(dst, b, h)                                                                                               \
;   _Pragma("unroll") for (int n = 0; n < 2; ++n) _Pragma("unroll") for (int k = 0; k < 2; ++k)                         \
;     dst[n][k] = *(const bf16x8*)(SB8(b, h) + lb + n * 2048 + k * 1024)
; #define WAITL8(n) asm volatile("s_waitcnt lgkmcnt(" #n ")" ::: "memory")
; #define BAR8 __builtin_amdgcn_s_barrier()
; #define SCHED8 __builtin_amdgcn_sched_barrier(0)
; template <class Epi>
; DEV void gemm_tile8(char* shm, const u16* __restrict__ A, const u16* __restrict__ Bt, int K, int brow, int bcol, Epi& epi) {
;     ...
;   for (int t = 0; t < nt - 2; t += 2) {
;     LDB8(B0, 0, 0); SCHED8; LDA8(At, 0, 0); STAGE8(SA8(1, 1), A, brow + HALF, t + 1);
;     WAITL8(8); BAR8; WAITL8(0); MMA8(0, 0, At, B0); BAR8; SCHED8;
;     LDB8(B1, 0, 1); STAGE8(SB8(0, 0), Bt, bcol, t + 2);
;     BAR8; WAITL8(0); MMA8(0, 1, At, B1); BAR8;
;     LDA8(At, 0, 1); STAGE8(SA8(0, 0), A, brow, t + 2);
;     BAR8; WAITL8(0); MMA8(1, 0, At, B0); BAR8; SCHED8;
;     STAGE8(SB8(0, 1), Bt, bcol + HALF, t + 2);
.LBB0_424:
	v_or_b32_e32 v134, 0x10000, v133
	v_add_u32_e32 v136, 0x10800, v133
	v_add_u32_e32 v135, 0x10400, v133
	ds_read_b128 v[144:147], v134
	ds_read_b128 v[148:151], v135
	v_add_u32_e32 v137, 0x10c00, v133
	ds_read_b128 v[152:155], v136
	ds_read_b128 v[156:159], v137
	v_lshl_add_u64 v[228:229], s[22:23], 0, v[130:131]
	s_mov_b64 s[96:97], 0x112b0080
	v_lshl_add_u64 v[138:139], v[228:229], 0, s[96:97]
	s_add_i32 s97, s54, 0xc000
	s_mov_b32 m0, s97
	s_mov_b64 vcc, 0x11308080
	s_add_i32 s96, s54, 0xe000
	ds_read_b128 v[160:163], v132
	ds_read_b128 v[164:167], v132 offset:1024
	ds_read_b128 v[168:171], v132 offset:2048
	ds_read_b128 v[172:175], v132 offset:3072
	ds_read_b128 v[176:179], v132 offset:4096
	ds_read_b128 v[180:183], v132 offset:5120
	ds_read_b128 v[184:187], v132 offset:6144
	ds_read_b128 v[188:191], v132 offset:7168
	global_load_lds_dwordx4 v[138:139], off
	v_lshl_add_u64 v[138:139], v[228:229], 0, vcc
	s_mov_b32 m0, s96
	s_nop 0
	global_load_lds_dwordx4 v[138:139], off
	s_waitcnt lgkmcnt(8)
	s_barrier
	s_waitcnt lgkmcnt(0)
	s_setprio 1
	s_waitcnt lgkmcnt(0)
	v_mfma_f32_16x16x32_bf16 v[124:127], v[144:147], v[160:163], v[124:127]
	v_mfma_f32_16x16x32_bf16 v[120:123], v[152:155], v[160:163], v[120:123]
	v_mfma_f32_16x16x32_bf16 v[116:119], v[144:147], v[168:171], v[116:119]
	v_mfma_f32_16x16x32_bf16 v[112:115], v[152:155], v[168:171], v[112:115]
	v_mfma_f32_16x16x32_bf16 v[108:111], v[144:147], v[176:179], v[108:111]
	v_mfma_f32_16x16x32_bf16 v[104:107], v[152:155], v[176:179], v[104:107]
	v_mfma_f32_16x16x32_bf16 v[100:103], v[144:147], v[184:187], v[100:103]
	v_mfma_f32_16x16x32_bf16 v[96:99], v[152:155], v[184:187], v[96:99]
	v_mfma_f32_16x16x32_bf16 v[124:127], v[148:151], v[164:167], v[124:127]
	v_mfma_f32_16x16x32_bf16 v[120:123], v[156:159], v[164:167], v[120:123]
	v_mfma_f32_16x16x32_bf16 v[116:119], v[148:151], v[172:175], v[116:119]
	v_mfma_f32_16x16x32_bf16 v[112:115], v[156:159], v[172:175], v[112:115]
	v_mfma_f32_16x16x32_bf16 v[108:111], v[148:151], v[180:183], v[108:111]
	v_mfma_f32_16x16x32_bf16 v[104:107], v[156:159], v[180:183], v[104:107]
	v_mfma_f32_16x16x32_bf16 v[100:103], v[148:151], v[188:191], v[100:103]
	v_mfma_f32_16x16x32_bf16 v[96:99], v[156:159], v[188:191], v[96:99]
	s_setprio 0
	s_barrier
	v_lshl_add_u64 v[230:231], s[20:21], 0, v[130:131]
	s_mov_b64 vcc, 0x1a00100
	s_mov_b32 m0, s55
	v_or_b32_e32 v138, 0x14000, v133
	v_add_u32_e32 v140, 0x14800, v133
	v_lshl_add_u64 v[220:221], v[230:231], 0, vcc
	s_mov_b64 vcc, 0x1a58100
	v_add_u32_e32 v139, 0x14400, v133
	ds_read_b128 v[204:207], v138
	ds_read_b128 v[208:211], v139
	v_add_u32_e32 v142, 0x14c00, v133
	ds_read_b128 v[212:215], v140
	ds_read_b128 v[216:219], v142
	global_load_lds_dwordx4 v[220:221], off
	v_lshl_add_u64 v[220:221], v[230:231], 0, vcc
	s_mov_b32 m0, s70
	s_nop 0
	global_load_lds_dwordx4 v[220:221], off
	s_barrier
	s_waitcnt lgkmcnt(0)
	s_setprio 1
	s_waitcnt lgkmcnt(0)
	v_mfma_f32_16x16x32_bf16 v[92:95], v[204:207], v[160:163], v[92:95]
	v_mfma_f32_16x16x32_bf16 v[88:91], v[212:215], v[160:163], v[88:91]
	v_mfma_f32_16x16x32_bf16 v[84:87], v[204:207], v[168:171], v[84:87]
	v_mfma_f32_16x16x32_bf16 v[80:83], v[212:215], v[168:171], v[80:83]
	v_mfma_f32_16x16x32_bf16 v[76:79], v[204:207], v[176:179], v[76:79]
	v_mfma_f32_16x16x32_bf16 v[72:75], v[212:215], v[176:179], v[72:75]
	v_mfma_f32_16x16x32_bf16 v[68:71], v[204:207], v[184:187], v[68:71]
	v_mfma_f32_16x16x32_bf16 v[64:67], v[212:215], v[184:187], v[64:67]
	v_mfma_f32_16x16x32_bf16 v[92:95], v[208:211], v[164:167], v[92:95]
	v_mfma_f32_16x16x32_bf16 v[88:91], v[216:219], v[164:167], v[88:91]
	v_mfma_f32_16x16x32_bf16 v[84:87], v[208:211], v[172:175], v[84:87]
	v_mfma_f32_16x16x32_bf16 v[80:83], v[216:219], v[172:175], v[80:83]
	v_mfma_f32_16x16x32_bf16 v[76:79], v[208:211], v[180:183], v[76:79]
	v_mfma_f32_16x16x32_bf16 v[72:75], v[216:219], v[180:183], v[72:75]
	v_mfma_f32_16x16x32_bf16 v[68:71], v[208:211], v[188:191], v[68:71]
	v_mfma_f32_16x16x32_bf16 v[64:67], v[216:219], v[188:191], v[64:67]
	s_setprio 0
	s_mov_b64 vcc, 0x11200100
	s_mov_b32 m0, s54
	v_lshl_add_u64 v[220:221], v[228:229], 0, vcc
	s_mov_b64 vcc, 0x11258100
	s_barrier
	ds_read_b128 v[160:163], v132 offset:16384
	ds_read_b128 v[164:167], v132 offset:17408
	ds_read_b128 v[168:171], v132 offset:18432
	ds_read_b128 v[172:175], v132 offset:19456
	ds_read_b128 v[176:179], v132 offset:20480
	ds_read_b128 v[180:183], v132 offset:21504
	ds_read_b128 v[184:187], v132 offset:22528
	ds_read_b128 v[188:191], v132 offset:23552
	global_load_lds_dwordx4 v[220:221], off
	v_lshl_add_u64 v[220:221], v[228:229], 0, vcc
	s_mov_b32 m0, s71
	s_nop 0
	global_load_lds_dwordx4 v[220:221], off
	s_barrier
	s_waitcnt lgkmcnt(0)
	s_setprio 1
	s_waitcnt lgkmcnt(0)
	v_mfma_f32_16x16x32_bf16 v[60:63], v[144:147], v[160:163], v[60:63]
	v_mfma_f32_16x16x32_bf16 v[56:59], v[152:155], v[160:163], v[56:59]
	v_mfma_f32_16x16x32_bf16 v[52:55], v[144:147], v[168:171], v[52:55]
	v_mfma_f32_16x16x32_bf16 v[48:51], v[152:155], v[168:171], v[48:51]
	v_mfma_f32_16x16x32_bf16 v[44:47], v[144:147], v[176:179], v[44:47]
	v_mfma_f32_16x16x32_bf16 v[40:43], v[152:155], v[176:179], v[40:43]
	v_mfma_f32_16x16x32_bf16 v[36:39], v[144:147], v[184:187], v[36:39]
	v_mfma_f32_16x16x32_bf16 v[32:35], v[152:155], v[184:187], v[32:35]
	v_mfma_f32_16x16x32_bf16 v[60:63], v[148:151], v[164:167], v[60:63]
	v_mfma_f32_16x16x32_bf16 v[56:59], v[156:159], v[164:167], v[56:59]
	v_mfma_f32_16x16x32_bf16 v[52:55], v[148:151], v[172:175], v[52:55]
	v_mfma_f32_16x16x32_bf16 v[48:51], v[156:159], v[172:175], v[48:51]
	v_mfma_f32_16x16x32_bf16 v[44:47], v[148:151], v[180:183], v[44:47]
	v_mfma_f32_16x16x32_bf16 v[40:43], v[156:159], v[180:183], v[40:43]
	v_mfma_f32_16x16x32_bf16 v[36:39], v[148:151], v[188:191], v[36:39]
	v_mfma_f32_16x16x32_bf16 v[32:35], v[156:159], v[188:191], v[32:35]
	s_setprio 0
	s_barrier
; #define LDA8(dst, b, h)                                                                                               \
;   _Pragma("unroll") for (int m = 0; m < 4; ++m) _Pragma("unroll") for (int k = 0; k < 2; ++k)                         \
;     dst[m][k] = *(const bf16x8*)(SA8(b, h) + la + m * 2048 + k * 1024)
; #define LDB8(dst, b, h)                                                                                               \
;   _Pragma("unroll") for (int n = 0; n < 2; ++n) _Pragma("unroll") for (int k = 0; k < 2; ++k)                         \
;     dst[n][k] = *(const bf16x8*)(SB8(b, h) + lb + n * 2048 + k * 1024)
; #define WAITV8(n) asm volatile("s_waitcnt vmcnt(" #n ")" ::: "memory")
; #define WAITL8(n) asm volatile("s_waitcnt lgkmcnt(" #n ")" ::: "memory")
; #define BAR8 __builtin_amdgcn_s_barrier()
; #define SCHED8 __builtin_amdgcn_sched_barrier(0)
; template <class Epi>
; DEV void gemm_tile8(char* shm, const u16* __restrict__ A, const u16* __restrict__ Bt, int K, int brow, int bcol, Epi& epi) {
;     ...
;     STAGE8(SB8(0, 1), Bt, bcol + HALF, t + 2);
;     WAITV8(6); BAR8; MMA8(1, 1, At, B1); BAR8;
;     LDB8(B0, 1, 0); SCHED8; LDA8(At, 1, 0); STAGE8(SA8(0, 1), A, brow + HALF, t + 2);
;     WAITL8(8); BAR8; WAITL8(0); MMA8(0, 0, At, B0); BAR8; SCHED8;
;     LDB8(B1, 1, 1); STAGE8(SB8(1, 0), Bt, bcol, t + 3);
;     BAR8; WAITL8(0); MMA8(0, 1, At, B1); BAR8;
	s_mov_b64 vcc, 0x1ab0100
	s_mov_b32 m0, s72
	v_lshl_add_u64 v[144:145], v[230:231], 0, vcc
	s_mov_b64 vcc, 0x1b08100
	global_load_lds_dwordx4 v[144:145], off
	v_lshl_add_u64 v[144:145], v[230:231], 0, vcc
	s_mov_b32 m0, s73
	s_nop 0
	global_load_lds_dwordx4 v[144:145], off
	s_waitcnt vmcnt(6)
	s_barrier
	s_setprio 1
	v_mfma_f32_16x16x32_bf16 v[28:31], v[204:207], v[160:163], v[28:31]
	v_mfma_f32_16x16x32_bf16 v[24:27], v[212:215], v[160:163], v[24:27]
	v_mfma_f32_16x16x32_bf16 v[20:23], v[204:207], v[168:171], v[20:23]
	v_mfma_f32_16x16x32_bf16 v[16:19], v[212:215], v[168:171], v[16:19]
	v_mfma_f32_16x16x32_bf16 v[12:15], v[204:207], v[176:179], v[12:15]
	v_mfma_f32_16x16x32_bf16 v[8:11], v[212:215], v[176:179], v[8:11]
	v_mfma_f32_16x16x32_bf16 v[4:7], v[204:207], v[184:187], v[4:7]
	v_mfma_f32_16x16x32_bf16 v[0:3], v[212:215], v[184:187], v[0:3]
	v_mfma_f32_16x16x32_bf16 v[28:31], v[208:211], v[164:167], v[28:31]
	v_mfma_f32_16x16x32_bf16 v[24:27], v[216:219], v[164:167], v[24:27]
	v_mfma_f32_16x16x32_bf16 v[20:23], v[208:211], v[172:175], v[20:23]
	v_mfma_f32_16x16x32_bf16 v[16:19], v[216:219], v[172:175], v[16:19]
	v_mfma_f32_16x16x32_bf16 v[12:15], v[208:211], v[180:183], v[12:15]
	v_mfma_f32_16x16x32_bf16 v[8:11], v[216:219], v[180:183], v[8:11]
	v_mfma_f32_16x16x32_bf16 v[4:7], v[208:211], v[188:191], v[4:7]
	v_mfma_f32_16x16x32_bf16 v[0:3], v[216:219], v[188:191], v[0:3]
	s_setprio 0
	v_or_b32_e32 v143, 0x18000, v133
	v_add_u32_e32 v145, 0x18800, v133
	s_barrier
	v_add_u32_e32 v144, 0x18400, v133
	ds_read_b128 v[152:155], v143
	ds_read_b128 v[156:159], v144
	v_add_u32_e32 v146, 0x18c00, v133
	ds_read_b128 v[160:163], v145
	ds_read_b128 v[164:167], v146
	s_mov_b64 vcc, 0x112b0100
	s_mov_b32 m0, s81
	v_lshl_add_u64 v[148:149], v[228:229], 0, vcc
	s_mov_b64 vcc, 0x11308100
	ds_read_b128 v[168:171], v132 offset:32768
	ds_read_b128 v[172:175], v132 offset:33792
	ds_read_b128 v[176:179], v132 offset:34816
	ds_read_b128 v[180:183], v132 offset:35840
	ds_read_b128 v[184:187], v132 offset:36864
	ds_read_b128 v[188:191], v132 offset:37888
	ds_read_b128 v[204:207], v132 offset:38912
	ds_read_b128 v[208:211], v132 offset:39936
	global_load_lds_dwordx4 v[148:149], off
	v_lshl_add_u64 v[148:149], v[228:229], 0, vcc
	s_mov_b32 m0, s84
	s_nop 0
	global_load_lds_dwordx4 v[148:149], off
	s_waitcnt lgkmcnt(8)
	s_barrier
	s_waitcnt lgkmcnt(0)
	s_setprio 1
	s_waitcnt lgkmcnt(0)
	v_mfma_f32_16x16x32_bf16 v[124:127], v[152:155], v[168:171], v[124:127]
	v_mfma_f32_16x16x32_bf16 v[120:123], v[160:163], v[168:171], v[120:123]
	v_mfma_f32_16x16x32_bf16 v[116:119], v[152:155], v[176:179], v[116:119]
	v_mfma_f32_16x16x32_bf16 v[112:115], v[160:163], v[176:179], v[112:115]
	v_mfma_f32_16x16x32_bf16 v[108:111], v[152:155], v[184:187], v[108:111]
	v_mfma_f32_16x16x32_bf16 v[104:107], v[160:163], v[184:187], v[104:107]
	v_mfma_f32_16x16x32_bf16 v[100:103], v[152:155], v[204:207], v[100:103]
	v_mfma_f32_16x16x32_bf16 v[96:99], v[160:163], v[204:207], v[96:99]
	v_mfma_f32_16x16x32_bf16 v[124:127], v[156:159], v[172:175], v[124:127]
	v_mfma_f32_16x16x32_bf16 v[120:123], v[164:167], v[172:175], v[120:123]
	v_mfma_f32_16x16x32_bf16 v[116:119], v[156:159], v[180:183], v[116:119]
	v_mfma_f32_16x16x32_bf16 v[112:115], v[164:167], v[180:183], v[112:115]
	v_mfma_f32_16x16x32_bf16 v[108:111], v[156:159], v[188:191], v[108:111]
	v_mfma_f32_16x16x32_bf16 v[104:107], v[164:167], v[188:191], v[104:107]
	v_mfma_f32_16x16x32_bf16 v[100:103], v[156:159], v[208:211], v[100:103]
	v_mfma_f32_16x16x32_bf16 v[96:99], v[164:167], v[208:211], v[96:99]
	s_setprio 0
	s_barrier
	s_mov_b64 vcc, 0x1a00180
	s_mov_b32 m0, s85
	v_or_b32_e32 v147, 0x1c000, v133
	v_add_u32_e32 v149, 0x1c800, v133
	v_lshl_add_u64 v[232:233], v[230:231], 0, vcc
	s_mov_b64 vcc, 0x1a58180
	v_add_u32_e32 v148, 0x1c400, v133
	ds_read_b128 v[212:215], v147
	ds_read_b128 v[216:219], v148
	v_add_u32_e32 v150, 0x1cc00, v133
	ds_read_b128 v[220:223], v149
	ds_read_b128 v[224:227], v150
	global_load_lds_dwordx4 v[232:233], off
	v_lshl_add_u64 v[232:233], v[230:231], 0, vcc
	s_mov_b32 m0, s90
	s_nop 0
	global_load_lds_dwordx4 v[232:233], off
	s_barrier
	s_waitcnt lgkmcnt(0)
	s_setprio 1
	s_waitcnt lgkmcnt(0)
	v_mfma_f32_16x16x32_bf16 v[92:95], v[212:215], v[168:171], v[92:95]
	v_mfma_f32_16x16x32_bf16 v[88:91], v[220:223], v[168:171], v[88:91]
	v_mfma_f32_16x16x32_bf16 v[84:87], v[212:215], v[176:179], v[84:87]
	v_mfma_f32_16x16x32_bf16 v[80:83], v[220:223], v[176:179], v[80:83]
	v_mfma_f32_16x16x32_bf16 v[76:79], v[212:215], v[184:187], v[76:79]
	v_mfma_f32_16x16x32_bf16 v[72:75], v[220:223], v[184:187], v[72:75]
	v_mfma_f32_16x16x32_bf16 v[68:71], v[212:215], v[204:207], v[68:71]
	v_mfma_f32_16x16x32_bf16 v[64:67], v[220:223], v[204:207], v[64:67]
	v_mfma_f32_16x16x32_bf16 v[92:95], v[216:219], v[172:175], v[92:95]
	v_mfma_f32_16x16x32_bf16 v[88:91], v[224:227], v[172:175], v[88:91]
	v_mfma_f32_16x16x32_bf16 v[84:87], v[216:219], v[180:183], v[84:87]
	v_mfma_f32_16x16x32_bf16 v[80:83], v[224:227], v[180:183], v[80:83]
	v_mfma_f32_16x16x32_bf16 v[76:79], v[216:219], v[188:191], v[76:79]
	v_mfma_f32_16x16x32_bf16 v[72:75], v[224:227], v[188:191], v[72:75]
	v_mfma_f32_16x16x32_bf16 v[68:71], v[216:219], v[208:211], v[68:71]
	v_mfma_f32_16x16x32_bf16 v[64:67], v[224:227], v[208:211], v[64:67]
	s_setprio 0
	s_mov_b64 vcc, 0x11200180
	s_mov_b32 m0, s91
	v_lshl_add_u64 v[232:233], v[228:229], 0, vcc
	s_mov_b64 vcc, 0x11258180
	s_barrier
; #define LDA8(dst, b, h)                                                                                               \
;   _Pragma("unroll") for (int m = 0; m < 4; ++m) _Pragma("unroll") for (int k = 0; k < 2; ++k)                         \
;     dst[m][k] = *(const bf16x8*)(SA8(b, h) + la + m * 2048 + k * 1024)
; #define LDB8(dst, b, h)                                                                                               \
;   _Pragma("unroll") for (int n = 0; n < 2; ++n) _Pragma("unroll") for (int k = 0; k < 2; ++k)                         \
;     dst[n][k] = *(const bf16x8*)(SB8(b, h) + lb + n * 2048 + k * 1024)
; #define WAITV8(n) asm volatile("s_waitcnt vmcnt(" #n ")" ::: "memory")
; #define WAITL8(n) asm volatile("s_waitcnt lgkmcnt(" #n ")" ::: "memory")
; #define BAR8 __builtin_amdgcn_s_barrier()
; #define SCHED8 __builtin_amdgcn_sched_barrier(0)
; template <class Epi>
; DEV void gemm_tile8(char* shm, const u16* __restrict__ A, const u16* __restrict__ Bt, int K, int brow, int bcol, Epi& epi) {
;     ...
;     LDA8(At, 1, 1); STAGE8(SA8(1, 0), A, brow, t + 3);
;     BAR8; WAITL8(0); MMA8(1, 0, At, B0); BAR8; SCHED8;
;     STAGE8(SB8(1, 1), Bt, bcol + HALF, t + 3);
;     WAITV8(6); BAR8; MMA8(1, 1, At, B1); BAR8;
;   }
;   { LDB8(B0, 0, 0); LDA8(At, 0, 0); STAGE8(SA8(1, 1), A, brow + HALF, nt - 1);
;     BAR8; WAITL8(0); MMA8(0, 0, At, B0); BAR8;
;     LDB8(B1, 0, 1); BAR8; WAITL8(0); MMA8(0, 1, At, B1); BAR8;
	ds_read_b128 v[168:171], v132 offset:49152
	ds_read_b128 v[172:175], v132 offset:50176
	ds_read_b128 v[176:179], v132 offset:51200
	ds_read_b128 v[180:183], v132 offset:52224
	ds_read_b128 v[184:187], v132 offset:53248
	ds_read_b128 v[188:191], v132 offset:54272
	ds_read_b128 v[204:207], v132 offset:55296
	ds_read_b128 v[208:211], v132 offset:56320
	global_load_lds_dwordx4 v[232:233], off
	v_lshl_add_u64 v[228:229], v[228:229], 0, vcc
	s_mov_b32 m0, s92
	s_nop 0
	global_load_lds_dwordx4 v[228:229], off
	s_barrier
	s_waitcnt lgkmcnt(0)
	s_setprio 1
	s_waitcnt lgkmcnt(0)
	v_mfma_f32_16x16x32_bf16 v[60:63], v[152:155], v[168:171], v[60:63]
	v_mfma_f32_16x16x32_bf16 v[56:59], v[160:163], v[168:171], v[56:59]
	v_mfma_f32_16x16x32_bf16 v[52:55], v[152:155], v[176:179], v[52:55]
	v_mfma_f32_16x16x32_bf16 v[48:51], v[160:163], v[176:179], v[48:51]
	v_mfma_f32_16x16x32_bf16 v[44:47], v[152:155], v[184:187], v[44:47]
	v_mfma_f32_16x16x32_bf16 v[40:43], v[160:163], v[184:187], v[40:43]
	v_mfma_f32_16x16x32_bf16 v[36:39], v[152:155], v[204:207], v[36:39]
	v_mfma_f32_16x16x32_bf16 v[32:35], v[160:163], v[204:207], v[32:35]
	v_mfma_f32_16x16x32_bf16 v[60:63], v[156:159], v[172:175], v[60:63]
	v_mfma_f32_16x16x32_bf16 v[56:59], v[164:167], v[172:175], v[56:59]
	v_mfma_f32_16x16x32_bf16 v[52:55], v[156:159], v[180:183], v[52:55]
	v_mfma_f32_16x16x32_bf16 v[48:51], v[164:167], v[180:183], v[48:51]
	v_mfma_f32_16x16x32_bf16 v[44:47], v[156:159], v[188:191], v[44:47]
	v_mfma_f32_16x16x32_bf16 v[40:43], v[164:167], v[188:191], v[40:43]
	v_mfma_f32_16x16x32_bf16 v[36:39], v[156:159], v[208:211], v[36:39]
	v_mfma_f32_16x16x32_bf16 v[32:35], v[164:167], v[208:211], v[32:35]
	s_setprio 0
	s_barrier
	s_mov_b64 vcc, 0x1ab0180
	s_mov_b32 m0, s93
	v_lshl_add_u64 v[152:153], v[230:231], 0, vcc
	s_mov_b64 vcc, 0x1b08180
	global_load_lds_dwordx4 v[152:153], off
	v_lshl_add_u64 v[152:153], v[230:231], 0, vcc
	s_mov_b32 m0, s94
	s_nop 0
	global_load_lds_dwordx4 v[152:153], off
	s_waitcnt vmcnt(6)
	s_barrier
	s_setprio 1
	v_mfma_f32_16x16x32_bf16 v[28:31], v[212:215], v[168:171], v[28:31]
	v_mfma_f32_16x16x32_bf16 v[24:27], v[220:223], v[168:171], v[24:27]
	v_mfma_f32_16x16x32_bf16 v[20:23], v[212:215], v[176:179], v[20:23]
	v_mfma_f32_16x16x32_bf16 v[16:19], v[220:223], v[176:179], v[16:19]
	v_mfma_f32_16x16x32_bf16 v[12:15], v[212:215], v[184:187], v[12:15]
	v_mfma_f32_16x16x32_bf16 v[8:11], v[220:223], v[184:187], v[8:11]
	v_mfma_f32_16x16x32_bf16 v[4:7], v[212:215], v[204:207], v[4:7]
	v_mfma_f32_16x16x32_bf16 v[0:3], v[220:223], v[204:207], v[0:3]
	v_mfma_f32_16x16x32_bf16 v[28:31], v[216:219], v[172:175], v[28:31]
	v_mfma_f32_16x16x32_bf16 v[24:27], v[224:227], v[172:175], v[24:27]
	v_mfma_f32_16x16x32_bf16 v[20:23], v[216:219], v[180:183], v[20:23]
	v_mfma_f32_16x16x32_bf16 v[16:19], v[224:227], v[180:183], v[16:19]
	v_mfma_f32_16x16x32_bf16 v[12:15], v[216:219], v[188:191], v[12:15]
	v_mfma_f32_16x16x32_bf16 v[8:11], v[224:227], v[188:191], v[8:11]
	v_mfma_f32_16x16x32_bf16 v[4:7], v[216:219], v[208:211], v[4:7]
	v_mfma_f32_16x16x32_bf16 v[0:3], v[224:227], v[208:211], v[0:3]
	s_setprio 0
	s_add_i32 s95, s95, 2
	s_add_u32 s20, s20, 0x100
	s_addc_u32 s21, s21, 0
	s_add_u32 s22, s22, 0x100
	s_addc_u32 s23, s23, 0
	s_cmp_lt_u32 s95, 40
	s_barrier
	s_cbranch_scc1 .LBB0_424
	v_lshl_add_u64 v[128:129], v[128:129], 1, s[6:7]
	s_mov_b64 s[6:7], 0x1580
	s_mov_b32 m0, s97
	v_lshl_add_u64 v[130:131], v[128:129], 0, s[6:7]
	s_mov_b64 s[6:7], 0x59580
	ds_read_b128 v[152:155], v134
	ds_read_b128 v[156:159], v135
	ds_read_b128 v[160:163], v136
	ds_read_b128 v[134:137], v137
	ds_read_b128 v[164:167], v132
	ds_read_b128 v[168:171], v132 offset:1024
	ds_read_b128 v[172:175], v132 offset:2048
	ds_read_b128 v[176:179], v132 offset:3072
	ds_read_b128 v[180:183], v132 offset:4096
	ds_read_b128 v[184:187], v132 offset:5120
	ds_read_b128 v[188:191], v132 offset:6144
	ds_read_b128 v[204:207], v132 offset:7168
	global_load_lds_dwordx4 v[130:131], off
	v_lshl_add_u64 v[128:129], v[128:129], 0, s[6:7]
	s_mov_b32 m0, s96
	s_nop 0
	global_load_lds_dwordx4 v[128:129], off
	s_barrier
	s_waitcnt lgkmcnt(0)
	s_setprio 1
	s_waitcnt lgkmcnt(0)
	v_mfma_f32_16x16x32_bf16 v[124:127], v[152:155], v[164:167], v[124:127]
	v_mfma_f32_16x16x32_bf16 v[120:123], v[160:163], v[164:167], v[120:123]
	v_mfma_f32_16x16x32_bf16 v[116:119], v[152:155], v[172:175], v[116:119]
	v_mfma_f32_16x16x32_bf16 v[112:115], v[160:163], v[172:175], v[112:115]
	v_mfma_f32_16x16x32_bf16 v[108:111], v[152:155], v[180:183], v[108:111]
	v_mfma_f32_16x16x32_bf16 v[104:107], v[160:163], v[180:183], v[104:107]
	v_mfma_f32_16x16x32_bf16 v[100:103], v[152:155], v[188:191], v[100:103]
	v_mfma_f32_16x16x32_bf16 v[96:99], v[160:163], v[188:191], v[96:99]
	v_mfma_f32_16x16x32_bf16 v[124:127], v[156:159], v[168:171], v[124:127]
	v_mfma_f32_16x16x32_bf16 v[120:123], v[134:137], v[168:171], v[120:123]
	v_mfma_f32_16x16x32_bf16 v[116:119], v[156:159], v[176:179], v[116:119]
	v_mfma_f32_16x16x32_bf16 v[112:115], v[134:137], v[176:179], v[112:115]
	v_mfma_f32_16x16x32_bf16 v[108:111], v[156:159], v[184:187], v[108:111]
	v_mfma_f32_16x16x32_bf16 v[104:107], v[134:137], v[184:187], v[104:107]
	v_mfma_f32_16x16x32_bf16 v[100:103], v[156:159], v[204:207], v[100:103]
	v_mfma_f32_16x16x32_bf16 v[96:99], v[134:137], v[204:207], v[96:99]
	s_setprio 0
	s_barrier
	ds_read_b128 v[128:131], v138
	ds_read_b128 v[208:211], v139
	ds_read_b128 v[212:215], v140
	ds_read_b128 v[216:219], v142
	s_barrier
; #define LDA8(dst, b, h)                                                                                               \
;   _Pragma("unroll") for (int m = 0; m < 4; ++m) _Pragma("unroll") for (int k = 0; k < 2; ++k)                         \
;     dst[m][k] = *(const bf16x8*)(SA8(b, h) + la + m * 2048 + k * 1024)
; #define LDB8(dst, b, h)                                                                                               \
;   _Pragma("unroll") for (int n = 0; n < 2; ++n) _Pragma("unroll") for (int k = 0; k < 2; ++k)                         \
;     dst[n][k] = *(const bf16x8*)(SB8(b, h) + lb + n * 2048 + k * 1024)
; #define WAITV8(n) asm volatile("s_waitcnt vmcnt(" #n ")" ::: "memory")
; #define WAITL8(n) asm volatile("s_waitcnt lgkmcnt(" #n ")" ::: "memory")
; #define BAR8 __builtin_amdgcn_s_barrier()
; template <class Epi>
; DEV void gemm_tile8(char* shm, const u16* __restrict__ A, const u16* __restrict__ Bt, int K, int brow, int bcol, Epi& epi) {
;     ...
;     LDB8(B1, 0, 1); BAR8; WAITL8(0); MMA8(0, 1, At, B1); BAR8;
;     LDA8(At, 0, 1); WAITV8(4); BAR8; WAITL8(0); MMA8(1, 0, At, B0); MMA8(1, 1, At, B1); BAR8; }
;   { LDB8(B0, 1, 0); LDA8(At, 1, 0); WAITV8(2); BAR8; WAITL8(0); MMA8(0, 0, At, B0); BAR8;
	s_waitcnt lgkmcnt(0)
	s_setprio 1
	s_waitcnt lgkmcnt(3)
	v_mfma_f32_16x16x32_bf16 v[92:95], v[128:131], v[164:167], v[92:95]
	s_waitcnt lgkmcnt(1)
	v_mfma_f32_16x16x32_bf16 v[88:91], v[212:215], v[164:167], v[88:91]
	v_mfma_f32_16x16x32_bf16 v[84:87], v[128:131], v[172:175], v[84:87]
	v_mfma_f32_16x16x32_bf16 v[80:83], v[212:215], v[172:175], v[80:83]
	v_mfma_f32_16x16x32_bf16 v[76:79], v[128:131], v[180:183], v[76:79]
	v_mfma_f32_16x16x32_bf16 v[72:75], v[212:215], v[180:183], v[72:75]
	v_mfma_f32_16x16x32_bf16 v[68:71], v[128:131], v[188:191], v[68:71]
	v_mfma_f32_16x16x32_bf16 v[64:67], v[212:215], v[188:191], v[64:67]
	v_mfma_f32_16x16x32_bf16 v[220:223], v[208:211], v[168:171], v[92:95]
	s_waitcnt lgkmcnt(0)
	v_mfma_f32_16x16x32_bf16 v[164:167], v[216:219], v[168:171], v[88:91]
	v_mfma_f32_16x16x32_bf16 v[168:171], v[208:211], v[176:179], v[84:87]
	v_mfma_f32_16x16x32_bf16 v[172:175], v[216:219], v[176:179], v[80:83]
	v_mfma_f32_16x16x32_bf16 v[176:179], v[208:211], v[184:187], v[76:79]
	v_mfma_f32_16x16x32_bf16 v[180:183], v[216:219], v[184:187], v[72:75]
	v_mfma_f32_16x16x32_bf16 v[184:187], v[208:211], v[204:207], v[68:71]
	v_mfma_f32_16x16x32_bf16 v[188:191], v[216:219], v[204:207], v[64:67]
	s_setprio 0
	s_barrier
	s_nop 0
	ds_read_b128 v[64:67], v132 offset:16384
	ds_read_b128 v[68:71], v132 offset:17408
	ds_read_b128 v[72:75], v132 offset:18432
	ds_read_b128 v[76:79], v132 offset:19456
	ds_read_b128 v[80:83], v132 offset:20480
	ds_read_b128 v[84:87], v132 offset:21504
	ds_read_b128 v[88:91], v132 offset:22528
	ds_read_b128 v[92:95], v132 offset:23552
	s_waitcnt vmcnt(4)
	s_barrier
	s_waitcnt lgkmcnt(0)
	s_setprio 1
	s_waitcnt lgkmcnt(7)
	v_mfma_f32_16x16x32_bf16 v[60:63], v[152:155], v[64:67], v[60:63]
	v_mfma_f32_16x16x32_bf16 v[56:59], v[160:163], v[64:67], v[56:59]
	s_waitcnt lgkmcnt(5)
	v_mfma_f32_16x16x32_bf16 v[52:55], v[152:155], v[72:75], v[52:55]
	v_mfma_f32_16x16x32_bf16 v[48:51], v[160:163], v[72:75], v[48:51]
	s_waitcnt lgkmcnt(3)
	v_mfma_f32_16x16x32_bf16 v[44:47], v[152:155], v[80:83], v[44:47]
	v_mfma_f32_16x16x32_bf16 v[40:43], v[160:163], v[80:83], v[40:43]
	s_waitcnt lgkmcnt(1)
	v_mfma_f32_16x16x32_bf16 v[36:39], v[152:155], v[88:91], v[36:39]
	v_mfma_f32_16x16x32_bf16 v[32:35], v[160:163], v[88:91], v[32:35]
	v_mfma_f32_16x16x32_bf16 v[60:63], v[156:159], v[68:71], v[60:63]
	v_mfma_f32_16x16x32_bf16 v[56:59], v[134:137], v[68:71], v[56:59]
	v_mfma_f32_16x16x32_bf16 v[52:55], v[156:159], v[76:79], v[52:55]
	v_mfma_f32_16x16x32_bf16 v[48:51], v[134:137], v[76:79], v[48:51]
	v_mfma_f32_16x16x32_bf16 v[44:47], v[156:159], v[84:87], v[44:47]
	v_mfma_f32_16x16x32_bf16 v[40:43], v[134:137], v[84:87], v[40:43]
	s_waitcnt lgkmcnt(0)
	v_mfma_f32_16x16x32_bf16 v[36:39], v[156:159], v[92:95], v[36:39]
	v_mfma_f32_16x16x32_bf16 v[32:35], v[134:137], v[92:95], v[32:35]
	s_setprio 0
	s_setprio 1
	v_mfma_f32_16x16x32_bf16 v[28:31], v[128:131], v[64:67], v[28:31]
	v_mfma_f32_16x16x32_bf16 v[24:27], v[212:215], v[64:67], v[24:27]
	v_mfma_f32_16x16x32_bf16 v[20:23], v[128:131], v[72:75], v[20:23]
	v_mfma_f32_16x16x32_bf16 v[16:19], v[212:215], v[72:75], v[16:19]
	v_mfma_f32_16x16x32_bf16 v[12:15], v[128:131], v[80:83], v[12:15]
	v_mfma_f32_16x16x32_bf16 v[8:11], v[212:215], v[80:83], v[8:11]
	v_mfma_f32_16x16x32_bf16 v[4:7], v[128:131], v[88:91], v[4:7]
	v_mfma_f32_16x16x32_bf16 v[0:3], v[212:215], v[88:91], v[0:3]
	v_mfma_f32_16x16x32_bf16 v[134:137], v[208:211], v[68:71], v[28:31]
	v_mfma_f32_16x16x32_bf16 v[152:155], v[216:219], v[68:71], v[24:27]
	v_mfma_f32_16x16x32_bf16 v[156:159], v[208:211], v[76:79], v[20:23]
	v_mfma_f32_16x16x32_bf16 v[160:163], v[216:219], v[76:79], v[16:19]
	v_mfma_f32_16x16x32_bf16 v[204:207], v[208:211], v[84:87], v[12:15]
	v_mfma_f32_16x16x32_bf16 v[224:227], v[216:219], v[84:87], v[8:11]
	v_mfma_f32_16x16x32_bf16 v[128:131], v[208:211], v[92:95], v[4:7]
	v_mfma_f32_16x16x32_bf16 v[208:211], v[216:219], v[92:95], v[0:3]
	s_setprio 0
	s_barrier
	ds_read_b128 v[24:27], v143
	ds_read_b128 v[28:31], v144
	ds_read_b128 v[142:145], v145
	ds_read_b128 v[212:215], v146
	ds_read_b128 v[0:3], v132 offset:32768
	ds_read_b128 v[4:7], v132 offset:33792
	ds_read_b128 v[8:11], v132 offset:34816
	ds_read_b128 v[12:15], v132 offset:35840
	ds_read_b128 v[16:19], v132 offset:36864
	ds_read_b128 v[20:23], v132 offset:37888
	ds_read_b128 v[216:219], v132 offset:38912
	ds_read_b128 v[228:231], v132 offset:39936
	s_waitcnt vmcnt(2)
	s_barrier
; #define LDA8(dst, b, h)                                                                                               \
;   _Pragma("unroll") for (int m = 0; m < 4; ++m) _Pragma("unroll") for (int k = 0; k < 2; ++k)                         \
;     dst[m][k] = *(const bf16x8*)(SA8(b, h) + la + m * 2048 + k * 1024)
; #define LDB8(dst, b, h)                                                                                               \
;   _Pragma("unroll") for (int n = 0; n < 2; ++n) _Pragma("unroll") for (int k = 0; k < 2; ++k)                         \
;     dst[n][k] = *(const bf16x8*)(SB8(b, h) + lb + n * 2048 + k * 1024)
; #define WAITV8(n) asm volatile("s_waitcnt vmcnt(" #n ")" ::: "memory")
; #define WAITL8(n) asm volatile("s_waitcnt lgkmcnt(" #n ")" ::: "memory")
; #define BAR8 __builtin_amdgcn_s_barrier()
; template <class Epi>
; DEV void gemm_tile8(char* shm, const u16* __restrict__ A, const u16* __restrict__ Bt, int K, int brow, int bcol, Epi& epi) {
;     ...
;   { LDB8(B0, 1, 0); LDA8(At, 1, 0); WAITV8(2); BAR8; WAITL8(0); MMA8(0, 0, At, B0); BAR8;
;     LDB8(B1, 1, 1); WAITV8(0); BAR8; WAITL8(0); MMA8(0, 1, At, B1); BAR8;
;     LDA8(At, 1, 1); BAR8; WAITL8(0); MMA8(1, 0, At, B0); MMA8(1, 1, At, B1); BAR8; }
;   if (wrs == 0) BAR8;
	s_waitcnt lgkmcnt(0)
	s_setprio 1
	s_waitcnt lgkmcnt(7)
	v_mfma_f32_16x16x32_bf16 v[64:67], v[24:27], v[0:3], v[124:127]
	s_waitcnt lgkmcnt(6)
	v_mfma_f32_16x16x32_bf16 v[72:75], v[28:31], v[4:7], v[64:67]
	v_mfma_f32_16x16x32_bf16 v[64:67], v[142:145], v[0:3], v[120:123]
	s_waitcnt lgkmcnt(5)
	v_mfma_f32_16x16x32_bf16 v[68:71], v[24:27], v[8:11], v[116:119]
	v_mfma_f32_16x16x32_bf16 v[76:79], v[142:145], v[8:11], v[112:115]
	s_waitcnt lgkmcnt(3)
	v_mfma_f32_16x16x32_bf16 v[80:83], v[24:27], v[16:19], v[108:111]
	v_mfma_f32_16x16x32_bf16 v[84:87], v[142:145], v[16:19], v[104:107]
	s_waitcnt lgkmcnt(1)
	v_mfma_f32_16x16x32_bf16 v[88:91], v[24:27], v[216:219], v[100:103]
	v_mfma_f32_16x16x32_bf16 v[92:95], v[142:145], v[216:219], v[96:99]
	v_mfma_f32_16x16x32_bf16 v[64:67], v[212:215], v[4:7], v[64:67]
	v_mfma_f32_16x16x32_bf16 v[68:71], v[28:31], v[12:15], v[68:71]
	v_mfma_f32_16x16x32_bf16 v[76:79], v[212:215], v[12:15], v[76:79]
	v_mfma_f32_16x16x32_bf16 v[80:83], v[28:31], v[20:23], v[80:83]
	v_mfma_f32_16x16x32_bf16 v[84:87], v[212:215], v[20:23], v[84:87]
	s_waitcnt lgkmcnt(0)
	v_mfma_f32_16x16x32_bf16 v[88:91], v[28:31], v[228:231], v[88:91]
	v_mfma_f32_16x16x32_bf16 v[92:95], v[212:215], v[228:231], v[92:95]
	s_setprio 0
	s_barrier
	ds_read_b128 v[232:235], v147
	ds_read_b128 v[236:239], v148
	ds_read_b128 v[146:149], v149
	ds_read_b128 v[240:243], v150
	s_waitcnt vmcnt(0)
	s_barrier
	s_waitcnt lgkmcnt(0)
	s_setprio 1
	s_waitcnt lgkmcnt(3)
	v_mfma_f32_16x16x32_bf16 v[96:99], v[232:235], v[0:3], v[220:223]
	s_waitcnt lgkmcnt(1)
	v_mfma_f32_16x16x32_bf16 v[0:3], v[146:149], v[0:3], v[164:167]
	v_mfma_f32_16x16x32_bf16 v[104:107], v[236:239], v[4:7], v[96:99]
	s_waitcnt lgkmcnt(0)
	v_mfma_f32_16x16x32_bf16 v[96:99], v[240:243], v[4:7], v[0:3]
	v_mfma_f32_16x16x32_bf16 v[0:3], v[232:235], v[8:11], v[168:171]
	v_mfma_f32_16x16x32_bf16 v[100:103], v[236:239], v[12:15], v[0:3]
	v_mfma_f32_16x16x32_bf16 v[0:3], v[146:149], v[8:11], v[172:175]
	v_mfma_f32_16x16x32_bf16 v[108:111], v[240:243], v[12:15], v[0:3]
	v_mfma_f32_16x16x32_bf16 v[0:3], v[232:235], v[16:19], v[176:179]
	v_mfma_f32_16x16x32_bf16 v[112:115], v[236:239], v[20:23], v[0:3]
	v_mfma_f32_16x16x32_bf16 v[0:3], v[146:149], v[16:19], v[180:183]
	v_mfma_f32_16x16x32_bf16 v[116:119], v[240:243], v[20:23], v[0:3]
	v_mfma_f32_16x16x32_bf16 v[0:3], v[232:235], v[216:219], v[184:187]
	v_mfma_f32_16x16x32_bf16 v[120:123], v[236:239], v[228:231], v[0:3]
	v_mfma_f32_16x16x32_bf16 v[0:3], v[146:149], v[216:219], v[188:191]
	v_mfma_f32_16x16x32_bf16 v[124:127], v[240:243], v[228:231], v[0:3]
	s_setprio 0
	s_barrier
	ds_read_b128 v[164:167], v132 offset:49152
	ds_read_b128 v[168:171], v132 offset:50176
	ds_read_b128 v[172:175], v132 offset:51200
	ds_read_b128 v[176:179], v132 offset:52224
	ds_read_b128 v[180:183], v132 offset:53248
	ds_read_b128 v[184:187], v132 offset:54272
	ds_read_b128 v[188:191], v132 offset:55296
	ds_read_b128 v[216:219], v132 offset:56320
	s_barrier
	s_waitcnt lgkmcnt(0)
	s_setprio 1
	s_waitcnt lgkmcnt(7)
	v_mfma_f32_16x16x32_bf16 v[0:3], v[24:27], v[164:167], v[60:63]
	s_waitcnt lgkmcnt(5)
	v_mfma_f32_16x16x32_bf16 v[8:11], v[24:27], v[172:175], v[52:55]
	s_waitcnt lgkmcnt(3)
	v_mfma_f32_16x16x32_bf16 v[16:19], v[24:27], v[180:183], v[44:47]
	s_waitcnt lgkmcnt(1)
	v_mfma_f32_16x16x32_bf16 v[24:27], v[24:27], v[188:191], v[36:39]
	v_mfma_f32_16x16x32_bf16 v[0:3], v[28:31], v[168:171], v[0:3]
	v_mfma_f32_16x16x32_bf16 v[4:7], v[142:145], v[164:167], v[56:59]
	v_mfma_f32_16x16x32_bf16 v[8:11], v[28:31], v[176:179], v[8:11]
	v_mfma_f32_16x16x32_bf16 v[12:15], v[142:145], v[172:175], v[48:51]
	v_mfma_f32_16x16x32_bf16 v[16:19], v[28:31], v[184:187], v[16:19]
	v_mfma_f32_16x16x32_bf16 v[20:23], v[142:145], v[180:183], v[40:43]
	s_waitcnt lgkmcnt(0)
	v_mfma_f32_16x16x32_bf16 v[24:27], v[28:31], v[216:219], v[24:27]
	v_mfma_f32_16x16x32_bf16 v[28:31], v[142:145], v[188:191], v[32:35]
	v_mfma_f32_16x16x32_bf16 v[4:7], v[212:215], v[168:171], v[4:7]
	v_mfma_f32_16x16x32_bf16 v[12:15], v[212:215], v[176:179], v[12:15]
	v_mfma_f32_16x16x32_bf16 v[20:23], v[212:215], v[184:187], v[20:23]
	v_mfma_f32_16x16x32_bf16 v[28:31], v[212:215], v[216:219], v[28:31]
	s_setprio 0
	s_setprio 1
	v_mfma_f32_16x16x32_bf16 v[32:35], v[232:235], v[164:167], v[134:137]
	v_mfma_f32_16x16x32_bf16 v[36:39], v[146:149], v[164:167], v[152:155]
	v_mfma_f32_16x16x32_bf16 v[40:43], v[232:235], v[172:175], v[156:159]
	v_mfma_f32_16x16x32_bf16 v[44:47], v[146:149], v[172:175], v[160:163]
	v_mfma_f32_16x16x32_bf16 v[48:51], v[232:235], v[180:183], v[204:207]
	v_mfma_f32_16x16x32_bf16 v[52:55], v[146:149], v[180:183], v[224:227]
	v_mfma_f32_16x16x32_bf16 v[56:59], v[232:235], v[188:191], v[128:131]
	v_mfma_f32_16x16x32_bf16 v[60:63], v[146:149], v[188:191], v[208:211]
	v_mfma_f32_16x16x32_bf16 v[32:35], v[236:239], v[168:171], v[32:35]
	v_mfma_f32_16x16x32_bf16 v[36:39], v[240:243], v[168:171], v[36:39]
	v_mfma_f32_16x16x32_bf16 v[40:43], v[236:239], v[176:179], v[40:43]
	v_mfma_f32_16x16x32_bf16 v[44:47], v[240:243], v[176:179], v[44:47]
	v_mfma_f32_16x16x32_bf16 v[48:51], v[236:239], v[184:187], v[48:51]
	v_mfma_f32_16x16x32_bf16 v[52:55], v[240:243], v[184:187], v[52:55]
	v_mfma_f32_16x16x32_bf16 v[56:59], v[236:239], v[216:219], v[56:59]
	v_mfma_f32_16x16x32_bf16 v[60:63], v[240:243], v[216:219], v[60:63]
	s_setprio 0
	s_cmp_lg_u32 s48, 0
	s_barrier
	s_cbranch_scc1 .LBB0_427
	s_barrier

; #define WAIT_V0() asm volatile("s_waitcnt vmcnt(0)" ::: "memory")
; template <int MT, class Epi>
; DEV void gemm_tile(char* shm, const u16* __restrict__ Ab, const u16* __restrict__ Bb, int K, int brow, int bcol, Epi& epi) {
;     ...
;   for (int t = 0; t < nt; ++t) {
;     const int cur = t & 1;
;     if (t + 1 < nt) GLDS_STAGE_(cur ^ 1, t + 1);
;     {
;       bf16x8 At[MT], Bf0[4], Bf1[4];
; #pragma unroll
;       for (int m = 0; m < MT; ++m) At[m] = *(const bf16x8*)(SA_(cur) + lds_byte<KS>(wr * (MT * 16) + m * 16 + fr, fq * 8));
; #pragma unroll
;       for (int n = 0; n < 4; ++n) Bf0[n] = *(const bf16x8*)(SB_(cur) + lds_byte<KS>(wc * 64 + n * 16 + fr, fq * 8));
; #pragma unroll
;       for (int n = 0; n < 4; ++n) Bf1[n] = *(const bf16x8*)(SB_(cur) + lds_byte<KS>(wc * 64 + n * 16 + fr, 32 + fq * 8));
;       __builtin_amdgcn_s_setprio(1);
; #pragma unroll
;       for (int m = 0; m < MT; ++m) {
; #pragma unroll
;         for (int n = 0; n < 4; ++n) acc[m][n] = __builtin_amdgcn_mfma_f32_16x16x32_bf16(Bf0[n], At[m], acc[m][n], 0, 0, 0);
;         At[m] = *(const bf16x8*)(SA_(cur) + lds_byte<KS>(wr * (MT * 16) + m * 16 + fr, 32 + fq * 8));
;       }
; #pragma unroll
;       for (int m = 0; m < MT; ++m)
; #pragma unroll
;         for (int n = 0; n < 4; ++n) acc[m][n] = __builtin_amdgcn_mfma_f32_16x16x32_bf16(Bf1[n], At[m], acc[m][n], 0, 0, 0);
;       __builtin_amdgcn_s_setprio(0);
;       __builtin_amdgcn_sched_barrier(0);
;     }
;     WAIT_V0();
;     __syncthreads();
;   }
.LBB0_456:
	v_add3_u32 v140, s24, v85, v87
	v_add3_u32 v143, s24, v89, v90
	v_add3_u32 v120, s24, v85, v84
	v_add_u32_e32 v136, s24, v86
	v_add3_u32 v142, s24, v89, v88
	ds_read_b128 v[92:95], v140
	ds_read_b128 v[96:99], v142
	v_add3_u32 v144, s24, v89, v91
	ds_read_b128 v[100:103], v143
	ds_read_b128 v[104:107], v144
	ds_read_b128 v[108:111], v120 offset:32768
	ds_read_b128 v[112:115], v120 offset:34816
	ds_read_b128 v[116:119], v120 offset:36864
	ds_read_b128 v[120:123], v120 offset:38912
	ds_read_b128 v[124:127], v136 offset:33792
	ds_read_b128 v[128:131], v136 offset:35840
	ds_read_b128 v[132:135], v136 offset:37888
	ds_read_b128 v[136:139], v136 offset:39936
	s_setprio 1
	s_waitcnt lgkmcnt(0)
	v_mfma_f32_16x16x32_bf16 v[40:43], v[108:111], v[92:95], v[40:43]
	v_mfma_f32_16x16x32_bf16 v[28:31], v[112:115], v[92:95], v[28:31]
	v_mfma_f32_16x16x32_bf16 v[20:23], v[116:119], v[92:95], v[20:23]
	v_mfma_f32_16x16x32_bf16 v[16:19], v[120:123], v[92:95], v[16:19]
	v_mfma_f32_16x16x32_bf16 v[12:15], v[108:111], v[96:99], v[12:15]
	v_mfma_f32_16x16x32_bf16 v[8:11], v[112:115], v[96:99], v[8:11]
	v_mfma_f32_16x16x32_bf16 v[4:7], v[116:119], v[96:99], v[4:7]
	v_mfma_f32_16x16x32_bf16 v[0:3], v[120:123], v[96:99], v[0:3]
	ds_read_b128 v[92:95], v140 offset:1024
	ds_read_b128 v[96:99], v142 offset:1024
	s_waitcnt lgkmcnt(1)
	v_mfma_f32_16x16x32_bf16 v[40:43], v[124:127], v[92:95], v[40:43]
	v_mfma_f32_16x16x32_bf16 v[28:31], v[128:131], v[92:95], v[28:31]
	v_mfma_f32_16x16x32_bf16 v[20:23], v[132:135], v[92:95], v[20:23]
	v_mfma_f32_16x16x32_bf16 v[16:19], v[136:139], v[92:95], v[16:19]
	s_waitcnt lgkmcnt(0)
	v_mfma_f32_16x16x32_bf16 v[12:15], v[124:127], v[96:99], v[12:15]
	v_mfma_f32_16x16x32_bf16 v[8:11], v[128:131], v[96:99], v[8:11]
	v_mfma_f32_16x16x32_bf16 v[4:7], v[132:135], v[96:99], v[4:7]
	v_mfma_f32_16x16x32_bf16 v[0:3], v[136:139], v[96:99], v[0:3]
	ds_read_b128 v[92:95], v143 offset:1024
	ds_read_b128 v[96:99], v144 offset:1024
	v_mfma_f32_16x16x32_bf16 v[24:27], v[108:111], v[100:103], v[24:27]
	v_mfma_f32_16x16x32_bf16 v[32:35], v[112:115], v[100:103], v[32:35]
	v_mfma_f32_16x16x32_bf16 v[36:39], v[116:119], v[100:103], v[36:39]
	v_mfma_f32_16x16x32_bf16 v[44:47], v[120:123], v[100:103], v[44:47]
	v_mfma_f32_16x16x32_bf16 v[48:51], v[108:111], v[104:107], v[48:51]
	v_mfma_f32_16x16x32_bf16 v[52:55], v[112:115], v[104:107], v[52:55]
	v_mfma_f32_16x16x32_bf16 v[56:59], v[116:119], v[104:107], v[56:59]
	v_mfma_f32_16x16x32_bf16 v[60:63], v[120:123], v[104:107], v[60:63]
	s_waitcnt lgkmcnt(1)
	v_mfma_f32_16x16x32_bf16 v[24:27], v[124:127], v[92:95], v[24:27]
	v_mfma_f32_16x16x32_bf16 v[32:35], v[128:131], v[92:95], v[32:35]
	v_mfma_f32_16x16x32_bf16 v[36:39], v[132:135], v[92:95], v[36:39]
	v_mfma_f32_16x16x32_bf16 v[44:47], v[136:139], v[92:95], v[44:47]
	s_waitcnt lgkmcnt(0)
	v_mfma_f32_16x16x32_bf16 v[48:51], v[124:127], v[96:99], v[48:51]
	v_mfma_f32_16x16x32_bf16 v[52:55], v[128:131], v[96:99], v[52:55]
	v_mfma_f32_16x16x32_bf16 v[56:59], v[132:135], v[96:99], v[56:59]
	v_mfma_f32_16x16x32_bf16 v[60:63], v[136:139], v[96:99], v[60:63]
	s_setprio 0
	s_add_i32 s23, s23, 0x10000
	s_waitcnt vmcnt(0)
	s_add_u32 s10, s10, 0x80
	s_addc_u32 s11, s11, 0
	s_cmpk_eq_i32 s10, 0x800
	s_barrier
	s_cbranch_scc1 .LBB0_459

; #define LDA8(dst, b, h)                                                                                               \
;   _Pragma("unroll") for (int m = 0; m < 4; ++m) _Pragma("unroll") for (int k = 0; k < 2; ++k)                         \
;     dst[m][k] = *(const bf16x8*)(SA8(b, h) + la + m * 2048 + k * 1024)
; #define LDB8(dst, b, h)                                                                                               \
;   _Pragma("unroll") for (int n = 0; n < 2; ++n) _Pragma("unroll") for (int k = 0; k < 2; ++k)                         \
;     dst[n][k] = *(const bf16x8*)(SB8(b, h) + lb + n * 2048 + k * 1024)
; #define WAITL8(n) asm volatile("s_waitcnt lgkmcnt(" #n ")" ::: "memory")
; #define BAR8 __builtin_amdgcn_s_barrier()
; #define SCHED8 __builtin_amdgcn_sched_barrier(0)
; template <class Epi>
; DEV void gemm_tile8(char* shm, const u16* __restrict__ A, const u16* __restrict__ Bt, int K, int brow, int bcol, Epi& epi) {
;     ...
;   for (int t = 0; t < nt - 2; t += 2) {
;     LDB8(B0, 0, 0); SCHED8; LDA8(At, 0, 0); STAGE8(SA8(1, 1), A, brow + HALF, t + 1);
;     WAITL8(8); BAR8; WAITL8(0); MMA8(0, 0, At, B0); BAR8; SCHED8;
;     LDB8(B1, 0, 1); STAGE8(SB8(0, 0), Bt, bcol, t + 2);
;     BAR8; WAITL8(0); MMA8(0, 1, At, B1); BAR8;
;     LDA8(At, 0, 1); STAGE8(SA8(0, 0), A, brow, t + 2);
;     BAR8; WAITL8(0); MMA8(1, 0, At, B0); BAR8; SCHED8;
;     STAGE8(SB8(0, 1), Bt, bcol + HALF, t + 2);
.LBB0_468:
	v_or_b32_e32 v134, 0x10000, v133
	v_add_u32_e32 v136, 0x10800, v133
	v_add_u32_e32 v135, 0x10400, v133
	ds_read_b128 v[144:147], v134
	ds_read_b128 v[148:151], v135
	v_add_u32_e32 v137, 0x10c00, v133
	ds_read_b128 v[152:155], v136
	ds_read_b128 v[156:159], v137
	v_lshl_add_u64 v[228:229], s[10:11], 0, v[130:131]
	s_add_i32 s93, s7, 0xc000
	v_lshl_add_u64 v[138:139], v[228:229], 0, s[96:97]
	s_mov_b32 m0, s93
	s_add_i32 s25, s7, 0xe000
	ds_read_b128 v[160:163], v132
	ds_read_b128 v[164:167], v132 offset:1024
	ds_read_b128 v[168:171], v132 offset:2048
	ds_read_b128 v[172:175], v132 offset:3072
	ds_read_b128 v[176:179], v132 offset:4096
	ds_read_b128 v[180:183], v132 offset:5120
	ds_read_b128 v[184:187], v132 offset:6144
	ds_read_b128 v[188:191], v132 offset:7168
	global_load_lds_dwordx4 v[138:139], off
	v_lshl_add_u64 v[138:139], v[228:229], 0, vcc
	s_mov_b32 m0, s25
	s_nop 0
	global_load_lds_dwordx4 v[138:139], off
	s_waitcnt lgkmcnt(8)
	s_barrier
	s_waitcnt lgkmcnt(0)
	s_setprio 1
	s_waitcnt lgkmcnt(0)
	v_mfma_f32_16x16x32_bf16 v[124:127], v[144:147], v[160:163], v[124:127]
	v_mfma_f32_16x16x32_bf16 v[120:123], v[152:155], v[160:163], v[120:123]
	v_mfma_f32_16x16x32_bf16 v[116:119], v[144:147], v[168:171], v[116:119]
	v_mfma_f32_16x16x32_bf16 v[112:115], v[152:155], v[168:171], v[112:115]
	v_mfma_f32_16x16x32_bf16 v[108:111], v[144:147], v[176:179], v[108:111]
	v_mfma_f32_16x16x32_bf16 v[104:107], v[152:155], v[176:179], v[104:107]
	v_mfma_f32_16x16x32_bf16 v[100:103], v[144:147], v[184:187], v[100:103]
	v_mfma_f32_16x16x32_bf16 v[96:99], v[152:155], v[184:187], v[96:99]
	v_mfma_f32_16x16x32_bf16 v[124:127], v[148:151], v[164:167], v[124:127]
	v_mfma_f32_16x16x32_bf16 v[120:123], v[156:159], v[164:167], v[120:123]
	v_mfma_f32_16x16x32_bf16 v[116:119], v[148:151], v[172:175], v[116:119]
	v_mfma_f32_16x16x32_bf16 v[112:115], v[156:159], v[172:175], v[112:115]
	v_mfma_f32_16x16x32_bf16 v[108:111], v[148:151], v[180:183], v[108:111]
	v_mfma_f32_16x16x32_bf16 v[104:107], v[156:159], v[180:183], v[104:107]
	v_mfma_f32_16x16x32_bf16 v[100:103], v[148:151], v[188:191], v[100:103]
	v_mfma_f32_16x16x32_bf16 v[96:99], v[156:159], v[188:191], v[96:99]
	s_setprio 0
	s_barrier
	v_lshl_add_u64 v[230:231], s[22:23], 0, v[130:131]
	s_mov_b64 s[94:95], 0xf00100
	s_mov_b32 m0, s48
	v_or_b32_e32 v138, 0x14000, v133
	v_add_u32_e32 v140, 0x14800, v133
	v_lshl_add_u64 v[220:221], v[230:231], 0, s[94:95]
	s_mov_b64 s[94:95], 0xf20100
	v_add_u32_e32 v139, 0x14400, v133
	ds_read_b128 v[204:207], v138
	ds_read_b128 v[208:211], v139
	v_add_u32_e32 v142, 0x14c00, v133
	ds_read_b128 v[212:215], v140
	ds_read_b128 v[216:219], v142
	global_load_lds_dwordx4 v[220:221], off
	v_lshl_add_u64 v[220:221], v[230:231], 0, s[94:95]
	s_mov_b32 m0, s54
	s_nop 0
	global_load_lds_dwordx4 v[220:221], off
	s_barrier
	s_waitcnt lgkmcnt(0)
	s_setprio 1
	s_waitcnt lgkmcnt(0)
	v_mfma_f32_16x16x32_bf16 v[92:95], v[204:207], v[160:163], v[92:95]
	v_mfma_f32_16x16x32_bf16 v[88:91], v[212:215], v[160:163], v[88:91]
	v_mfma_f32_16x16x32_bf16 v[84:87], v[204:207], v[168:171], v[84:87]
	v_mfma_f32_16x16x32_bf16 v[80:83], v[212:215], v[168:171], v[80:83]
	v_mfma_f32_16x16x32_bf16 v[76:79], v[204:207], v[176:179], v[76:79]
	v_mfma_f32_16x16x32_bf16 v[72:75], v[212:215], v[176:179], v[72:75]
	v_mfma_f32_16x16x32_bf16 v[68:71], v[204:207], v[184:187], v[68:71]
	v_mfma_f32_16x16x32_bf16 v[64:67], v[212:215], v[184:187], v[64:67]
	v_mfma_f32_16x16x32_bf16 v[92:95], v[208:211], v[164:167], v[92:95]
	v_mfma_f32_16x16x32_bf16 v[88:91], v[216:219], v[164:167], v[88:91]
	v_mfma_f32_16x16x32_bf16 v[84:87], v[208:211], v[172:175], v[84:87]
	v_mfma_f32_16x16x32_bf16 v[80:83], v[216:219], v[172:175], v[80:83]
	v_mfma_f32_16x16x32_bf16 v[76:79], v[208:211], v[180:183], v[76:79]
	v_mfma_f32_16x16x32_bf16 v[72:75], v[216:219], v[180:183], v[72:75]
	v_mfma_f32_16x16x32_bf16 v[68:71], v[208:211], v[188:191], v[68:71]
	v_mfma_f32_16x16x32_bf16 v[64:67], v[216:219], v[188:191], v[64:67]
	s_setprio 0
	s_mov_b32 m0, s7
	v_lshl_add_u64 v[220:221], v[228:229], 0, s[2:3]
	s_barrier
	ds_read_b128 v[160:163], v132 offset:16384
	ds_read_b128 v[164:167], v132 offset:17408
	ds_read_b128 v[168:171], v132 offset:18432
	ds_read_b128 v[172:175], v132 offset:19456
	ds_read_b128 v[176:179], v132 offset:20480
	ds_read_b128 v[180:183], v132 offset:21504
	ds_read_b128 v[184:187], v132 offset:22528
	ds_read_b128 v[188:191], v132 offset:23552
	global_load_lds_dwordx4 v[220:221], off
	v_lshl_add_u64 v[220:221], v[228:229], 0, s[74:75]
	s_mov_b32 m0, s55
	s_nop 0
	global_load_lds_dwordx4 v[220:221], off
	s_barrier
	s_waitcnt lgkmcnt(0)
	s_setprio 1
	s_waitcnt lgkmcnt(0)
	v_mfma_f32_16x16x32_bf16 v[60:63], v[144:147], v[160:163], v[60:63]
	v_mfma_f32_16x16x32_bf16 v[56:59], v[152:155], v[160:163], v[56:59]
	v_mfma_f32_16x16x32_bf16 v[52:55], v[144:147], v[168:171], v[52:55]
	v_mfma_f32_16x16x32_bf16 v[48:51], v[152:155], v[168:171], v[48:51]
	v_mfma_f32_16x16x32_bf16 v[44:47], v[144:147], v[176:179], v[44:47]
	v_mfma_f32_16x16x32_bf16 v[40:43], v[152:155], v[176:179], v[40:43]
	v_mfma_f32_16x16x32_bf16 v[36:39], v[144:147], v[184:187], v[36:39]
	v_mfma_f32_16x16x32_bf16 v[32:35], v[152:155], v[184:187], v[32:35]
	v_mfma_f32_16x16x32_bf16 v[60:63], v[148:151], v[164:167], v[60:63]
	v_mfma_f32_16x16x32_bf16 v[56:59], v[156:159], v[164:167], v[56:59]
	v_mfma_f32_16x16x32_bf16 v[52:55], v[148:151], v[172:175], v[52:55]
	v_mfma_f32_16x16x32_bf16 v[48:51], v[156:159], v[172:175], v[48:51]
	v_mfma_f32_16x16x32_bf16 v[44:47], v[148:151], v[180:183], v[44:47]
	v_mfma_f32_16x16x32_bf16 v[40:43], v[156:159], v[180:183], v[40:43]
	v_mfma_f32_16x16x32_bf16 v[36:39], v[148:151], v[188:191], v[36:39]
	v_mfma_f32_16x16x32_bf16 v[32:35], v[156:159], v[188:191], v[32:35]
	s_setprio 0
	s_barrier
; #define LDA8(dst, b, h)                                                                                               \
;   _Pragma("unroll") for (int m = 0; m < 4; ++m) _Pragma("unroll") for (int k = 0; k < 2; ++k)                         \
;     dst[m][k] = *(const bf16x8*)(SA8(b, h) + la + m * 2048 + k * 1024)
; #define LDB8(dst, b, h)                                                                                               \
;   _Pragma("unroll") for (int n = 0; n < 2; ++n) _Pragma("unroll") for (int k = 0; k < 2; ++k)                         \
;     dst[n][k] = *(const bf16x8*)(SB8(b, h) + lb + n * 2048 + k * 1024)
; #define WAITV8(n) asm volatile("s_waitcnt vmcnt(" #n ")" ::: "memory")
; #define WAITL8(n) asm volatile("s_waitcnt lgkmcnt(" #n ")" ::: "memory")
; #define BAR8 __builtin_amdgcn_s_barrier()
; #define SCHED8 __builtin_amdgcn_sched_barrier(0)
; template <class Epi>
; DEV void gemm_tile8(char* shm, const u16* __restrict__ A, const u16* __restrict__ Bt, int K, int brow, int bcol, Epi& epi) {
;     ...
;     STAGE8(SB8(0, 1), Bt, bcol + HALF, t + 2);
;     WAITV8(6); BAR8; MMA8(1, 1, At, B1); BAR8;
;     LDB8(B0, 1, 0); SCHED8; LDA8(At, 1, 0); STAGE8(SA8(0, 1), A, brow + HALF, t + 2);
;     WAITL8(8); BAR8; WAITL8(0); MMA8(0, 0, At, B0); BAR8; SCHED8;
;     LDB8(B1, 1, 1); STAGE8(SB8(1, 0), Bt, bcol, t + 3);
;     BAR8; WAITL8(0); MMA8(0, 1, At, B1); BAR8;
	s_mov_b64 s[94:95], 0xf40100
	s_mov_b32 m0, s70
	v_lshl_add_u64 v[144:145], v[230:231], 0, s[94:95]
	s_mov_b64 s[94:95], 0xf60100
	global_load_lds_dwordx4 v[144:145], off
	v_lshl_add_u64 v[144:145], v[230:231], 0, s[94:95]
	s_mov_b32 m0, s71
	s_nop 0
	global_load_lds_dwordx4 v[144:145], off
	s_waitcnt vmcnt(6)
	s_barrier
	s_setprio 1
	v_mfma_f32_16x16x32_bf16 v[28:31], v[204:207], v[160:163], v[28:31]
	v_mfma_f32_16x16x32_bf16 v[24:27], v[212:215], v[160:163], v[24:27]
	v_mfma_f32_16x16x32_bf16 v[20:23], v[204:207], v[168:171], v[20:23]
	v_mfma_f32_16x16x32_bf16 v[16:19], v[212:215], v[168:171], v[16:19]
	v_mfma_f32_16x16x32_bf16 v[12:15], v[204:207], v[176:179], v[12:15]
	v_mfma_f32_16x16x32_bf16 v[8:11], v[212:215], v[176:179], v[8:11]
	v_mfma_f32_16x16x32_bf16 v[4:7], v[204:207], v[184:187], v[4:7]
	v_mfma_f32_16x16x32_bf16 v[0:3], v[212:215], v[184:187], v[0:3]
	v_mfma_f32_16x16x32_bf16 v[28:31], v[208:211], v[164:167], v[28:31]
	v_mfma_f32_16x16x32_bf16 v[24:27], v[216:219], v[164:167], v[24:27]
	v_mfma_f32_16x16x32_bf16 v[20:23], v[208:211], v[172:175], v[20:23]
	v_mfma_f32_16x16x32_bf16 v[16:19], v[216:219], v[172:175], v[16:19]
	v_mfma_f32_16x16x32_bf16 v[12:15], v[208:211], v[180:183], v[12:15]
	v_mfma_f32_16x16x32_bf16 v[8:11], v[216:219], v[180:183], v[8:11]
	v_mfma_f32_16x16x32_bf16 v[4:7], v[208:211], v[188:191], v[4:7]
	v_mfma_f32_16x16x32_bf16 v[0:3], v[216:219], v[188:191], v[0:3]
	s_setprio 0
	v_or_b32_e32 v143, 0x18000, v133
	v_add_u32_e32 v145, 0x18800, v133
	s_barrier
	v_add_u32_e32 v144, 0x18400, v133
	ds_read_b128 v[152:155], v143
	ds_read_b128 v[156:159], v144
	v_add_u32_e32 v146, 0x18c00, v133
	ds_read_b128 v[160:163], v145
	ds_read_b128 v[164:167], v146
	s_mov_b32 m0, s72
	v_lshl_add_u64 v[148:149], v[228:229], 0, s[14:15]
	ds_read_b128 v[168:171], v132 offset:32768
	ds_read_b128 v[172:175], v132 offset:33792
	ds_read_b128 v[176:179], v132 offset:34816
	ds_read_b128 v[180:183], v132 offset:35840
	ds_read_b128 v[184:187], v132 offset:36864
	ds_read_b128 v[188:191], v132 offset:37888
	ds_read_b128 v[204:207], v132 offset:38912
	ds_read_b128 v[208:211], v132 offset:39936
	global_load_lds_dwordx4 v[148:149], off
	v_lshl_add_u64 v[148:149], v[228:229], 0, s[16:17]
	s_mov_b32 m0, s73
	s_nop 0
	global_load_lds_dwordx4 v[148:149], off
	s_waitcnt lgkmcnt(8)
	s_barrier
	s_waitcnt lgkmcnt(0)
	s_setprio 1
	s_waitcnt lgkmcnt(0)
	v_mfma_f32_16x16x32_bf16 v[124:127], v[152:155], v[168:171], v[124:127]
	v_mfma_f32_16x16x32_bf16 v[120:123], v[160:163], v[168:171], v[120:123]
	v_mfma_f32_16x16x32_bf16 v[116:119], v[152:155], v[176:179], v[116:119]
	v_mfma_f32_16x16x32_bf16 v[112:115], v[160:163], v[176:179], v[112:115]
	v_mfma_f32_16x16x32_bf16 v[108:111], v[152:155], v[184:187], v[108:111]
	v_mfma_f32_16x16x32_bf16 v[104:107], v[160:163], v[184:187], v[104:107]
	v_mfma_f32_16x16x32_bf16 v[100:103], v[152:155], v[204:207], v[100:103]
	v_mfma_f32_16x16x32_bf16 v[96:99], v[160:163], v[204:207], v[96:99]
	v_mfma_f32_16x16x32_bf16 v[124:127], v[156:159], v[172:175], v[124:127]
	v_mfma_f32_16x16x32_bf16 v[120:123], v[164:167], v[172:175], v[120:123]
	v_mfma_f32_16x16x32_bf16 v[116:119], v[156:159], v[180:183], v[116:119]
	v_mfma_f32_16x16x32_bf16 v[112:115], v[164:167], v[180:183], v[112:115]
	v_mfma_f32_16x16x32_bf16 v[108:111], v[156:159], v[188:191], v[108:111]
	v_mfma_f32_16x16x32_bf16 v[104:107], v[164:167], v[188:191], v[104:107]
	v_mfma_f32_16x16x32_bf16 v[100:103], v[156:159], v[208:211], v[100:103]
	v_mfma_f32_16x16x32_bf16 v[96:99], v[164:167], v[208:211], v[96:99]
	s_setprio 0
	s_barrier
	s_mov_b64 s[94:95], 0xf00180
	s_mov_b32 m0, s81
	v_or_b32_e32 v147, 0x1c000, v133
	v_add_u32_e32 v149, 0x1c800, v133
	v_lshl_add_u64 v[232:233], v[230:231], 0, s[94:95]
	s_mov_b64 s[94:95], 0xf20180
	v_add_u32_e32 v148, 0x1c400, v133
	ds_read_b128 v[212:215], v147
	ds_read_b128 v[216:219], v148
	v_add_u32_e32 v150, 0x1cc00, v133
	ds_read_b128 v[220:223], v149
	ds_read_b128 v[224:227], v150
	global_load_lds_dwordx4 v[232:233], off
	v_lshl_add_u64 v[232:233], v[230:231], 0, s[94:95]
	s_mov_b32 m0, s84
	s_nop 0
	global_load_lds_dwordx4 v[232:233], off
	s_barrier
	s_waitcnt lgkmcnt(0)
	s_setprio 1
	s_waitcnt lgkmcnt(0)
	v_mfma_f32_16x16x32_bf16 v[92:95], v[212:215], v[168:171], v[92:95]
	v_mfma_f32_16x16x32_bf16 v[88:91], v[220:223], v[168:171], v[88:91]
	v_mfma_f32_16x16x32_bf16 v[84:87], v[212:215], v[176:179], v[84:87]
	v_mfma_f32_16x16x32_bf16 v[80:83], v[220:223], v[176:179], v[80:83]
	v_mfma_f32_16x16x32_bf16 v[76:79], v[212:215], v[184:187], v[76:79]
	v_mfma_f32_16x16x32_bf16 v[72:75], v[220:223], v[184:187], v[72:75]
	v_mfma_f32_16x16x32_bf16 v[68:71], v[212:215], v[204:207], v[68:71]
	v_mfma_f32_16x16x32_bf16 v[64:67], v[220:223], v[204:207], v[64:67]
	v_mfma_f32_16x16x32_bf16 v[92:95], v[216:219], v[172:175], v[92:95]
	v_mfma_f32_16x16x32_bf16 v[88:91], v[224:227], v[172:175], v[88:91]
	v_mfma_f32_16x16x32_bf16 v[84:87], v[216:219], v[180:183], v[84:87]
	v_mfma_f32_16x16x32_bf16 v[80:83], v[224:227], v[180:183], v[80:83]
	v_mfma_f32_16x16x32_bf16 v[76:79], v[216:219], v[188:191], v[76:79]
	v_mfma_f32_16x16x32_bf16 v[72:75], v[224:227], v[188:191], v[72:75]
	v_mfma_f32_16x16x32_bf16 v[68:71], v[216:219], v[208:211], v[68:71]
	v_mfma_f32_16x16x32_bf16 v[64:67], v[224:227], v[208:211], v[64:67]
	s_setprio 0
	s_mov_b32 m0, s85
	v_lshl_add_u64 v[232:233], v[228:229], 0, s[64:65]
	s_barrier
; #define LDA8(dst, b, h)                                                                                               \
;   _Pragma("unroll") for (int m = 0; m < 4; ++m) _Pragma("unroll") for (int k = 0; k < 2; ++k)                         \
;     dst[m][k] = *(const bf16x8*)(SA8(b, h) + la + m * 2048 + k * 1024)
; #define LDB8(dst, b, h)                                                                                               \
;   _Pragma("unroll") for (int n = 0; n < 2; ++n) _Pragma("unroll") for (int k = 0; k < 2; ++k)                         \
;     dst[n][k] = *(const bf16x8*)(SB8(b, h) + lb + n * 2048 + k * 1024)
; #define WAITV8(n) asm volatile("s_waitcnt vmcnt(" #n ")" ::: "memory")
; #define WAITL8(n) asm volatile("s_waitcnt lgkmcnt(" #n ")" ::: "memory")
; #define BAR8 __builtin_amdgcn_s_barrier()
; #define SCHED8 __builtin_amdgcn_sched_barrier(0)
; template <class Epi>
; DEV void gemm_tile8(char* shm, const u16* __restrict__ A, const u16* __restrict__ Bt, int K, int brow, int bcol, Epi& epi) {
;     ...
;     LDA8(At, 1, 1); STAGE8(SA8(1, 0), A, brow, t + 3);
;     BAR8; WAITL8(0); MMA8(1, 0, At, B0); BAR8; SCHED8;
;     STAGE8(SB8(1, 1), Bt, bcol + HALF, t + 3);
;     WAITV8(6); BAR8; MMA8(1, 1, At, B1); BAR8;
;   }
;   { LDB8(B0, 0, 0); LDA8(At, 0, 0); STAGE8(SA8(1, 1), A, brow + HALF, nt - 1);
;     BAR8; WAITL8(0); MMA8(0, 0, At, B0); BAR8;
;     LDB8(B1, 0, 1); BAR8; WAITL8(0); MMA8(0, 1, At, B1); BAR8;
	ds_read_b128 v[168:171], v132 offset:49152
	ds_read_b128 v[172:175], v132 offset:50176
	ds_read_b128 v[176:179], v132 offset:51200
	ds_read_b128 v[180:183], v132 offset:52224
	ds_read_b128 v[184:187], v132 offset:53248
	ds_read_b128 v[188:191], v132 offset:54272
	ds_read_b128 v[204:207], v132 offset:55296
	ds_read_b128 v[208:211], v132 offset:56320
	global_load_lds_dwordx4 v[232:233], off
	v_lshl_add_u64 v[228:229], v[228:229], 0, s[82:83]
	s_mov_b32 m0, s90
	s_nop 0
	global_load_lds_dwordx4 v[228:229], off
	s_barrier
	s_waitcnt lgkmcnt(0)
	s_setprio 1
	s_waitcnt lgkmcnt(0)
	v_mfma_f32_16x16x32_bf16 v[60:63], v[152:155], v[168:171], v[60:63]
	v_mfma_f32_16x16x32_bf16 v[56:59], v[160:163], v[168:171], v[56:59]
	v_mfma_f32_16x16x32_bf16 v[52:55], v[152:155], v[176:179], v[52:55]
	v_mfma_f32_16x16x32_bf16 v[48:51], v[160:163], v[176:179], v[48:51]
	v_mfma_f32_16x16x32_bf16 v[44:47], v[152:155], v[184:187], v[44:47]
	v_mfma_f32_16x16x32_bf16 v[40:43], v[160:163], v[184:187], v[40:43]
	v_mfma_f32_16x16x32_bf16 v[36:39], v[152:155], v[204:207], v[36:39]
	v_mfma_f32_16x16x32_bf16 v[32:35], v[160:163], v[204:207], v[32:35]
	v_mfma_f32_16x16x32_bf16 v[60:63], v[156:159], v[172:175], v[60:63]
	v_mfma_f32_16x16x32_bf16 v[56:59], v[164:167], v[172:175], v[56:59]
	v_mfma_f32_16x16x32_bf16 v[52:55], v[156:159], v[180:183], v[52:55]
	v_mfma_f32_16x16x32_bf16 v[48:51], v[164:167], v[180:183], v[48:51]
	v_mfma_f32_16x16x32_bf16 v[44:47], v[156:159], v[188:191], v[44:47]
	v_mfma_f32_16x16x32_bf16 v[40:43], v[164:167], v[188:191], v[40:43]
	v_mfma_f32_16x16x32_bf16 v[36:39], v[156:159], v[208:211], v[36:39]
	v_mfma_f32_16x16x32_bf16 v[32:35], v[164:167], v[208:211], v[32:35]
	s_setprio 0
	s_barrier
	s_mov_b64 s[94:95], 0xf40180
	s_mov_b32 m0, s91
	v_lshl_add_u64 v[152:153], v[230:231], 0, s[94:95]
	s_mov_b64 s[94:95], 0xf60180
	global_load_lds_dwordx4 v[152:153], off
	v_lshl_add_u64 v[152:153], v[230:231], 0, s[94:95]
	s_mov_b32 m0, s92
	s_nop 0
	global_load_lds_dwordx4 v[152:153], off
	s_waitcnt vmcnt(6)
	s_barrier
	s_setprio 1
	v_mfma_f32_16x16x32_bf16 v[28:31], v[212:215], v[168:171], v[28:31]
	v_mfma_f32_16x16x32_bf16 v[24:27], v[220:223], v[168:171], v[24:27]
	v_mfma_f32_16x16x32_bf16 v[20:23], v[212:215], v[176:179], v[20:23]
	v_mfma_f32_16x16x32_bf16 v[16:19], v[220:223], v[176:179], v[16:19]
	v_mfma_f32_16x16x32_bf16 v[12:15], v[212:215], v[184:187], v[12:15]
	v_mfma_f32_16x16x32_bf16 v[8:11], v[220:223], v[184:187], v[8:11]
	v_mfma_f32_16x16x32_bf16 v[4:7], v[212:215], v[204:207], v[4:7]
	v_mfma_f32_16x16x32_bf16 v[0:3], v[220:223], v[204:207], v[0:3]
	v_mfma_f32_16x16x32_bf16 v[28:31], v[216:219], v[172:175], v[28:31]
	v_mfma_f32_16x16x32_bf16 v[24:27], v[224:227], v[172:175], v[24:27]
	v_mfma_f32_16x16x32_bf16 v[20:23], v[216:219], v[180:183], v[20:23]
	v_mfma_f32_16x16x32_bf16 v[16:19], v[224:227], v[180:183], v[16:19]
	v_mfma_f32_16x16x32_bf16 v[12:15], v[216:219], v[188:191], v[12:15]
	v_mfma_f32_16x16x32_bf16 v[8:11], v[224:227], v[188:191], v[8:11]
	v_mfma_f32_16x16x32_bf16 v[4:7], v[216:219], v[208:211], v[4:7]
	v_mfma_f32_16x16x32_bf16 v[0:3], v[224:227], v[208:211], v[0:3]
	s_setprio 0
	s_add_i32 s24, s24, 2
	s_add_u32 s10, s10, 0x100
	s_addc_u32 s11, s11, 0
	s_add_u32 s22, s22, 0x100
	s_addc_u32 s23, s23, 0
	s_cmp_lt_u32 s24, 12
	s_barrier
	s_cbranch_scc1 .LBB0_468
	s_mov_b64 s[10:11], 0x780
	s_mov_b32 m0, s93
	v_lshl_add_u64 v[130:131], v[128:129], 0, s[10:11]
	s_mov_b64 s[10:11], 0x20780
	ds_read_b128 v[152:155], v134
	ds_read_b128 v[156:159], v135
	ds_read_b128 v[160:163], v136
	ds_read_b128 v[134:137], v137
	ds_read_b128 v[164:167], v132
	ds_read_b128 v[168:171], v132 offset:1024
	ds_read_b128 v[172:175], v132 offset:2048
	ds_read_b128 v[176:179], v132 offset:3072
	ds_read_b128 v[180:183], v132 offset:4096
	ds_read_b128 v[184:187], v132 offset:5120
	ds_read_b128 v[188:191], v132 offset:6144
	ds_read_b128 v[204:207], v132 offset:7168
	global_load_lds_dwordx4 v[130:131], off
	v_lshl_add_u64 v[128:129], v[128:129], 0, s[10:11]
	s_mov_b32 m0, s25
	s_nop 0
	global_load_lds_dwordx4 v[128:129], off
	s_barrier
	s_waitcnt lgkmcnt(0)
	s_setprio 1
	s_waitcnt lgkmcnt(0)
	v_mfma_f32_16x16x32_bf16 v[124:127], v[152:155], v[164:167], v[124:127]
	v_mfma_f32_16x16x32_bf16 v[120:123], v[160:163], v[164:167], v[120:123]
	v_mfma_f32_16x16x32_bf16 v[116:119], v[152:155], v[172:175], v[116:119]
	v_mfma_f32_16x16x32_bf16 v[112:115], v[160:163], v[172:175], v[112:115]
	v_mfma_f32_16x16x32_bf16 v[108:111], v[152:155], v[180:183], v[108:111]
	v_mfma_f32_16x16x32_bf16 v[104:107], v[160:163], v[180:183], v[104:107]
	v_mfma_f32_16x16x32_bf16 v[100:103], v[152:155], v[188:191], v[100:103]
	v_mfma_f32_16x16x32_bf16 v[96:99], v[160:163], v[188:191], v[96:99]
	v_mfma_f32_16x16x32_bf16 v[124:127], v[156:159], v[168:171], v[124:127]
	v_mfma_f32_16x16x32_bf16 v[120:123], v[134:137], v[168:171], v[120:123]
	v_mfma_f32_16x16x32_bf16 v[116:119], v[156:159], v[176:179], v[116:119]
	v_mfma_f32_16x16x32_bf16 v[112:115], v[134:137], v[176:179], v[112:115]
	v_mfma_f32_16x16x32_bf16 v[108:111], v[156:159], v[184:187], v[108:111]
	v_mfma_f32_16x16x32_bf16 v[104:107], v[134:137], v[184:187], v[104:107]
	v_mfma_f32_16x16x32_bf16 v[100:103], v[156:159], v[204:207], v[100:103]
	v_mfma_f32_16x16x32_bf16 v[96:99], v[134:137], v[204:207], v[96:99]
	s_setprio 0
	s_barrier
	ds_read_b128 v[128:131], v138
	ds_read_b128 v[208:211], v139
	ds_read_b128 v[212:215], v140
	ds_read_b128 v[216:219], v142
	s_barrier
; #define LDA8(dst, b, h)                                                                                               \
;   _Pragma("unroll") for (int m = 0; m < 4; ++m) _Pragma("unroll") for (int k = 0; k < 2; ++k)                         \
;     dst[m][k] = *(const bf16x8*)(SA8(b, h) + la + m * 2048 + k * 1024)
; #define LDB8(dst, b, h)                                                                                               \
;   _Pragma("unroll") for (int n = 0; n < 2; ++n) _Pragma("unroll") for (int k = 0; k < 2; ++k)                         \
;     dst[n][k] = *(const bf16x8*)(SB8(b, h) + lb + n * 2048 + k * 1024)
; #define WAITV8(n) asm volatile("s_waitcnt vmcnt(" #n ")" ::: "memory")
; #define WAITL8(n) asm volatile("s_waitcnt lgkmcnt(" #n ")" ::: "memory")
; #define BAR8 __builtin_amdgcn_s_barrier()
; template <class Epi>
; DEV void gemm_tile8(char* shm, const u16* __restrict__ A, const u16* __restrict__ Bt, int K, int brow, int bcol, Epi& epi) {
;     ...
;     LDB8(B1, 0, 1); BAR8; WAITL8(0); MMA8(0, 1, At, B1); BAR8;
;     LDA8(At, 0, 1); WAITV8(4); BAR8; WAITL8(0); MMA8(1, 0, At, B0); MMA8(1, 1, At, B1); BAR8; }
;   { LDB8(B0, 1, 0); LDA8(At, 1, 0); WAITV8(2); BAR8; WAITL8(0); MMA8(0, 0, At, B0); BAR8;
	s_waitcnt lgkmcnt(0)
	s_setprio 1
	s_waitcnt lgkmcnt(3)
	v_mfma_f32_16x16x32_bf16 v[92:95], v[128:131], v[164:167], v[92:95]
	s_waitcnt lgkmcnt(1)
	v_mfma_f32_16x16x32_bf16 v[88:91], v[212:215], v[164:167], v[88:91]
	v_mfma_f32_16x16x32_bf16 v[84:87], v[128:131], v[172:175], v[84:87]
	v_mfma_f32_16x16x32_bf16 v[80:83], v[212:215], v[172:175], v[80:83]
	v_mfma_f32_16x16x32_bf16 v[76:79], v[128:131], v[180:183], v[76:79]
	v_mfma_f32_16x16x32_bf16 v[72:75], v[212:215], v[180:183], v[72:75]
	v_mfma_f32_16x16x32_bf16 v[68:71], v[128:131], v[188:191], v[68:71]
	v_mfma_f32_16x16x32_bf16 v[64:67], v[212:215], v[188:191], v[64:67]
	v_mfma_f32_16x16x32_bf16 v[220:223], v[208:211], v[168:171], v[92:95]
	s_waitcnt lgkmcnt(0)
	v_mfma_f32_16x16x32_bf16 v[164:167], v[216:219], v[168:171], v[88:91]
	v_mfma_f32_16x16x32_bf16 v[168:171], v[208:211], v[176:179], v[84:87]
	v_mfma_f32_16x16x32_bf16 v[172:175], v[216:219], v[176:179], v[80:83]
	v_mfma_f32_16x16x32_bf16 v[176:179], v[208:211], v[184:187], v[76:79]
	v_mfma_f32_16x16x32_bf16 v[180:183], v[216:219], v[184:187], v[72:75]
	v_mfma_f32_16x16x32_bf16 v[184:187], v[208:211], v[204:207], v[68:71]
	v_mfma_f32_16x16x32_bf16 v[188:191], v[216:219], v[204:207], v[64:67]
	s_setprio 0
	s_barrier
	s_nop 0
	ds_read_b128 v[64:67], v132 offset:16384
	ds_read_b128 v[68:71], v132 offset:17408
	ds_read_b128 v[72:75], v132 offset:18432
	ds_read_b128 v[76:79], v132 offset:19456
	ds_read_b128 v[80:83], v132 offset:20480
	ds_read_b128 v[84:87], v132 offset:21504
	ds_read_b128 v[88:91], v132 offset:22528
	ds_read_b128 v[92:95], v132 offset:23552
	s_waitcnt vmcnt(4)
	s_barrier
	s_waitcnt lgkmcnt(0)
	s_setprio 1
	s_waitcnt lgkmcnt(7)
	v_mfma_f32_16x16x32_bf16 v[60:63], v[152:155], v[64:67], v[60:63]
	v_mfma_f32_16x16x32_bf16 v[56:59], v[160:163], v[64:67], v[56:59]
	s_waitcnt lgkmcnt(5)
	v_mfma_f32_16x16x32_bf16 v[52:55], v[152:155], v[72:75], v[52:55]
	v_mfma_f32_16x16x32_bf16 v[48:51], v[160:163], v[72:75], v[48:51]
	s_waitcnt lgkmcnt(3)
	v_mfma_f32_16x16x32_bf16 v[44:47], v[152:155], v[80:83], v[44:47]
	v_mfma_f32_16x16x32_bf16 v[40:43], v[160:163], v[80:83], v[40:43]
	s_waitcnt lgkmcnt(1)
	v_mfma_f32_16x16x32_bf16 v[36:39], v[152:155], v[88:91], v[36:39]
	v_mfma_f32_16x16x32_bf16 v[32:35], v[160:163], v[88:91], v[32:35]
	v_mfma_f32_16x16x32_bf16 v[60:63], v[156:159], v[68:71], v[60:63]
	v_mfma_f32_16x16x32_bf16 v[56:59], v[134:137], v[68:71], v[56:59]
	v_mfma_f32_16x16x32_bf16 v[52:55], v[156:159], v[76:79], v[52:55]
	v_mfma_f32_16x16x32_bf16 v[48:51], v[134:137], v[76:79], v[48:51]
	v_mfma_f32_16x16x32_bf16 v[44:47], v[156:159], v[84:87], v[44:47]
	v_mfma_f32_16x16x32_bf16 v[40:43], v[134:137], v[84:87], v[40:43]
	s_waitcnt lgkmcnt(0)
	v_mfma_f32_16x16x32_bf16 v[36:39], v[156:159], v[92:95], v[36:39]
	v_mfma_f32_16x16x32_bf16 v[32:35], v[134:137], v[92:95], v[32:35]
	s_setprio 0
	s_setprio 1
	v_mfma_f32_16x16x32_bf16 v[28:31], v[128:131], v[64:67], v[28:31]
	v_mfma_f32_16x16x32_bf16 v[24:27], v[212:215], v[64:67], v[24:27]
	v_mfma_f32_16x16x32_bf16 v[20:23], v[128:131], v[72:75], v[20:23]
	v_mfma_f32_16x16x32_bf16 v[16:19], v[212:215], v[72:75], v[16:19]
	v_mfma_f32_16x16x32_bf16 v[12:15], v[128:131], v[80:83], v[12:15]
	v_mfma_f32_16x16x32_bf16 v[8:11], v[212:215], v[80:83], v[8:11]
	v_mfma_f32_16x16x32_bf16 v[4:7], v[128:131], v[88:91], v[4:7]
	v_mfma_f32_16x16x32_bf16 v[0:3], v[212:215], v[88:91], v[0:3]
	v_mfma_f32_16x16x32_bf16 v[134:137], v[208:211], v[68:71], v[28:31]
	v_mfma_f32_16x16x32_bf16 v[152:155], v[216:219], v[68:71], v[24:27]
	v_mfma_f32_16x16x32_bf16 v[156:159], v[208:211], v[76:79], v[20:23]
	v_mfma_f32_16x16x32_bf16 v[160:163], v[216:219], v[76:79], v[16:19]
	v_mfma_f32_16x16x32_bf16 v[204:207], v[208:211], v[84:87], v[12:15]
	v_mfma_f32_16x16x32_bf16 v[224:227], v[216:219], v[84:87], v[8:11]
	v_mfma_f32_16x16x32_bf16 v[128:131], v[208:211], v[92:95], v[4:7]
	v_mfma_f32_16x16x32_bf16 v[208:211], v[216:219], v[92:95], v[0:3]
	s_setprio 0
	s_barrier
	ds_read_b128 v[24:27], v143
	ds_read_b128 v[28:31], v144
	ds_read_b128 v[142:145], v145
	ds_read_b128 v[212:215], v146
	ds_read_b128 v[0:3], v132 offset:32768
	ds_read_b128 v[4:7], v132 offset:33792
	ds_read_b128 v[8:11], v132 offset:34816
	ds_read_b128 v[12:15], v132 offset:35840
	ds_read_b128 v[16:19], v132 offset:36864
	ds_read_b128 v[20:23], v132 offset:37888
	ds_read_b128 v[216:219], v132 offset:38912
	ds_read_b128 v[228:231], v132 offset:39936
	s_waitcnt vmcnt(2)
	s_barrier
; #define LDA8(dst, b, h)                                                                                               \
;   _Pragma("unroll") for (int m = 0; m < 4; ++m) _Pragma("unroll") for (int k = 0; k < 2; ++k)                         \
;     dst[m][k] = *(const bf16x8*)(SA8(b, h) + la + m * 2048 + k * 1024)
; #define LDB8(dst, b, h)                                                                                               \
;   _Pragma("unroll") for (int n = 0; n < 2; ++n) _Pragma("unroll") for (int k = 0; k < 2; ++k)                         \
;     dst[n][k] = *(const bf16x8*)(SB8(b, h) + lb + n * 2048 + k * 1024)
; #define WAITV8(n) asm volatile("s_waitcnt vmcnt(" #n ")" ::: "memory")
; #define WAITL8(n) asm volatile("s_waitcnt lgkmcnt(" #n ")" ::: "memory")
; #define BAR8 __builtin_amdgcn_s_barrier()
; template <class Epi>
; DEV void gemm_tile8(char* shm, const u16* __restrict__ A, const u16* __restrict__ Bt, int K, int brow, int bcol, Epi& epi) {
;     ...
;   { LDB8(B0, 1, 0); LDA8(At, 1, 0); WAITV8(2); BAR8; WAITL8(0); MMA8(0, 0, At, B0); BAR8;
;     LDB8(B1, 1, 1); WAITV8(0); BAR8; WAITL8(0); MMA8(0, 1, At, B1); BAR8;
;     LDA8(At, 1, 1); BAR8; WAITL8(0); MMA8(1, 0, At, B0); MMA8(1, 1, At, B1); BAR8; }
;   if (wrs == 0) BAR8;
	s_waitcnt lgkmcnt(0)
	s_setprio 1
	s_waitcnt lgkmcnt(7)
	v_mfma_f32_16x16x32_bf16 v[64:67], v[24:27], v[0:3], v[124:127]
	s_waitcnt lgkmcnt(6)
	v_mfma_f32_16x16x32_bf16 v[72:75], v[28:31], v[4:7], v[64:67]
	v_mfma_f32_16x16x32_bf16 v[64:67], v[142:145], v[0:3], v[120:123]
	s_waitcnt lgkmcnt(5)
	v_mfma_f32_16x16x32_bf16 v[68:71], v[24:27], v[8:11], v[116:119]
	v_mfma_f32_16x16x32_bf16 v[76:79], v[142:145], v[8:11], v[112:115]
	s_waitcnt lgkmcnt(3)
	v_mfma_f32_16x16x32_bf16 v[80:83], v[24:27], v[16:19], v[108:111]
	v_mfma_f32_16x16x32_bf16 v[84:87], v[142:145], v[16:19], v[104:107]
	s_waitcnt lgkmcnt(1)
	v_mfma_f32_16x16x32_bf16 v[88:91], v[24:27], v[216:219], v[100:103]
	v_mfma_f32_16x16x32_bf16 v[92:95], v[142:145], v[216:219], v[96:99]
	v_mfma_f32_16x16x32_bf16 v[64:67], v[212:215], v[4:7], v[64:67]
	v_mfma_f32_16x16x32_bf16 v[68:71], v[28:31], v[12:15], v[68:71]
	v_mfma_f32_16x16x32_bf16 v[76:79], v[212:215], v[12:15], v[76:79]
	v_mfma_f32_16x16x32_bf16 v[80:83], v[28:31], v[20:23], v[80:83]
	v_mfma_f32_16x16x32_bf16 v[84:87], v[212:215], v[20:23], v[84:87]
	s_waitcnt lgkmcnt(0)
	v_mfma_f32_16x16x32_bf16 v[88:91], v[28:31], v[228:231], v[88:91]
	v_mfma_f32_16x16x32_bf16 v[92:95], v[212:215], v[228:231], v[92:95]
	s_setprio 0
	s_barrier
	ds_read_b128 v[232:235], v147
	ds_read_b128 v[236:239], v148
	ds_read_b128 v[146:149], v149
	ds_read_b128 v[240:243], v150
	s_waitcnt vmcnt(0)
	s_barrier
	s_waitcnt lgkmcnt(0)
	s_setprio 1
	s_waitcnt lgkmcnt(3)
	v_mfma_f32_16x16x32_bf16 v[96:99], v[232:235], v[0:3], v[220:223]
	s_waitcnt lgkmcnt(1)
	v_mfma_f32_16x16x32_bf16 v[0:3], v[146:149], v[0:3], v[164:167]
	v_mfma_f32_16x16x32_bf16 v[104:107], v[236:239], v[4:7], v[96:99]
	s_waitcnt lgkmcnt(0)
	v_mfma_f32_16x16x32_bf16 v[96:99], v[240:243], v[4:7], v[0:3]
	v_mfma_f32_16x16x32_bf16 v[0:3], v[232:235], v[8:11], v[168:171]
	v_mfma_f32_16x16x32_bf16 v[100:103], v[236:239], v[12:15], v[0:3]
	v_mfma_f32_16x16x32_bf16 v[0:3], v[146:149], v[8:11], v[172:175]
	v_mfma_f32_16x16x32_bf16 v[108:111], v[240:243], v[12:15], v[0:3]
	v_mfma_f32_16x16x32_bf16 v[0:3], v[232:235], v[16:19], v[176:179]
	v_mfma_f32_16x16x32_bf16 v[112:115], v[236:239], v[20:23], v[0:3]
	v_mfma_f32_16x16x32_bf16 v[0:3], v[146:149], v[16:19], v[180:183]
	v_mfma_f32_16x16x32_bf16 v[116:119], v[240:243], v[20:23], v[0:3]
	v_mfma_f32_16x16x32_bf16 v[0:3], v[232:235], v[216:219], v[184:187]
	v_mfma_f32_16x16x32_bf16 v[120:123], v[236:239], v[228:231], v[0:3]
	v_mfma_f32_16x16x32_bf16 v[0:3], v[146:149], v[216:219], v[188:191]
	v_mfma_f32_16x16x32_bf16 v[124:127], v[240:243], v[228:231], v[0:3]
	s_setprio 0
	s_barrier
	ds_read_b128 v[164:167], v132 offset:49152
	ds_read_b128 v[168:171], v132 offset:50176
	ds_read_b128 v[172:175], v132 offset:51200
	ds_read_b128 v[176:179], v132 offset:52224
	ds_read_b128 v[180:183], v132 offset:53248
	ds_read_b128 v[184:187], v132 offset:54272
	ds_read_b128 v[188:191], v132 offset:55296
	ds_read_b128 v[216:219], v132 offset:56320
	s_barrier
	s_waitcnt lgkmcnt(0)
	s_setprio 1
	s_waitcnt lgkmcnt(7)
	v_mfma_f32_16x16x32_bf16 v[0:3], v[24:27], v[164:167], v[60:63]
	s_waitcnt lgkmcnt(5)
	v_mfma_f32_16x16x32_bf16 v[8:11], v[24:27], v[172:175], v[52:55]
	s_waitcnt lgkmcnt(3)
	v_mfma_f32_16x16x32_bf16 v[16:19], v[24:27], v[180:183], v[44:47]
	s_waitcnt lgkmcnt(1)
	v_mfma_f32_16x16x32_bf16 v[24:27], v[24:27], v[188:191], v[36:39]
	v_mfma_f32_16x16x32_bf16 v[0:3], v[28:31], v[168:171], v[0:3]
	v_mfma_f32_16x16x32_bf16 v[4:7], v[142:145], v[164:167], v[56:59]
	v_mfma_f32_16x16x32_bf16 v[8:11], v[28:31], v[176:179], v[8:11]
	v_mfma_f32_16x16x32_bf16 v[12:15], v[142:145], v[172:175], v[48:51]
	v_mfma_f32_16x16x32_bf16 v[16:19], v[28:31], v[184:187], v[16:19]
	v_mfma_f32_16x16x32_bf16 v[20:23], v[142:145], v[180:183], v[40:43]
	s_waitcnt lgkmcnt(0)
	v_mfma_f32_16x16x32_bf16 v[24:27], v[28:31], v[216:219], v[24:27]
	v_mfma_f32_16x16x32_bf16 v[28:31], v[142:145], v[188:191], v[32:35]
	v_mfma_f32_16x16x32_bf16 v[4:7], v[212:215], v[168:171], v[4:7]
	v_mfma_f32_16x16x32_bf16 v[12:15], v[212:215], v[176:179], v[12:15]
	v_mfma_f32_16x16x32_bf16 v[20:23], v[212:215], v[184:187], v[20:23]
	v_mfma_f32_16x16x32_bf16 v[28:31], v[212:215], v[216:219], v[28:31]
	s_setprio 0
	s_setprio 1
	v_mfma_f32_16x16x32_bf16 v[32:35], v[232:235], v[164:167], v[134:137]
	v_mfma_f32_16x16x32_bf16 v[36:39], v[146:149], v[164:167], v[152:155]
	v_mfma_f32_16x16x32_bf16 v[40:43], v[232:235], v[172:175], v[156:159]
	v_mfma_f32_16x16x32_bf16 v[44:47], v[146:149], v[172:175], v[160:163]
	v_mfma_f32_16x16x32_bf16 v[48:51], v[232:235], v[180:183], v[204:207]
	v_mfma_f32_16x16x32_bf16 v[52:55], v[146:149], v[180:183], v[224:227]
	v_mfma_f32_16x16x32_bf16 v[56:59], v[232:235], v[188:191], v[128:131]
	v_mfma_f32_16x16x32_bf16 v[60:63], v[146:149], v[188:191], v[208:211]
	v_mfma_f32_16x16x32_bf16 v[32:35], v[236:239], v[168:171], v[32:35]
	v_mfma_f32_16x16x32_bf16 v[36:39], v[240:243], v[168:171], v[36:39]
	v_mfma_f32_16x16x32_bf16 v[40:43], v[236:239], v[176:179], v[40:43]
	v_mfma_f32_16x16x32_bf16 v[44:47], v[240:243], v[176:179], v[44:47]
	v_mfma_f32_16x16x32_bf16 v[48:51], v[236:239], v[184:187], v[48:51]
	v_mfma_f32_16x16x32_bf16 v[52:55], v[240:243], v[184:187], v[52:55]
	v_mfma_f32_16x16x32_bf16 v[56:59], v[236:239], v[216:219], v[56:59]
	v_mfma_f32_16x16x32_bf16 v[60:63], v[240:243], v[216:219], v[60:63]
	s_setprio 0
	s_cmp_lg_u32 s45, 0
	s_barrier
	s_cbranch_scc1 .LBB0_471
	s_barrier

; #define LDA8(dst, b, h)                                                                                               \
;   _Pragma("unroll") for (int m = 0; m < 4; ++m) _Pragma("unroll") for (int k = 0; k < 2; ++k)                         \
;     dst[m][k] = *(const bf16x8*)(SA8(b, h) + la + m * 2048 + k * 1024)
; #define LDB8(dst, b, h)                                                                                               \
;   _Pragma("unroll") for (int n = 0; n < 2; ++n) _Pragma("unroll") for (int k = 0; k < 2; ++k)                         \
;     dst[n][k] = *(const bf16x8*)(SB8(b, h) + lb + n * 2048 + k * 1024)
; #define WAITL8(n) asm volatile("s_waitcnt lgkmcnt(" #n ")" ::: "memory")
; #define BAR8 __builtin_amdgcn_s_barrier()
; #define SCHED8 __builtin_amdgcn_sched_barrier(0)
; template <class Epi>
; DEV void gemm_tile8(char* shm, const u16* __restrict__ A, const u16* __restrict__ Bt, int K, int brow, int bcol, Epi& epi) {
;     ...
;   for (int t = 0; t < nt - 2; t += 2) {
;     LDB8(B0, 0, 0); SCHED8; LDA8(At, 0, 0); STAGE8(SA8(1, 1), A, brow + HALF, t + 1);
;     WAITL8(8); BAR8; WAITL8(0); MMA8(0, 0, At, B0); BAR8; SCHED8;
;     LDB8(B1, 0, 1); STAGE8(SB8(0, 0), Bt, bcol, t + 2);
;     BAR8; WAITL8(0); MMA8(0, 1, At, B1); BAR8;
;     LDA8(At, 0, 1); STAGE8(SA8(0, 0), A, brow, t + 2);
;     BAR8; WAITL8(0); MMA8(1, 0, At, B0); BAR8; SCHED8;
;     STAGE8(SB8(0, 1), Bt, bcol + HALF, t + 2);
.LBB0_528:
	v_or_b32_e32 v134, 0x10000, v133
	v_add_u32_e32 v136, 0x10800, v133
	v_add_u32_e32 v135, 0x10400, v133
	ds_read_b128 v[144:147], v134
	ds_read_b128 v[148:151], v135
	v_add_u32_e32 v137, 0x10c00, v133
	ds_read_b128 v[152:155], v136
	ds_read_b128 v[156:159], v137
	v_lshl_add_u64 v[228:229], s[22:23], 0, v[130:131]
	s_mov_b64 s[94:95], 0x6240080
	s_add_i32 s93, s45, 0xc000
	v_lshl_add_u64 v[138:139], v[228:229], 0, s[94:95]
	s_mov_b32 m0, s93
	s_mov_b64 s[94:95], 0x6260080
	s_add_i32 s25, s45, 0xe000
	ds_read_b128 v[160:163], v132
	ds_read_b128 v[164:167], v132 offset:1024
	ds_read_b128 v[168:171], v132 offset:2048
	ds_read_b128 v[172:175], v132 offset:3072
	ds_read_b128 v[176:179], v132 offset:4096
	ds_read_b128 v[180:183], v132 offset:5120
	ds_read_b128 v[184:187], v132 offset:6144
	ds_read_b128 v[188:191], v132 offset:7168
	global_load_lds_dwordx4 v[138:139], off
	v_lshl_add_u64 v[138:139], v[228:229], 0, s[94:95]
	s_mov_b32 m0, s25
	s_nop 0
	global_load_lds_dwordx4 v[138:139], off
	s_waitcnt lgkmcnt(8)
	s_barrier
	s_waitcnt lgkmcnt(0)
	s_setprio 1
	s_waitcnt lgkmcnt(0)
	v_mfma_f32_16x16x32_bf16 v[124:127], v[144:147], v[160:163], v[124:127]
	v_mfma_f32_16x16x32_bf16 v[120:123], v[152:155], v[160:163], v[120:123]
	v_mfma_f32_16x16x32_bf16 v[116:119], v[144:147], v[168:171], v[116:119]
	v_mfma_f32_16x16x32_bf16 v[112:115], v[152:155], v[168:171], v[112:115]
	v_mfma_f32_16x16x32_bf16 v[108:111], v[144:147], v[176:179], v[108:111]
	v_mfma_f32_16x16x32_bf16 v[104:107], v[152:155], v[176:179], v[104:107]
	v_mfma_f32_16x16x32_bf16 v[100:103], v[144:147], v[184:187], v[100:103]
	v_mfma_f32_16x16x32_bf16 v[96:99], v[152:155], v[184:187], v[96:99]
	v_mfma_f32_16x16x32_bf16 v[124:127], v[148:151], v[164:167], v[124:127]
	v_mfma_f32_16x16x32_bf16 v[120:123], v[156:159], v[164:167], v[120:123]
	v_mfma_f32_16x16x32_bf16 v[116:119], v[148:151], v[172:175], v[116:119]
	v_mfma_f32_16x16x32_bf16 v[112:115], v[156:159], v[172:175], v[112:115]
	v_mfma_f32_16x16x32_bf16 v[108:111], v[148:151], v[180:183], v[108:111]
	v_mfma_f32_16x16x32_bf16 v[104:107], v[156:159], v[180:183], v[104:107]
	v_mfma_f32_16x16x32_bf16 v[100:103], v[148:151], v[188:191], v[100:103]
	v_mfma_f32_16x16x32_bf16 v[96:99], v[156:159], v[188:191], v[96:99]
	s_setprio 0
	s_barrier
	v_lshl_add_u64 v[230:231], s[20:21], 0, v[130:131]
	s_mov_b64 s[94:95], 0xd00100
	s_mov_b32 m0, s48
	v_or_b32_e32 v138, 0x14000, v133
	v_add_u32_e32 v140, 0x14800, v133
	v_lshl_add_u64 v[220:221], v[230:231], 0, s[94:95]
	s_mov_b64 s[94:95], 0xd20100
	v_add_u32_e32 v139, 0x14400, v133
	ds_read_b128 v[204:207], v138
	ds_read_b128 v[208:211], v139
	v_add_u32_e32 v142, 0x14c00, v133
	ds_read_b128 v[212:215], v140
	ds_read_b128 v[216:219], v142
	global_load_lds_dwordx4 v[220:221], off
	v_lshl_add_u64 v[220:221], v[230:231], 0, s[94:95]
	s_mov_b32 m0, s54
	s_nop 0
	global_load_lds_dwordx4 v[220:221], off
	s_barrier
	s_waitcnt lgkmcnt(0)
	s_setprio 1
	s_waitcnt lgkmcnt(0)
	v_mfma_f32_16x16x32_bf16 v[92:95], v[204:207], v[160:163], v[92:95]
	v_mfma_f32_16x16x32_bf16 v[88:91], v[212:215], v[160:163], v[88:91]
	v_mfma_f32_16x16x32_bf16 v[84:87], v[204:207], v[168:171], v[84:87]
	v_mfma_f32_16x16x32_bf16 v[80:83], v[212:215], v[168:171], v[80:83]
	v_mfma_f32_16x16x32_bf16 v[76:79], v[204:207], v[176:179], v[76:79]
	v_mfma_f32_16x16x32_bf16 v[72:75], v[212:215], v[176:179], v[72:75]
	v_mfma_f32_16x16x32_bf16 v[68:71], v[204:207], v[184:187], v[68:71]
	v_mfma_f32_16x16x32_bf16 v[64:67], v[212:215], v[184:187], v[64:67]
	v_mfma_f32_16x16x32_bf16 v[92:95], v[208:211], v[164:167], v[92:95]
	v_mfma_f32_16x16x32_bf16 v[88:91], v[216:219], v[164:167], v[88:91]
	v_mfma_f32_16x16x32_bf16 v[84:87], v[208:211], v[172:175], v[84:87]
	v_mfma_f32_16x16x32_bf16 v[80:83], v[216:219], v[172:175], v[80:83]
	v_mfma_f32_16x16x32_bf16 v[76:79], v[208:211], v[180:183], v[76:79]
	v_mfma_f32_16x16x32_bf16 v[72:75], v[216:219], v[180:183], v[72:75]
	v_mfma_f32_16x16x32_bf16 v[68:71], v[208:211], v[188:191], v[68:71]
	v_mfma_f32_16x16x32_bf16 v[64:67], v[216:219], v[188:191], v[64:67]
	s_setprio 0
	s_mov_b64 s[94:95], 0x6200100
	s_mov_b32 m0, s45
	v_lshl_add_u64 v[220:221], v[228:229], 0, s[94:95]
	s_mov_b64 s[94:95], 0x6220100
	s_barrier
	ds_read_b128 v[160:163], v132 offset:16384
	ds_read_b128 v[164:167], v132 offset:17408
	ds_read_b128 v[168:171], v132 offset:18432
	ds_read_b128 v[172:175], v132 offset:19456
	ds_read_b128 v[176:179], v132 offset:20480
	ds_read_b128 v[180:183], v132 offset:21504
	ds_read_b128 v[184:187], v132 offset:22528
	ds_read_b128 v[188:191], v132 offset:23552
	global_load_lds_dwordx4 v[220:221], off
	v_lshl_add_u64 v[220:221], v[228:229], 0, s[94:95]
	s_mov_b32 m0, s55
	s_nop 0
	global_load_lds_dwordx4 v[220:221], off
	s_barrier
	s_waitcnt lgkmcnt(0)
	s_setprio 1
	s_waitcnt lgkmcnt(0)
	v_mfma_f32_16x16x32_bf16 v[60:63], v[144:147], v[160:163], v[60:63]
	v_mfma_f32_16x16x32_bf16 v[56:59], v[152:155], v[160:163], v[56:59]
	v_mfma_f32_16x16x32_bf16 v[52:55], v[144:147], v[168:171], v[52:55]
	v_mfma_f32_16x16x32_bf16 v[48:51], v[152:155], v[168:171], v[48:51]
	v_mfma_f32_16x16x32_bf16 v[44:47], v[144:147], v[176:179], v[44:47]
	v_mfma_f32_16x16x32_bf16 v[40:43], v[152:155], v[176:179], v[40:43]
	v_mfma_f32_16x16x32_bf16 v[36:39], v[144:147], v[184:187], v[36:39]
	v_mfma_f32_16x16x32_bf16 v[32:35], v[152:155], v[184:187], v[32:35]
	v_mfma_f32_16x16x32_bf16 v[60:63], v[148:151], v[164:167], v[60:63]
	v_mfma_f32_16x16x32_bf16 v[56:59], v[156:159], v[164:167], v[56:59]
	v_mfma_f32_16x16x32_bf16 v[52:55], v[148:151], v[172:175], v[52:55]
	v_mfma_f32_16x16x32_bf16 v[48:51], v[156:159], v[172:175], v[48:51]
	v_mfma_f32_16x16x32_bf16 v[44:47], v[148:151], v[180:183], v[44:47]
	v_mfma_f32_16x16x32_bf16 v[40:43], v[156:159], v[180:183], v[40:43]
	v_mfma_f32_16x16x32_bf16 v[36:39], v[148:151], v[188:191], v[36:39]
	v_mfma_f32_16x16x32_bf16 v[32:35], v[156:159], v[188:191], v[32:35]
	s_setprio 0
	s_barrier
; #define LDA8(dst, b, h)                                                                                               \
;   _Pragma("unroll") for (int m = 0; m < 4; ++m) _Pragma("unroll") for (int k = 0; k < 2; ++k)                         \
;     dst[m][k] = *(const bf16x8*)(SA8(b, h) + la + m * 2048 + k * 1024)
; #define LDB8(dst, b, h)                                                                                               \
;   _Pragma("unroll") for (int n = 0; n < 2; ++n) _Pragma("unroll") for (int k = 0; k < 2; ++k)                         \
;     dst[n][k] = *(const bf16x8*)(SB8(b, h) + lb + n * 2048 + k * 1024)
; #define WAITV8(n) asm volatile("s_waitcnt vmcnt(" #n ")" ::: "memory")
; #define WAITL8(n) asm volatile("s_waitcnt lgkmcnt(" #n ")" ::: "memory")
; #define BAR8 __builtin_amdgcn_s_barrier()
; #define SCHED8 __builtin_amdgcn_sched_barrier(0)
; template <class Epi>
; DEV void gemm_tile8(char* shm, const u16* __restrict__ A, const u16* __restrict__ Bt, int K, int brow, int bcol, Epi& epi) {
;     ...
;     STAGE8(SB8(0, 1), Bt, bcol + HALF, t + 2);
;     WAITV8(6); BAR8; MMA8(1, 1, At, B1); BAR8;
;     LDB8(B0, 1, 0); SCHED8; LDA8(At, 1, 0); STAGE8(SA8(0, 1), A, brow + HALF, t + 2);
;     WAITL8(8); BAR8; WAITL8(0); MMA8(0, 0, At, B0); BAR8; SCHED8;
;     LDB8(B1, 1, 1); STAGE8(SB8(1, 0), Bt, bcol, t + 3);
;     BAR8; WAITL8(0); MMA8(0, 1, At, B1); BAR8;
	s_mov_b64 s[94:95], 0xd40100
	s_mov_b32 m0, s70
	v_lshl_add_u64 v[144:145], v[230:231], 0, s[94:95]
	s_mov_b64 s[94:95], 0xd60100
	global_load_lds_dwordx4 v[144:145], off
	v_lshl_add_u64 v[144:145], v[230:231], 0, s[94:95]
	s_mov_b32 m0, s71
	s_nop 0
	global_load_lds_dwordx4 v[144:145], off
	s_waitcnt vmcnt(6)
	s_barrier
	s_setprio 1
	v_mfma_f32_16x16x32_bf16 v[28:31], v[204:207], v[160:163], v[28:31]
	v_mfma_f32_16x16x32_bf16 v[24:27], v[212:215], v[160:163], v[24:27]
	v_mfma_f32_16x16x32_bf16 v[20:23], v[204:207], v[168:171], v[20:23]
	v_mfma_f32_16x16x32_bf16 v[16:19], v[212:215], v[168:171], v[16:19]
	v_mfma_f32_16x16x32_bf16 v[12:15], v[204:207], v[176:179], v[12:15]
	v_mfma_f32_16x16x32_bf16 v[8:11], v[212:215], v[176:179], v[8:11]
	v_mfma_f32_16x16x32_bf16 v[4:7], v[204:207], v[184:187], v[4:7]
	v_mfma_f32_16x16x32_bf16 v[0:3], v[212:215], v[184:187], v[0:3]
	v_mfma_f32_16x16x32_bf16 v[28:31], v[208:211], v[164:167], v[28:31]
	v_mfma_f32_16x16x32_bf16 v[24:27], v[216:219], v[164:167], v[24:27]
	v_mfma_f32_16x16x32_bf16 v[20:23], v[208:211], v[172:175], v[20:23]
	v_mfma_f32_16x16x32_bf16 v[16:19], v[216:219], v[172:175], v[16:19]
	v_mfma_f32_16x16x32_bf16 v[12:15], v[208:211], v[180:183], v[12:15]
	v_mfma_f32_16x16x32_bf16 v[8:11], v[216:219], v[180:183], v[8:11]
	v_mfma_f32_16x16x32_bf16 v[4:7], v[208:211], v[188:191], v[4:7]
	v_mfma_f32_16x16x32_bf16 v[0:3], v[216:219], v[188:191], v[0:3]
	s_setprio 0
	v_or_b32_e32 v143, 0x18000, v133
	v_add_u32_e32 v145, 0x18800, v133
	s_barrier
	v_add_u32_e32 v144, 0x18400, v133
	ds_read_b128 v[152:155], v143
	ds_read_b128 v[156:159], v144
	v_add_u32_e32 v146, 0x18c00, v133
	ds_read_b128 v[160:163], v145
	ds_read_b128 v[164:167], v146
	s_mov_b64 s[94:95], 0x6240100
	s_mov_b32 m0, s72
	v_lshl_add_u64 v[148:149], v[228:229], 0, s[94:95]
	s_mov_b64 s[94:95], 0x6260100
	ds_read_b128 v[168:171], v132 offset:32768
	ds_read_b128 v[172:175], v132 offset:33792
	ds_read_b128 v[176:179], v132 offset:34816
	ds_read_b128 v[180:183], v132 offset:35840
	ds_read_b128 v[184:187], v132 offset:36864
	ds_read_b128 v[188:191], v132 offset:37888
	ds_read_b128 v[204:207], v132 offset:38912
	ds_read_b128 v[208:211], v132 offset:39936
	global_load_lds_dwordx4 v[148:149], off
	v_lshl_add_u64 v[148:149], v[228:229], 0, s[94:95]
	s_mov_b32 m0, s73
	s_nop 0
	global_load_lds_dwordx4 v[148:149], off
	s_waitcnt lgkmcnt(8)
	s_barrier
	s_waitcnt lgkmcnt(0)
	s_setprio 1
	s_waitcnt lgkmcnt(0)
	v_mfma_f32_16x16x32_bf16 v[124:127], v[152:155], v[168:171], v[124:127]
	v_mfma_f32_16x16x32_bf16 v[120:123], v[160:163], v[168:171], v[120:123]
	v_mfma_f32_16x16x32_bf16 v[116:119], v[152:155], v[176:179], v[116:119]
	v_mfma_f32_16x16x32_bf16 v[112:115], v[160:163], v[176:179], v[112:115]
	v_mfma_f32_16x16x32_bf16 v[108:111], v[152:155], v[184:187], v[108:111]
	v_mfma_f32_16x16x32_bf16 v[104:107], v[160:163], v[184:187], v[104:107]
	v_mfma_f32_16x16x32_bf16 v[100:103], v[152:155], v[204:207], v[100:103]
	v_mfma_f32_16x16x32_bf16 v[96:99], v[160:163], v[204:207], v[96:99]
	v_mfma_f32_16x16x32_bf16 v[124:127], v[156:159], v[172:175], v[124:127]
	v_mfma_f32_16x16x32_bf16 v[120:123], v[164:167], v[172:175], v[120:123]
	v_mfma_f32_16x16x32_bf16 v[116:119], v[156:159], v[180:183], v[116:119]
	v_mfma_f32_16x16x32_bf16 v[112:115], v[164:167], v[180:183], v[112:115]
	v_mfma_f32_16x16x32_bf16 v[108:111], v[156:159], v[188:191], v[108:111]
	v_mfma_f32_16x16x32_bf16 v[104:107], v[164:167], v[188:191], v[104:107]
	v_mfma_f32_16x16x32_bf16 v[100:103], v[156:159], v[208:211], v[100:103]
	v_mfma_f32_16x16x32_bf16 v[96:99], v[164:167], v[208:211], v[96:99]
	s_setprio 0
	s_barrier
	s_mov_b64 s[94:95], 0xd00180
	s_mov_b32 m0, s81
	v_or_b32_e32 v147, 0x1c000, v133
	v_add_u32_e32 v149, 0x1c800, v133
	v_lshl_add_u64 v[232:233], v[230:231], 0, s[94:95]
	s_mov_b64 s[94:95], 0xd20180
	v_add_u32_e32 v148, 0x1c400, v133
	ds_read_b128 v[212:215], v147
	ds_read_b128 v[216:219], v148
	v_add_u32_e32 v150, 0x1cc00, v133
	ds_read_b128 v[220:223], v149
	ds_read_b128 v[224:227], v150
	global_load_lds_dwordx4 v[232:233], off
	v_lshl_add_u64 v[232:233], v[230:231], 0, s[94:95]
	s_mov_b32 m0, s84
	s_nop 0
	global_load_lds_dwordx4 v[232:233], off
	s_barrier
	s_waitcnt lgkmcnt(0)
	s_setprio 1
	s_waitcnt lgkmcnt(0)
	v_mfma_f32_16x16x32_bf16 v[92:95], v[212:215], v[168:171], v[92:95]
	v_mfma_f32_16x16x32_bf16 v[88:91], v[220:223], v[168:171], v[88:91]
	v_mfma_f32_16x16x32_bf16 v[84:87], v[212:215], v[176:179], v[84:87]
	v_mfma_f32_16x16x32_bf16 v[80:83], v[220:223], v[176:179], v[80:83]
	v_mfma_f32_16x16x32_bf16 v[76:79], v[212:215], v[184:187], v[76:79]
	v_mfma_f32_16x16x32_bf16 v[72:75], v[220:223], v[184:187], v[72:75]
	v_mfma_f32_16x16x32_bf16 v[68:71], v[212:215], v[204:207], v[68:71]
	v_mfma_f32_16x16x32_bf16 v[64:67], v[220:223], v[204:207], v[64:67]
	v_mfma_f32_16x16x32_bf16 v[92:95], v[216:219], v[172:175], v[92:95]
	v_mfma_f32_16x16x32_bf16 v[88:91], v[224:227], v[172:175], v[88:91]
	v_mfma_f32_16x16x32_bf16 v[84:87], v[216:219], v[180:183], v[84:87]
	v_mfma_f32_16x16x32_bf16 v[80:83], v[224:227], v[180:183], v[80:83]
	v_mfma_f32_16x16x32_bf16 v[76:79], v[216:219], v[188:191], v[76:79]
	v_mfma_f32_16x16x32_bf16 v[72:75], v[224:227], v[188:191], v[72:75]
	v_mfma_f32_16x16x32_bf16 v[68:71], v[216:219], v[208:211], v[68:71]
	v_mfma_f32_16x16x32_bf16 v[64:67], v[224:227], v[208:211], v[64:67]
	s_setprio 0
	s_mov_b64 s[94:95], 0x6200180
	s_mov_b32 m0, s85
	v_lshl_add_u64 v[232:233], v[228:229], 0, s[94:95]
	s_mov_b64 s[94:95], 0x6220180
	s_barrier
; #define LDA8(dst, b, h)                                                                                               \
;   _Pragma("unroll") for (int m = 0; m < 4; ++m) _Pragma("unroll") for (int k = 0; k < 2; ++k)                         \
;     dst[m][k] = *(const bf16x8*)(SA8(b, h) + la + m * 2048 + k * 1024)
; #define LDB8(dst, b, h)                                                                                               \
;   _Pragma("unroll") for (int n = 0; n < 2; ++n) _Pragma("unroll") for (int k = 0; k < 2; ++k)                         \
;     dst[n][k] = *(const bf16x8*)(SB8(b, h) + lb + n * 2048 + k * 1024)
; #define WAITV8(n) asm volatile("s_waitcnt vmcnt(" #n ")" ::: "memory")
; #define WAITL8(n) asm volatile("s_waitcnt lgkmcnt(" #n ")" ::: "memory")
; #define BAR8 __builtin_amdgcn_s_barrier()
; #define SCHED8 __builtin_amdgcn_sched_barrier(0)
; template <class Epi>
; DEV void gemm_tile8(char* shm, const u16* __restrict__ A, const u16* __restrict__ Bt, int K, int brow, int bcol, Epi& epi) {
;     ...
;     LDA8(At, 1, 1); STAGE8(SA8(1, 0), A, brow, t + 3);
;     BAR8; WAITL8(0); MMA8(1, 0, At, B0); BAR8; SCHED8;
;     STAGE8(SB8(1, 1), Bt, bcol + HALF, t + 3);
;     WAITV8(6); BAR8; MMA8(1, 1, At, B1); BAR8;
;   }
;   { LDB8(B0, 0, 0); LDA8(At, 0, 0); STAGE8(SA8(1, 1), A, brow + HALF, nt - 1);
;     BAR8; WAITL8(0); MMA8(0, 0, At, B0); BAR8;
;     LDB8(B1, 0, 1); BAR8; WAITL8(0); MMA8(0, 1, At, B1); BAR8;
	ds_read_b128 v[168:171], v132 offset:49152
	ds_read_b128 v[172:175], v132 offset:50176
	ds_read_b128 v[176:179], v132 offset:51200
	ds_read_b128 v[180:183], v132 offset:52224
	ds_read_b128 v[184:187], v132 offset:53248
	ds_read_b128 v[188:191], v132 offset:54272
	ds_read_b128 v[204:207], v132 offset:55296
	ds_read_b128 v[208:211], v132 offset:56320
	global_load_lds_dwordx4 v[232:233], off
	v_lshl_add_u64 v[228:229], v[228:229], 0, s[94:95]
	s_mov_b32 m0, s90
	s_nop 0
	global_load_lds_dwordx4 v[228:229], off
	s_barrier
	s_waitcnt lgkmcnt(0)
	s_setprio 1
	s_waitcnt lgkmcnt(0)
	v_mfma_f32_16x16x32_bf16 v[60:63], v[152:155], v[168:171], v[60:63]
	v_mfma_f32_16x16x32_bf16 v[56:59], v[160:163], v[168:171], v[56:59]
	v_mfma_f32_16x16x32_bf16 v[52:55], v[152:155], v[176:179], v[52:55]
	v_mfma_f32_16x16x32_bf16 v[48:51], v[160:163], v[176:179], v[48:51]
	v_mfma_f32_16x16x32_bf16 v[44:47], v[152:155], v[184:187], v[44:47]
	v_mfma_f32_16x16x32_bf16 v[40:43], v[160:163], v[184:187], v[40:43]
	v_mfma_f32_16x16x32_bf16 v[36:39], v[152:155], v[204:207], v[36:39]
	v_mfma_f32_16x16x32_bf16 v[32:35], v[160:163], v[204:207], v[32:35]
	v_mfma_f32_16x16x32_bf16 v[60:63], v[156:159], v[172:175], v[60:63]
	v_mfma_f32_16x16x32_bf16 v[56:59], v[164:167], v[172:175], v[56:59]
	v_mfma_f32_16x16x32_bf16 v[52:55], v[156:159], v[180:183], v[52:55]
	v_mfma_f32_16x16x32_bf16 v[48:51], v[164:167], v[180:183], v[48:51]
	v_mfma_f32_16x16x32_bf16 v[44:47], v[156:159], v[188:191], v[44:47]
	v_mfma_f32_16x16x32_bf16 v[40:43], v[164:167], v[188:191], v[40:43]
	v_mfma_f32_16x16x32_bf16 v[36:39], v[156:159], v[208:211], v[36:39]
	v_mfma_f32_16x16x32_bf16 v[32:35], v[164:167], v[208:211], v[32:35]
	s_setprio 0
	s_barrier
	s_mov_b64 s[94:95], 0xd40180
	s_mov_b32 m0, s91
	v_lshl_add_u64 v[152:153], v[230:231], 0, s[94:95]
	s_mov_b64 s[94:95], 0xd60180
	global_load_lds_dwordx4 v[152:153], off
	v_lshl_add_u64 v[152:153], v[230:231], 0, s[94:95]
	s_mov_b32 m0, s92
	s_nop 0
	global_load_lds_dwordx4 v[152:153], off
	s_waitcnt vmcnt(6)
	s_barrier
	s_setprio 1
	v_mfma_f32_16x16x32_bf16 v[28:31], v[212:215], v[168:171], v[28:31]
	v_mfma_f32_16x16x32_bf16 v[24:27], v[220:223], v[168:171], v[24:27]
	v_mfma_f32_16x16x32_bf16 v[20:23], v[212:215], v[176:179], v[20:23]
	v_mfma_f32_16x16x32_bf16 v[16:19], v[220:223], v[176:179], v[16:19]
	v_mfma_f32_16x16x32_bf16 v[12:15], v[212:215], v[184:187], v[12:15]
	v_mfma_f32_16x16x32_bf16 v[8:11], v[220:223], v[184:187], v[8:11]
	v_mfma_f32_16x16x32_bf16 v[4:7], v[212:215], v[204:207], v[4:7]
	v_mfma_f32_16x16x32_bf16 v[0:3], v[220:223], v[204:207], v[0:3]
	v_mfma_f32_16x16x32_bf16 v[28:31], v[216:219], v[172:175], v[28:31]
	v_mfma_f32_16x16x32_bf16 v[24:27], v[224:227], v[172:175], v[24:27]
	v_mfma_f32_16x16x32_bf16 v[20:23], v[216:219], v[180:183], v[20:23]
	v_mfma_f32_16x16x32_bf16 v[16:19], v[224:227], v[180:183], v[16:19]
	v_mfma_f32_16x16x32_bf16 v[12:15], v[216:219], v[188:191], v[12:15]
	v_mfma_f32_16x16x32_bf16 v[8:11], v[224:227], v[188:191], v[8:11]
	v_mfma_f32_16x16x32_bf16 v[4:7], v[216:219], v[208:211], v[4:7]
	v_mfma_f32_16x16x32_bf16 v[0:3], v[224:227], v[208:211], v[0:3]
	s_setprio 0
	s_add_i32 s24, s24, 2
	s_add_u32 s20, s20, 0x100
	s_addc_u32 s21, s21, 0
	s_add_u32 s22, s22, 0x100
	s_addc_u32 s23, s23, 0
	s_cmp_lt_u32 s24, 12
	s_barrier
	s_cbranch_scc1 .LBB0_528
	s_mov_b64 s[20:21], 0x780
	s_mov_b32 m0, s93
	v_lshl_add_u64 v[130:131], v[128:129], 0, s[20:21]
	s_mov_b64 s[20:21], 0x20780
	ds_read_b128 v[152:155], v134
	ds_read_b128 v[156:159], v135
	ds_read_b128 v[160:163], v136
	ds_read_b128 v[134:137], v137
	ds_read_b128 v[164:167], v132
	ds_read_b128 v[168:171], v132 offset:1024
	ds_read_b128 v[172:175], v132 offset:2048
	ds_read_b128 v[176:179], v132 offset:3072
	ds_read_b128 v[180:183], v132 offset:4096
	ds_read_b128 v[184:187], v132 offset:5120
	ds_read_b128 v[188:191], v132 offset:6144
	ds_read_b128 v[204:207], v132 offset:7168
	global_load_lds_dwordx4 v[130:131], off
	v_lshl_add_u64 v[128:129], v[128:129], 0, s[20:21]
	s_mov_b32 m0, s25
	s_nop 0
	global_load_lds_dwordx4 v[128:129], off
	s_barrier
	s_waitcnt lgkmcnt(0)
	s_setprio 1
	s_waitcnt lgkmcnt(0)
	v_mfma_f32_16x16x32_bf16 v[124:127], v[152:155], v[164:167], v[124:127]
	v_mfma_f32_16x16x32_bf16 v[120:123], v[160:163], v[164:167], v[120:123]
	v_mfma_f32_16x16x32_bf16 v[116:119], v[152:155], v[172:175], v[116:119]
	v_mfma_f32_16x16x32_bf16 v[112:115], v[160:163], v[172:175], v[112:115]
	v_mfma_f32_16x16x32_bf16 v[108:111], v[152:155], v[180:183], v[108:111]
	v_mfma_f32_16x16x32_bf16 v[104:107], v[160:163], v[180:183], v[104:107]
	v_mfma_f32_16x16x32_bf16 v[100:103], v[152:155], v[188:191], v[100:103]
	v_mfma_f32_16x16x32_bf16 v[96:99], v[160:163], v[188:191], v[96:99]
	v_mfma_f32_16x16x32_bf16 v[124:127], v[156:159], v[168:171], v[124:127]
	v_mfma_f32_16x16x32_bf16 v[120:123], v[134:137], v[168:171], v[120:123]
	v_mfma_f32_16x16x32_bf16 v[116:119], v[156:159], v[176:179], v[116:119]
	v_mfma_f32_16x16x32_bf16 v[112:115], v[134:137], v[176:179], v[112:115]
	v_mfma_f32_16x16x32_bf16 v[108:111], v[156:159], v[184:187], v[108:111]
	v_mfma_f32_16x16x32_bf16 v[104:107], v[134:137], v[184:187], v[104:107]
	v_mfma_f32_16x16x32_bf16 v[100:103], v[156:159], v[204:207], v[100:103]
	v_mfma_f32_16x16x32_bf16 v[96:99], v[134:137], v[204:207], v[96:99]
	s_setprio 0
	s_barrier
	ds_read_b128 v[128:131], v138
	ds_read_b128 v[208:211], v139
	ds_read_b128 v[212:215], v140
	ds_read_b128 v[216:219], v142
	s_barrier
; #define LDA8(dst, b, h)                                                                                               \
;   _Pragma("unroll") for (int m = 0; m < 4; ++m) _Pragma("unroll") for (int k = 0; k < 2; ++k)                         \
;     dst[m][k] = *(const bf16x8*)(SA8(b, h) + la + m * 2048 + k * 1024)
; #define LDB8(dst, b, h)                                                                                               \
;   _Pragma("unroll") for (int n = 0; n < 2; ++n) _Pragma("unroll") for (int k = 0; k < 2; ++k)                         \
;     dst[n][k] = *(const bf16x8*)(SB8(b, h) + lb + n * 2048 + k * 1024)
; #define WAITV8(n) asm volatile("s_waitcnt vmcnt(" #n ")" ::: "memory")
; #define WAITL8(n) asm volatile("s_waitcnt lgkmcnt(" #n ")" ::: "memory")
; #define BAR8 __builtin_amdgcn_s_barrier()
; template <class Epi>
; DEV void gemm_tile8(char* shm, const u16* __restrict__ A, const u16* __restrict__ Bt, int K, int brow, int bcol, Epi& epi) {
;     ...
;     LDB8(B1, 0, 1); BAR8; WAITL8(0); MMA8(0, 1, At, B1); BAR8;
;     LDA8(At, 0, 1); WAITV8(4); BAR8; WAITL8(0); MMA8(1, 0, At, B0); MMA8(1, 1, At, B1); BAR8; }
;   { LDB8(B0, 1, 0); LDA8(At, 1, 0); WAITV8(2); BAR8; WAITL8(0); MMA8(0, 0, At, B0); BAR8;
	s_waitcnt lgkmcnt(0)
	s_setprio 1
	s_waitcnt lgkmcnt(3)
	v_mfma_f32_16x16x32_bf16 v[92:95], v[128:131], v[164:167], v[92:95]
	s_waitcnt lgkmcnt(1)
	v_mfma_f32_16x16x32_bf16 v[88:91], v[212:215], v[164:167], v[88:91]
	v_mfma_f32_16x16x32_bf16 v[84:87], v[128:131], v[172:175], v[84:87]
	v_mfma_f32_16x16x32_bf16 v[80:83], v[212:215], v[172:175], v[80:83]
	v_mfma_f32_16x16x32_bf16 v[76:79], v[128:131], v[180:183], v[76:79]
	v_mfma_f32_16x16x32_bf16 v[72:75], v[212:215], v[180:183], v[72:75]
	v_mfma_f32_16x16x32_bf16 v[68:71], v[128:131], v[188:191], v[68:71]
	v_mfma_f32_16x16x32_bf16 v[64:67], v[212:215], v[188:191], v[64:67]
	v_mfma_f32_16x16x32_bf16 v[220:223], v[208:211], v[168:171], v[92:95]
	s_waitcnt lgkmcnt(0)
	v_mfma_f32_16x16x32_bf16 v[164:167], v[216:219], v[168:171], v[88:91]
	v_mfma_f32_16x16x32_bf16 v[168:171], v[208:211], v[176:179], v[84:87]
	v_mfma_f32_16x16x32_bf16 v[172:175], v[216:219], v[176:179], v[80:83]
	v_mfma_f32_16x16x32_bf16 v[176:179], v[208:211], v[184:187], v[76:79]
	v_mfma_f32_16x16x32_bf16 v[180:183], v[216:219], v[184:187], v[72:75]
	v_mfma_f32_16x16x32_bf16 v[184:187], v[208:211], v[204:207], v[68:71]
	v_mfma_f32_16x16x32_bf16 v[188:191], v[216:219], v[204:207], v[64:67]
	s_setprio 0
	s_barrier
	s_nop 0
	ds_read_b128 v[64:67], v132 offset:16384
	ds_read_b128 v[68:71], v132 offset:17408
	ds_read_b128 v[72:75], v132 offset:18432
	ds_read_b128 v[76:79], v132 offset:19456
	ds_read_b128 v[80:83], v132 offset:20480
	ds_read_b128 v[84:87], v132 offset:21504
	ds_read_b128 v[88:91], v132 offset:22528
	ds_read_b128 v[92:95], v132 offset:23552
	s_waitcnt vmcnt(4)
	s_barrier
	s_waitcnt lgkmcnt(0)
	s_setprio 1
	s_waitcnt lgkmcnt(7)
	v_mfma_f32_16x16x32_bf16 v[60:63], v[152:155], v[64:67], v[60:63]
	v_mfma_f32_16x16x32_bf16 v[56:59], v[160:163], v[64:67], v[56:59]
	s_waitcnt lgkmcnt(5)
	v_mfma_f32_16x16x32_bf16 v[52:55], v[152:155], v[72:75], v[52:55]
	v_mfma_f32_16x16x32_bf16 v[48:51], v[160:163], v[72:75], v[48:51]
	s_waitcnt lgkmcnt(3)
	v_mfma_f32_16x16x32_bf16 v[44:47], v[152:155], v[80:83], v[44:47]
	v_mfma_f32_16x16x32_bf16 v[40:43], v[160:163], v[80:83], v[40:43]
	s_waitcnt lgkmcnt(1)
	v_mfma_f32_16x16x32_bf16 v[36:39], v[152:155], v[88:91], v[36:39]
	v_mfma_f32_16x16x32_bf16 v[32:35], v[160:163], v[88:91], v[32:35]
	v_mfma_f32_16x16x32_bf16 v[60:63], v[156:159], v[68:71], v[60:63]
	v_mfma_f32_16x16x32_bf16 v[56:59], v[134:137], v[68:71], v[56:59]
	v_mfma_f32_16x16x32_bf16 v[52:55], v[156:159], v[76:79], v[52:55]
	v_mfma_f32_16x16x32_bf16 v[48:51], v[134:137], v[76:79], v[48:51]
	v_mfma_f32_16x16x32_bf16 v[44:47], v[156:159], v[84:87], v[44:47]
	v_mfma_f32_16x16x32_bf16 v[40:43], v[134:137], v[84:87], v[40:43]
	s_waitcnt lgkmcnt(0)
	v_mfma_f32_16x16x32_bf16 v[36:39], v[156:159], v[92:95], v[36:39]
	v_mfma_f32_16x16x32_bf16 v[32:35], v[134:137], v[92:95], v[32:35]
	s_setprio 0
	s_setprio 1
	v_mfma_f32_16x16x32_bf16 v[28:31], v[128:131], v[64:67], v[28:31]
	v_mfma_f32_16x16x32_bf16 v[24:27], v[212:215], v[64:67], v[24:27]
	v_mfma_f32_16x16x32_bf16 v[20:23], v[128:131], v[72:75], v[20:23]
	v_mfma_f32_16x16x32_bf16 v[16:19], v[212:215], v[72:75], v[16:19]
	v_mfma_f32_16x16x32_bf16 v[12:15], v[128:131], v[80:83], v[12:15]
	v_mfma_f32_16x16x32_bf16 v[8:11], v[212:215], v[80:83], v[8:11]
	v_mfma_f32_16x16x32_bf16 v[4:7], v[128:131], v[88:91], v[4:7]
	v_mfma_f32_16x16x32_bf16 v[0:3], v[212:215], v[88:91], v[0:3]
	v_mfma_f32_16x16x32_bf16 v[134:137], v[208:211], v[68:71], v[28:31]
	v_mfma_f32_16x16x32_bf16 v[152:155], v[216:219], v[68:71], v[24:27]
	v_mfma_f32_16x16x32_bf16 v[156:159], v[208:211], v[76:79], v[20:23]
	v_mfma_f32_16x16x32_bf16 v[160:163], v[216:219], v[76:79], v[16:19]
	v_mfma_f32_16x16x32_bf16 v[204:207], v[208:211], v[84:87], v[12:15]
	v_mfma_f32_16x16x32_bf16 v[224:227], v[216:219], v[84:87], v[8:11]
	v_mfma_f32_16x16x32_bf16 v[128:131], v[208:211], v[92:95], v[4:7]
	v_mfma_f32_16x16x32_bf16 v[208:211], v[216:219], v[92:95], v[0:3]
	s_setprio 0
	s_barrier
	ds_read_b128 v[24:27], v143
	ds_read_b128 v[28:31], v144
	ds_read_b128 v[142:145], v145
	ds_read_b128 v[212:215], v146
	ds_read_b128 v[0:3], v132 offset:32768
	ds_read_b128 v[4:7], v132 offset:33792
	ds_read_b128 v[8:11], v132 offset:34816
	ds_read_b128 v[12:15], v132 offset:35840
	ds_read_b128 v[16:19], v132 offset:36864
	ds_read_b128 v[20:23], v132 offset:37888
	ds_read_b128 v[216:219], v132 offset:38912
	ds_read_b128 v[228:231], v132 offset:39936
	s_waitcnt vmcnt(2)
	s_barrier
; #define LDA8(dst, b, h)                                                                                               \
;   _Pragma("unroll") for (int m = 0; m < 4; ++m) _Pragma("unroll") for (int k = 0; k < 2; ++k)                         \
;     dst[m][k] = *(const bf16x8*)(SA8(b, h) + la + m * 2048 + k * 1024)
; #define LDB8(dst, b, h)                                                                                               \
;   _Pragma("unroll") for (int n = 0; n < 2; ++n) _Pragma("unroll") for (int k = 0; k < 2; ++k)                         \
;     dst[n][k] = *(const bf16x8*)(SB8(b, h) + lb + n * 2048 + k * 1024)
; #define WAITV8(n) asm volatile("s_waitcnt vmcnt(" #n ")" ::: "memory")
; #define WAITL8(n) asm volatile("s_waitcnt lgkmcnt(" #n ")" ::: "memory")
; #define BAR8 __builtin_amdgcn_s_barrier()
; template <class Epi>
; DEV void gemm_tile8(char* shm, const u16* __restrict__ A, const u16* __restrict__ Bt, int K, int brow, int bcol, Epi& epi) {
;     ...
;   { LDB8(B0, 1, 0); LDA8(At, 1, 0); WAITV8(2); BAR8; WAITL8(0); MMA8(0, 0, At, B0); BAR8;
;     LDB8(B1, 1, 1); WAITV8(0); BAR8; WAITL8(0); MMA8(0, 1, At, B1); BAR8;
;     LDA8(At, 1, 1); BAR8; WAITL8(0); MMA8(1, 0, At, B0); MMA8(1, 1, At, B1); BAR8; }
;   if (wrs == 0) BAR8;
	s_waitcnt lgkmcnt(0)
	s_setprio 1
	s_waitcnt lgkmcnt(7)
	v_mfma_f32_16x16x32_bf16 v[64:67], v[24:27], v[0:3], v[124:127]
	s_waitcnt lgkmcnt(6)
	v_mfma_f32_16x16x32_bf16 v[72:75], v[28:31], v[4:7], v[64:67]
	v_mfma_f32_16x16x32_bf16 v[64:67], v[142:145], v[0:3], v[120:123]
	s_waitcnt lgkmcnt(5)
	v_mfma_f32_16x16x32_bf16 v[68:71], v[24:27], v[8:11], v[116:119]
	v_mfma_f32_16x16x32_bf16 v[76:79], v[142:145], v[8:11], v[112:115]
	s_waitcnt lgkmcnt(3)
	v_mfma_f32_16x16x32_bf16 v[80:83], v[24:27], v[16:19], v[108:111]
	v_mfma_f32_16x16x32_bf16 v[84:87], v[142:145], v[16:19], v[104:107]
	s_waitcnt lgkmcnt(1)
	v_mfma_f32_16x16x32_bf16 v[88:91], v[24:27], v[216:219], v[100:103]
	v_mfma_f32_16x16x32_bf16 v[92:95], v[142:145], v[216:219], v[96:99]
	v_mfma_f32_16x16x32_bf16 v[64:67], v[212:215], v[4:7], v[64:67]
	v_mfma_f32_16x16x32_bf16 v[68:71], v[28:31], v[12:15], v[68:71]
	v_mfma_f32_16x16x32_bf16 v[76:79], v[212:215], v[12:15], v[76:79]
	v_mfma_f32_16x16x32_bf16 v[80:83], v[28:31], v[20:23], v[80:83]
	v_mfma_f32_16x16x32_bf16 v[84:87], v[212:215], v[20:23], v[84:87]
	s_waitcnt lgkmcnt(0)
	v_mfma_f32_16x16x32_bf16 v[88:91], v[28:31], v[228:231], v[88:91]
	v_mfma_f32_16x16x32_bf16 v[92:95], v[212:215], v[228:231], v[92:95]
	s_setprio 0
	s_barrier
	ds_read_b128 v[232:235], v147
	ds_read_b128 v[236:239], v148
	ds_read_b128 v[146:149], v149
	ds_read_b128 v[240:243], v150
	s_waitcnt vmcnt(0)
	s_barrier
	s_waitcnt lgkmcnt(0)
	s_setprio 1
	s_waitcnt lgkmcnt(3)
	v_mfma_f32_16x16x32_bf16 v[96:99], v[232:235], v[0:3], v[220:223]
	s_waitcnt lgkmcnt(1)
	v_mfma_f32_16x16x32_bf16 v[0:3], v[146:149], v[0:3], v[164:167]
	v_mfma_f32_16x16x32_bf16 v[104:107], v[236:239], v[4:7], v[96:99]
	s_waitcnt lgkmcnt(0)
	v_mfma_f32_16x16x32_bf16 v[96:99], v[240:243], v[4:7], v[0:3]
	v_mfma_f32_16x16x32_bf16 v[0:3], v[232:235], v[8:11], v[168:171]
	v_mfma_f32_16x16x32_bf16 v[100:103], v[236:239], v[12:15], v[0:3]
	v_mfma_f32_16x16x32_bf16 v[0:3], v[146:149], v[8:11], v[172:175]
	v_mfma_f32_16x16x32_bf16 v[108:111], v[240:243], v[12:15], v[0:3]
	v_mfma_f32_16x16x32_bf16 v[0:3], v[232:235], v[16:19], v[176:179]
	v_mfma_f32_16x16x32_bf16 v[112:115], v[236:239], v[20:23], v[0:3]
	v_mfma_f32_16x16x32_bf16 v[0:3], v[146:149], v[16:19], v[180:183]
	v_mfma_f32_16x16x32_bf16 v[116:119], v[240:243], v[20:23], v[0:3]
	v_mfma_f32_16x16x32_bf16 v[0:3], v[232:235], v[216:219], v[184:187]
	v_mfma_f32_16x16x32_bf16 v[120:123], v[236:239], v[228:231], v[0:3]
	v_mfma_f32_16x16x32_bf16 v[0:3], v[146:149], v[216:219], v[188:191]
	v_mfma_f32_16x16x32_bf16 v[124:127], v[240:243], v[228:231], v[0:3]
	s_setprio 0
	s_barrier
	ds_read_b128 v[164:167], v132 offset:49152
	ds_read_b128 v[168:171], v132 offset:50176
	ds_read_b128 v[172:175], v132 offset:51200
	ds_read_b128 v[176:179], v132 offset:52224
	ds_read_b128 v[180:183], v132 offset:53248
	ds_read_b128 v[184:187], v132 offset:54272
	ds_read_b128 v[188:191], v132 offset:55296
	ds_read_b128 v[216:219], v132 offset:56320
	s_barrier
	s_waitcnt lgkmcnt(0)
	s_setprio 1
	s_waitcnt lgkmcnt(7)
	v_mfma_f32_16x16x32_bf16 v[0:3], v[24:27], v[164:167], v[60:63]
	s_waitcnt lgkmcnt(5)
	v_mfma_f32_16x16x32_bf16 v[8:11], v[24:27], v[172:175], v[52:55]
	s_waitcnt lgkmcnt(3)
	v_mfma_f32_16x16x32_bf16 v[16:19], v[24:27], v[180:183], v[44:47]
	s_waitcnt lgkmcnt(1)
	v_mfma_f32_16x16x32_bf16 v[24:27], v[24:27], v[188:191], v[36:39]
	v_mfma_f32_16x16x32_bf16 v[0:3], v[28:31], v[168:171], v[0:3]
	v_mfma_f32_16x16x32_bf16 v[4:7], v[142:145], v[164:167], v[56:59]
	v_mfma_f32_16x16x32_bf16 v[8:11], v[28:31], v[176:179], v[8:11]
	v_mfma_f32_16x16x32_bf16 v[12:15], v[142:145], v[172:175], v[48:51]
	v_mfma_f32_16x16x32_bf16 v[16:19], v[28:31], v[184:187], v[16:19]
	v_mfma_f32_16x16x32_bf16 v[20:23], v[142:145], v[180:183], v[40:43]
	s_waitcnt lgkmcnt(0)
	v_mfma_f32_16x16x32_bf16 v[24:27], v[28:31], v[216:219], v[24:27]
	v_mfma_f32_16x16x32_bf16 v[28:31], v[142:145], v[188:191], v[32:35]
	v_mfma_f32_16x16x32_bf16 v[4:7], v[212:215], v[168:171], v[4:7]
	v_mfma_f32_16x16x32_bf16 v[12:15], v[212:215], v[176:179], v[12:15]
	v_mfma_f32_16x16x32_bf16 v[20:23], v[212:215], v[184:187], v[20:23]
	v_mfma_f32_16x16x32_bf16 v[28:31], v[212:215], v[216:219], v[28:31]
	s_setprio 0
	s_setprio 1
	v_mfma_f32_16x16x32_bf16 v[32:35], v[232:235], v[164:167], v[134:137]
	v_mfma_f32_16x16x32_bf16 v[36:39], v[146:149], v[164:167], v[152:155]
	v_mfma_f32_16x16x32_bf16 v[40:43], v[232:235], v[172:175], v[156:159]
	v_mfma_f32_16x16x32_bf16 v[44:47], v[146:149], v[172:175], v[160:163]
	v_mfma_f32_16x16x32_bf16 v[48:51], v[232:235], v[180:183], v[204:207]
	v_mfma_f32_16x16x32_bf16 v[52:55], v[146:149], v[180:183], v[224:227]
	v_mfma_f32_16x16x32_bf16 v[56:59], v[232:235], v[188:191], v[128:131]
	v_mfma_f32_16x16x32_bf16 v[60:63], v[146:149], v[188:191], v[208:211]
	v_mfma_f32_16x16x32_bf16 v[32:35], v[236:239], v[168:171], v[32:35]
	v_mfma_f32_16x16x32_bf16 v[36:39], v[240:243], v[168:171], v[36:39]
	v_mfma_f32_16x16x32_bf16 v[40:43], v[236:239], v[176:179], v[40:43]
	v_mfma_f32_16x16x32_bf16 v[44:47], v[240:243], v[176:179], v[44:47]
	v_mfma_f32_16x16x32_bf16 v[48:51], v[236:239], v[184:187], v[48:51]
	v_mfma_f32_16x16x32_bf16 v[52:55], v[240:243], v[184:187], v[52:55]
	v_mfma_f32_16x16x32_bf16 v[56:59], v[236:239], v[216:219], v[56:59]
	v_mfma_f32_16x16x32_bf16 v[60:63], v[240:243], v[216:219], v[60:63]
	s_setprio 0
	s_cmp_lg_u32 s7, 0
	s_barrier
	s_cbranch_scc1 .LBB0_531
	s_barrier

; #define LDA8(dst, b, h)                                                                                               \
;   _Pragma("unroll") for (int m = 0; m < 4; ++m) _Pragma("unroll") for (int k = 0; k < 2; ++k)                         \
;     dst[m][k] = *(const bf16x8*)(SA8(b, h) + la + m * 2048 + k * 1024)
; #define LDB8(dst, b, h)                                                                                               \
;   _Pragma("unroll") for (int n = 0; n < 2; ++n) _Pragma("unroll") for (int k = 0; k < 2; ++k)                         \
;     dst[n][k] = *(const bf16x8*)(SB8(b, h) + lb + n * 2048 + k * 1024)
; #define WAITL8(n) asm volatile("s_waitcnt lgkmcnt(" #n ")" ::: "memory")
; #define BAR8 __builtin_amdgcn_s_barrier()
; #define SCHED8 __builtin_amdgcn_sched_barrier(0)
; template <class Epi>
; DEV void gemm_tile8(char* shm, const u16* __restrict__ A, const u16* __restrict__ Bt, int K, int brow, int bcol, Epi& epi) {
;     ...
;   for (int t = 0; t < nt - 2; t += 2) {
;     LDB8(B0, 0, 0); SCHED8; LDA8(At, 0, 0); STAGE8(SA8(1, 1), A, brow + HALF, t + 1);
;     WAITL8(8); BAR8; WAITL8(0); MMA8(0, 0, At, B0); BAR8; SCHED8;
;     LDB8(B1, 0, 1); STAGE8(SB8(0, 0), Bt, bcol, t + 2);
;     BAR8; WAITL8(0); MMA8(0, 1, At, B1); BAR8;
;     LDA8(At, 0, 1); STAGE8(SA8(0, 0), A, brow, t + 2);
;     BAR8; WAITL8(0); MMA8(1, 0, At, B0); BAR8; SCHED8;
;     STAGE8(SB8(0, 1), Bt, bcol + HALF, t + 2);
.LBB0_563:
	v_or_b32_e32 v134, 0x10000, v133
	v_add_u32_e32 v136, 0x10800, v133
	v_add_u32_e32 v135, 0x10400, v133
	ds_read_b128 v[144:147], v134
	ds_read_b128 v[148:151], v135
	v_add_u32_e32 v137, 0x10c00, v133
	ds_read_b128 v[152:155], v136
	ds_read_b128 v[156:159], v137
	v_lshl_add_u64 v[228:229], s[18:19], 0, v[130:131]
	s_mov_b64 s[92:93], 0x19ca0080
	s_add_i32 s91, s43, 0xc000
	v_lshl_add_u64 v[138:139], v[228:229], 0, s[92:93]
	s_mov_b32 m0, s91
	s_mov_b64 s[92:93], 0x19cb0080
	s_add_i32 s23, s43, 0xe000
	ds_read_b128 v[160:163], v132
	ds_read_b128 v[164:167], v132 offset:1024
	ds_read_b128 v[168:171], v132 offset:2048
	ds_read_b128 v[172:175], v132 offset:3072
	ds_read_b128 v[176:179], v132 offset:4096
	ds_read_b128 v[180:183], v132 offset:5120
	ds_read_b128 v[184:187], v132 offset:6144
	ds_read_b128 v[188:191], v132 offset:7168
	global_load_lds_dwordx4 v[138:139], off
	v_lshl_add_u64 v[138:139], v[228:229], 0, s[92:93]
	s_mov_b32 m0, s23
	s_nop 0
	global_load_lds_dwordx4 v[138:139], off
	s_waitcnt lgkmcnt(8)
	s_barrier
	s_waitcnt lgkmcnt(0)
	s_setprio 1
	s_waitcnt lgkmcnt(0)
	v_mfma_f32_16x16x32_bf16 v[124:127], v[144:147], v[160:163], v[124:127]
	v_mfma_f32_16x16x32_bf16 v[120:123], v[152:155], v[160:163], v[120:123]
	v_mfma_f32_16x16x32_bf16 v[116:119], v[144:147], v[168:171], v[116:119]
	v_mfma_f32_16x16x32_bf16 v[112:115], v[152:155], v[168:171], v[112:115]
	v_mfma_f32_16x16x32_bf16 v[108:111], v[144:147], v[176:179], v[108:111]
	v_mfma_f32_16x16x32_bf16 v[104:107], v[152:155], v[176:179], v[104:107]
	v_mfma_f32_16x16x32_bf16 v[100:103], v[144:147], v[184:187], v[100:103]
	v_mfma_f32_16x16x32_bf16 v[96:99], v[152:155], v[184:187], v[96:99]
	v_mfma_f32_16x16x32_bf16 v[124:127], v[148:151], v[164:167], v[124:127]
	v_mfma_f32_16x16x32_bf16 v[120:123], v[156:159], v[164:167], v[120:123]
	v_mfma_f32_16x16x32_bf16 v[116:119], v[148:151], v[172:175], v[116:119]
	v_mfma_f32_16x16x32_bf16 v[112:115], v[156:159], v[172:175], v[112:115]
	v_mfma_f32_16x16x32_bf16 v[108:111], v[148:151], v[180:183], v[108:111]
	v_mfma_f32_16x16x32_bf16 v[104:107], v[156:159], v[180:183], v[104:107]
	v_mfma_f32_16x16x32_bf16 v[100:103], v[148:151], v[188:191], v[100:103]
	v_mfma_f32_16x16x32_bf16 v[96:99], v[156:159], v[188:191], v[96:99]
	s_setprio 0
	s_barrier
	v_lshl_add_u64 v[230:231], s[20:21], 0, v[130:131]
	s_mov_b64 s[92:93], 0xc00100
	s_mov_b32 m0, s44
	v_or_b32_e32 v138, 0x14000, v133
	v_add_u32_e32 v140, 0x14800, v133
	v_lshl_add_u64 v[220:221], v[230:231], 0, s[92:93]
	s_mov_b64 s[92:93], 0xc10100
	v_add_u32_e32 v139, 0x14400, v133
	ds_read_b128 v[204:207], v138
	ds_read_b128 v[208:211], v139
	v_add_u32_e32 v142, 0x14c00, v133
	ds_read_b128 v[212:215], v140
	ds_read_b128 v[216:219], v142
	global_load_lds_dwordx4 v[220:221], off
	v_lshl_add_u64 v[220:221], v[230:231], 0, s[92:93]
	s_mov_b32 m0, s45
	s_nop 0
	global_load_lds_dwordx4 v[220:221], off
	s_barrier
	s_waitcnt lgkmcnt(0)
	s_setprio 1
	s_waitcnt lgkmcnt(0)
	v_mfma_f32_16x16x32_bf16 v[92:95], v[204:207], v[160:163], v[92:95]
	v_mfma_f32_16x16x32_bf16 v[88:91], v[212:215], v[160:163], v[88:91]
	v_mfma_f32_16x16x32_bf16 v[84:87], v[204:207], v[168:171], v[84:87]
	v_mfma_f32_16x16x32_bf16 v[80:83], v[212:215], v[168:171], v[80:83]
	v_mfma_f32_16x16x32_bf16 v[76:79], v[204:207], v[176:179], v[76:79]
	v_mfma_f32_16x16x32_bf16 v[72:75], v[212:215], v[176:179], v[72:75]
	v_mfma_f32_16x16x32_bf16 v[68:71], v[204:207], v[184:187], v[68:71]
	v_mfma_f32_16x16x32_bf16 v[64:67], v[212:215], v[184:187], v[64:67]
	v_mfma_f32_16x16x32_bf16 v[92:95], v[208:211], v[164:167], v[92:95]
	v_mfma_f32_16x16x32_bf16 v[88:91], v[216:219], v[164:167], v[88:91]
	v_mfma_f32_16x16x32_bf16 v[84:87], v[208:211], v[172:175], v[84:87]
	v_mfma_f32_16x16x32_bf16 v[80:83], v[216:219], v[172:175], v[80:83]
	v_mfma_f32_16x16x32_bf16 v[76:79], v[208:211], v[180:183], v[76:79]
	v_mfma_f32_16x16x32_bf16 v[72:75], v[216:219], v[180:183], v[72:75]
	v_mfma_f32_16x16x32_bf16 v[68:71], v[208:211], v[188:191], v[68:71]
	v_mfma_f32_16x16x32_bf16 v[64:67], v[216:219], v[188:191], v[64:67]
	s_setprio 0
	s_mov_b32 m0, s43
	v_lshl_add_u64 v[220:221], v[228:229], 0, s[2:3]
	s_mov_b64 s[92:93], 0x19c90100
	s_barrier
	ds_read_b128 v[160:163], v132 offset:16384
	ds_read_b128 v[164:167], v132 offset:17408
	ds_read_b128 v[168:171], v132 offset:18432
	ds_read_b128 v[172:175], v132 offset:19456
	ds_read_b128 v[176:179], v132 offset:20480
	ds_read_b128 v[180:183], v132 offset:21504
	ds_read_b128 v[184:187], v132 offset:22528
	ds_read_b128 v[188:191], v132 offset:23552
	global_load_lds_dwordx4 v[220:221], off
	v_lshl_add_u64 v[220:221], v[228:229], 0, s[92:93]
	s_mov_b32 m0, s48
	s_nop 0
	global_load_lds_dwordx4 v[220:221], off
	s_barrier
	s_waitcnt lgkmcnt(0)
	s_setprio 1
	s_waitcnt lgkmcnt(0)
	v_mfma_f32_16x16x32_bf16 v[60:63], v[144:147], v[160:163], v[60:63]
	v_mfma_f32_16x16x32_bf16 v[56:59], v[152:155], v[160:163], v[56:59]
	v_mfma_f32_16x16x32_bf16 v[52:55], v[144:147], v[168:171], v[52:55]
	v_mfma_f32_16x16x32_bf16 v[48:51], v[152:155], v[168:171], v[48:51]
	v_mfma_f32_16x16x32_bf16 v[44:47], v[144:147], v[176:179], v[44:47]
	v_mfma_f32_16x16x32_bf16 v[40:43], v[152:155], v[176:179], v[40:43]
	v_mfma_f32_16x16x32_bf16 v[36:39], v[144:147], v[184:187], v[36:39]
	v_mfma_f32_16x16x32_bf16 v[32:35], v[152:155], v[184:187], v[32:35]
	v_mfma_f32_16x16x32_bf16 v[60:63], v[148:151], v[164:167], v[60:63]
	v_mfma_f32_16x16x32_bf16 v[56:59], v[156:159], v[164:167], v[56:59]
	v_mfma_f32_16x16x32_bf16 v[52:55], v[148:151], v[172:175], v[52:55]
	v_mfma_f32_16x16x32_bf16 v[48:51], v[156:159], v[172:175], v[48:51]
	v_mfma_f32_16x16x32_bf16 v[44:47], v[148:151], v[180:183], v[44:47]
	v_mfma_f32_16x16x32_bf16 v[40:43], v[156:159], v[180:183], v[40:43]
	v_mfma_f32_16x16x32_bf16 v[36:39], v[148:151], v[188:191], v[36:39]
	v_mfma_f32_16x16x32_bf16 v[32:35], v[156:159], v[188:191], v[32:35]
	s_setprio 0
	s_barrier
; #define LDA8(dst, b, h)                                                                                               \
;   _Pragma("unroll") for (int m = 0; m < 4; ++m) _Pragma("unroll") for (int k = 0; k < 2; ++k)                         \
;     dst[m][k] = *(const bf16x8*)(SA8(b, h) + la + m * 2048 + k * 1024)
; #define LDB8(dst, b, h)                                                                                               \
;   _Pragma("unroll") for (int n = 0; n < 2; ++n) _Pragma("unroll") for (int k = 0; k < 2; ++k)                         \
;     dst[n][k] = *(const bf16x8*)(SB8(b, h) + lb + n * 2048 + k * 1024)
; #define WAITV8(n) asm volatile("s_waitcnt vmcnt(" #n ")" ::: "memory")
; #define WAITL8(n) asm volatile("s_waitcnt lgkmcnt(" #n ")" ::: "memory")
; #define BAR8 __builtin_amdgcn_s_barrier()
; #define SCHED8 __builtin_amdgcn_sched_barrier(0)
; template <class Epi>
; DEV void gemm_tile8(char* shm, const u16* __restrict__ A, const u16* __restrict__ Bt, int K, int brow, int bcol, Epi& epi) {
;     ...
;     STAGE8(SB8(0, 1), Bt, bcol + HALF, t + 2);
;     WAITV8(6); BAR8; MMA8(1, 1, At, B1); BAR8;
;     LDB8(B0, 1, 0); SCHED8; LDA8(At, 1, 0); STAGE8(SA8(0, 1), A, brow + HALF, t + 2);
;     WAITL8(8); BAR8; WAITL8(0); MMA8(0, 0, At, B0); BAR8; SCHED8;
;     LDB8(B1, 1, 1); STAGE8(SB8(1, 0), Bt, bcol, t + 3);
;     BAR8; WAITL8(0); MMA8(0, 1, At, B1); BAR8;
	s_mov_b64 s[92:93], 0xc20100
	s_mov_b32 m0, s54
	v_lshl_add_u64 v[144:145], v[230:231], 0, s[92:93]
	s_mov_b64 s[92:93], 0xc30100
	global_load_lds_dwordx4 v[144:145], off
	v_lshl_add_u64 v[144:145], v[230:231], 0, s[92:93]
	s_mov_b32 m0, s55
	s_nop 0
	global_load_lds_dwordx4 v[144:145], off
	s_waitcnt vmcnt(6)
	s_barrier
	s_setprio 1
	v_mfma_f32_16x16x32_bf16 v[28:31], v[204:207], v[160:163], v[28:31]
	v_mfma_f32_16x16x32_bf16 v[24:27], v[212:215], v[160:163], v[24:27]
	v_mfma_f32_16x16x32_bf16 v[20:23], v[204:207], v[168:171], v[20:23]
	v_mfma_f32_16x16x32_bf16 v[16:19], v[212:215], v[168:171], v[16:19]
	v_mfma_f32_16x16x32_bf16 v[12:15], v[204:207], v[176:179], v[12:15]
	v_mfma_f32_16x16x32_bf16 v[8:11], v[212:215], v[176:179], v[8:11]
	v_mfma_f32_16x16x32_bf16 v[4:7], v[204:207], v[184:187], v[4:7]
	v_mfma_f32_16x16x32_bf16 v[0:3], v[212:215], v[184:187], v[0:3]
	v_mfma_f32_16x16x32_bf16 v[28:31], v[208:211], v[164:167], v[28:31]
	v_mfma_f32_16x16x32_bf16 v[24:27], v[216:219], v[164:167], v[24:27]
	v_mfma_f32_16x16x32_bf16 v[20:23], v[208:211], v[172:175], v[20:23]
	v_mfma_f32_16x16x32_bf16 v[16:19], v[216:219], v[172:175], v[16:19]
	v_mfma_f32_16x16x32_bf16 v[12:15], v[208:211], v[180:183], v[12:15]
	v_mfma_f32_16x16x32_bf16 v[8:11], v[216:219], v[180:183], v[8:11]
	v_mfma_f32_16x16x32_bf16 v[4:7], v[208:211], v[188:191], v[4:7]
	v_mfma_f32_16x16x32_bf16 v[0:3], v[216:219], v[188:191], v[0:3]
	s_setprio 0
	v_or_b32_e32 v143, 0x18000, v133
	v_add_u32_e32 v145, 0x18800, v133
	s_barrier
	v_add_u32_e32 v144, 0x18400, v133
	ds_read_b128 v[152:155], v143
	ds_read_b128 v[156:159], v144
	v_add_u32_e32 v146, 0x18c00, v133
	ds_read_b128 v[160:163], v145
	ds_read_b128 v[164:167], v146
	s_mov_b32 m0, s70
	v_lshl_add_u64 v[148:149], v[228:229], 0, s[74:75]
	s_mov_b64 s[92:93], 0x19cb0100
	ds_read_b128 v[168:171], v132 offset:32768
	ds_read_b128 v[172:175], v132 offset:33792
	ds_read_b128 v[176:179], v132 offset:34816
	ds_read_b128 v[180:183], v132 offset:35840
	ds_read_b128 v[184:187], v132 offset:36864
	ds_read_b128 v[188:191], v132 offset:37888
	ds_read_b128 v[204:207], v132 offset:38912
	ds_read_b128 v[208:211], v132 offset:39936
	global_load_lds_dwordx4 v[148:149], off
	v_lshl_add_u64 v[148:149], v[228:229], 0, s[92:93]
	s_mov_b32 m0, s71
	s_nop 0
	global_load_lds_dwordx4 v[148:149], off
	s_waitcnt lgkmcnt(8)
	s_barrier
	s_waitcnt lgkmcnt(0)
	s_setprio 1
	s_waitcnt lgkmcnt(0)
	v_mfma_f32_16x16x32_bf16 v[124:127], v[152:155], v[168:171], v[124:127]
	v_mfma_f32_16x16x32_bf16 v[120:123], v[160:163], v[168:171], v[120:123]
	v_mfma_f32_16x16x32_bf16 v[116:119], v[152:155], v[176:179], v[116:119]
	v_mfma_f32_16x16x32_bf16 v[112:115], v[160:163], v[176:179], v[112:115]
	v_mfma_f32_16x16x32_bf16 v[108:111], v[152:155], v[184:187], v[108:111]
	v_mfma_f32_16x16x32_bf16 v[104:107], v[160:163], v[184:187], v[104:107]
	v_mfma_f32_16x16x32_bf16 v[100:103], v[152:155], v[204:207], v[100:103]
	v_mfma_f32_16x16x32_bf16 v[96:99], v[160:163], v[204:207], v[96:99]
	v_mfma_f32_16x16x32_bf16 v[124:127], v[156:159], v[172:175], v[124:127]
	v_mfma_f32_16x16x32_bf16 v[120:123], v[164:167], v[172:175], v[120:123]
	v_mfma_f32_16x16x32_bf16 v[116:119], v[156:159], v[180:183], v[116:119]
	v_mfma_f32_16x16x32_bf16 v[112:115], v[164:167], v[180:183], v[112:115]
	v_mfma_f32_16x16x32_bf16 v[108:111], v[156:159], v[188:191], v[108:111]
	v_mfma_f32_16x16x32_bf16 v[104:107], v[164:167], v[188:191], v[104:107]
	v_mfma_f32_16x16x32_bf16 v[100:103], v[156:159], v[208:211], v[100:103]
	v_mfma_f32_16x16x32_bf16 v[96:99], v[164:167], v[208:211], v[96:99]
	s_setprio 0
	s_barrier
	s_mov_b64 s[92:93], 0xc00180
	s_mov_b32 m0, s72
	v_or_b32_e32 v147, 0x1c000, v133
	v_add_u32_e32 v149, 0x1c800, v133
	v_lshl_add_u64 v[232:233], v[230:231], 0, s[92:93]
	s_mov_b64 s[92:93], 0xc10180
	v_add_u32_e32 v148, 0x1c400, v133
	ds_read_b128 v[212:215], v147
	ds_read_b128 v[216:219], v148
	v_add_u32_e32 v150, 0x1cc00, v133
	ds_read_b128 v[220:223], v149
	ds_read_b128 v[224:227], v150
	global_load_lds_dwordx4 v[232:233], off
	v_lshl_add_u64 v[232:233], v[230:231], 0, s[92:93]
	s_mov_b32 m0, s73
	s_nop 0
	global_load_lds_dwordx4 v[232:233], off
	s_barrier
	s_waitcnt lgkmcnt(0)
	s_setprio 1
	s_waitcnt lgkmcnt(0)
	v_mfma_f32_16x16x32_bf16 v[92:95], v[212:215], v[168:171], v[92:95]
	v_mfma_f32_16x16x32_bf16 v[88:91], v[220:223], v[168:171], v[88:91]
	v_mfma_f32_16x16x32_bf16 v[84:87], v[212:215], v[176:179], v[84:87]
	v_mfma_f32_16x16x32_bf16 v[80:83], v[220:223], v[176:179], v[80:83]
	v_mfma_f32_16x16x32_bf16 v[76:79], v[212:215], v[184:187], v[76:79]
	v_mfma_f32_16x16x32_bf16 v[72:75], v[220:223], v[184:187], v[72:75]
	v_mfma_f32_16x16x32_bf16 v[68:71], v[212:215], v[204:207], v[68:71]
	v_mfma_f32_16x16x32_bf16 v[64:67], v[220:223], v[204:207], v[64:67]
	v_mfma_f32_16x16x32_bf16 v[92:95], v[216:219], v[172:175], v[92:95]
	v_mfma_f32_16x16x32_bf16 v[88:91], v[224:227], v[172:175], v[88:91]
	v_mfma_f32_16x16x32_bf16 v[84:87], v[216:219], v[180:183], v[84:87]
	v_mfma_f32_16x16x32_bf16 v[80:83], v[224:227], v[180:183], v[80:83]
	v_mfma_f32_16x16x32_bf16 v[76:79], v[216:219], v[188:191], v[76:79]
	v_mfma_f32_16x16x32_bf16 v[72:75], v[224:227], v[188:191], v[72:75]
	v_mfma_f32_16x16x32_bf16 v[68:71], v[216:219], v[208:211], v[68:71]
	v_mfma_f32_16x16x32_bf16 v[64:67], v[224:227], v[208:211], v[64:67]
	s_setprio 0
	s_mov_b32 m0, s81
	v_lshl_add_u64 v[232:233], v[228:229], 0, s[64:65]
	s_mov_b64 s[92:93], 0x19c90180
	s_barrier
; #define LDA8(dst, b, h)                                                                                               \
;   _Pragma("unroll") for (int m = 0; m < 4; ++m) _Pragma("unroll") for (int k = 0; k < 2; ++k)                         \
;     dst[m][k] = *(const bf16x8*)(SA8(b, h) + la + m * 2048 + k * 1024)
; #define LDB8(dst, b, h)                                                                                               \
;   _Pragma("unroll") for (int n = 0; n < 2; ++n) _Pragma("unroll") for (int k = 0; k < 2; ++k)                         \
;     dst[n][k] = *(const bf16x8*)(SB8(b, h) + lb + n * 2048 + k * 1024)
; #define WAITV8(n) asm volatile("s_waitcnt vmcnt(" #n ")" ::: "memory")
; #define WAITL8(n) asm volatile("s_waitcnt lgkmcnt(" #n ")" ::: "memory")
; #define BAR8 __builtin_amdgcn_s_barrier()
; #define SCHED8 __builtin_amdgcn_sched_barrier(0)
; template <class Epi>
; DEV void gemm_tile8(char* shm, const u16* __restrict__ A, const u16* __restrict__ Bt, int K, int brow, int bcol, Epi& epi) {
;     ...
;     LDA8(At, 1, 1); STAGE8(SA8(1, 0), A, brow, t + 3);
;     BAR8; WAITL8(0); MMA8(1, 0, At, B0); BAR8; SCHED8;
;     STAGE8(SB8(1, 1), Bt, bcol + HALF, t + 3);
;     WAITV8(6); BAR8; MMA8(1, 1, At, B1); BAR8;
;   }
;   { LDB8(B0, 0, 0); LDA8(At, 0, 0); STAGE8(SA8(1, 1), A, brow + HALF, nt - 1);
;     BAR8; WAITL8(0); MMA8(0, 0, At, B0); BAR8;
;     LDB8(B1, 0, 1); BAR8; WAITL8(0); MMA8(0, 1, At, B1); BAR8;
	ds_read_b128 v[168:171], v132 offset:49152
	ds_read_b128 v[172:175], v132 offset:50176
	ds_read_b128 v[176:179], v132 offset:51200
	ds_read_b128 v[180:183], v132 offset:52224
	ds_read_b128 v[184:187], v132 offset:53248
	ds_read_b128 v[188:191], v132 offset:54272
	ds_read_b128 v[204:207], v132 offset:55296
	ds_read_b128 v[208:211], v132 offset:56320
	global_load_lds_dwordx4 v[232:233], off
	v_lshl_add_u64 v[228:229], v[228:229], 0, s[92:93]
	s_mov_b32 m0, s84
	s_nop 0
	global_load_lds_dwordx4 v[228:229], off
	s_barrier
	s_waitcnt lgkmcnt(0)
	s_setprio 1
	s_waitcnt lgkmcnt(0)
	v_mfma_f32_16x16x32_bf16 v[60:63], v[152:155], v[168:171], v[60:63]
	v_mfma_f32_16x16x32_bf16 v[56:59], v[160:163], v[168:171], v[56:59]
	v_mfma_f32_16x16x32_bf16 v[52:55], v[152:155], v[176:179], v[52:55]
	v_mfma_f32_16x16x32_bf16 v[48:51], v[160:163], v[176:179], v[48:51]
	v_mfma_f32_16x16x32_bf16 v[44:47], v[152:155], v[184:187], v[44:47]
	v_mfma_f32_16x16x32_bf16 v[40:43], v[160:163], v[184:187], v[40:43]
	v_mfma_f32_16x16x32_bf16 v[36:39], v[152:155], v[204:207], v[36:39]
	v_mfma_f32_16x16x32_bf16 v[32:35], v[160:163], v[204:207], v[32:35]
	v_mfma_f32_16x16x32_bf16 v[60:63], v[156:159], v[172:175], v[60:63]
	v_mfma_f32_16x16x32_bf16 v[56:59], v[164:167], v[172:175], v[56:59]
	v_mfma_f32_16x16x32_bf16 v[52:55], v[156:159], v[180:183], v[52:55]
	v_mfma_f32_16x16x32_bf16 v[48:51], v[164:167], v[180:183], v[48:51]
	v_mfma_f32_16x16x32_bf16 v[44:47], v[156:159], v[188:191], v[44:47]
	v_mfma_f32_16x16x32_bf16 v[40:43], v[164:167], v[188:191], v[40:43]
	v_mfma_f32_16x16x32_bf16 v[36:39], v[156:159], v[208:211], v[36:39]
	v_mfma_f32_16x16x32_bf16 v[32:35], v[164:167], v[208:211], v[32:35]
	s_setprio 0
	s_barrier
	s_mov_b64 s[92:93], 0xc20180
	s_mov_b32 m0, s85
	v_lshl_add_u64 v[152:153], v[230:231], 0, s[92:93]
	s_mov_b64 s[92:93], 0xc30180
	global_load_lds_dwordx4 v[152:153], off
	v_lshl_add_u64 v[152:153], v[230:231], 0, s[92:93]
	s_mov_b32 m0, s90
	s_nop 0
	global_load_lds_dwordx4 v[152:153], off
	s_waitcnt vmcnt(6)
	s_barrier
	s_setprio 1
	v_mfma_f32_16x16x32_bf16 v[28:31], v[212:215], v[168:171], v[28:31]
	v_mfma_f32_16x16x32_bf16 v[24:27], v[220:223], v[168:171], v[24:27]
	v_mfma_f32_16x16x32_bf16 v[20:23], v[212:215], v[176:179], v[20:23]
	v_mfma_f32_16x16x32_bf16 v[16:19], v[220:223], v[176:179], v[16:19]
	v_mfma_f32_16x16x32_bf16 v[12:15], v[212:215], v[184:187], v[12:15]
	v_mfma_f32_16x16x32_bf16 v[8:11], v[220:223], v[184:187], v[8:11]
	v_mfma_f32_16x16x32_bf16 v[4:7], v[212:215], v[204:207], v[4:7]
	v_mfma_f32_16x16x32_bf16 v[0:3], v[220:223], v[204:207], v[0:3]
	v_mfma_f32_16x16x32_bf16 v[28:31], v[216:219], v[172:175], v[28:31]
	v_mfma_f32_16x16x32_bf16 v[24:27], v[224:227], v[172:175], v[24:27]
	v_mfma_f32_16x16x32_bf16 v[20:23], v[216:219], v[180:183], v[20:23]
	v_mfma_f32_16x16x32_bf16 v[16:19], v[224:227], v[180:183], v[16:19]
	v_mfma_f32_16x16x32_bf16 v[12:15], v[216:219], v[188:191], v[12:15]
	v_mfma_f32_16x16x32_bf16 v[8:11], v[224:227], v[188:191], v[8:11]
	v_mfma_f32_16x16x32_bf16 v[4:7], v[216:219], v[208:211], v[4:7]
	v_mfma_f32_16x16x32_bf16 v[0:3], v[224:227], v[208:211], v[0:3]
	s_setprio 0
	s_add_i32 s22, s22, 2
	s_add_u32 s18, s18, 0x100
	s_addc_u32 s19, s19, 0
	s_add_u32 s20, s20, 0x100
	s_addc_u32 s21, s21, 0
	s_cmp_lt_u32 s22, 4
	s_barrier
	s_cbranch_scc1 .LBB0_563
	s_mov_b64 s[18:19], 0x380
	s_mov_b32 m0, s91
	v_lshl_add_u64 v[130:131], v[128:129], 0, s[18:19]
	s_mov_b64 s[18:19], 0x10380
	ds_read_b128 v[152:155], v134
	ds_read_b128 v[156:159], v135
	ds_read_b128 v[160:163], v136
	ds_read_b128 v[134:137], v137
	ds_read_b128 v[164:167], v132
	ds_read_b128 v[168:171], v132 offset:1024
	ds_read_b128 v[172:175], v132 offset:2048
	ds_read_b128 v[176:179], v132 offset:3072
	ds_read_b128 v[180:183], v132 offset:4096
	ds_read_b128 v[184:187], v132 offset:5120
	ds_read_b128 v[188:191], v132 offset:6144
	ds_read_b128 v[204:207], v132 offset:7168
	global_load_lds_dwordx4 v[130:131], off
	v_lshl_add_u64 v[128:129], v[128:129], 0, s[18:19]
	s_mov_b32 m0, s23
	s_nop 0
	global_load_lds_dwordx4 v[128:129], off
	s_barrier
	s_waitcnt lgkmcnt(0)
	s_setprio 1
	s_waitcnt lgkmcnt(0)
	v_mfma_f32_16x16x32_bf16 v[124:127], v[152:155], v[164:167], v[124:127]
	v_mfma_f32_16x16x32_bf16 v[120:123], v[160:163], v[164:167], v[120:123]
	v_mfma_f32_16x16x32_bf16 v[116:119], v[152:155], v[172:175], v[116:119]
	v_mfma_f32_16x16x32_bf16 v[112:115], v[160:163], v[172:175], v[112:115]
	v_mfma_f32_16x16x32_bf16 v[108:111], v[152:155], v[180:183], v[108:111]
	v_mfma_f32_16x16x32_bf16 v[104:107], v[160:163], v[180:183], v[104:107]
	v_mfma_f32_16x16x32_bf16 v[100:103], v[152:155], v[188:191], v[100:103]
	v_mfma_f32_16x16x32_bf16 v[96:99], v[160:163], v[188:191], v[96:99]
	v_mfma_f32_16x16x32_bf16 v[124:127], v[156:159], v[168:171], v[124:127]
	v_mfma_f32_16x16x32_bf16 v[120:123], v[134:137], v[168:171], v[120:123]
	v_mfma_f32_16x16x32_bf16 v[116:119], v[156:159], v[176:179], v[116:119]
	v_mfma_f32_16x16x32_bf16 v[112:115], v[134:137], v[176:179], v[112:115]
	v_mfma_f32_16x16x32_bf16 v[108:111], v[156:159], v[184:187], v[108:111]
	v_mfma_f32_16x16x32_bf16 v[104:107], v[134:137], v[184:187], v[104:107]
	v_mfma_f32_16x16x32_bf16 v[100:103], v[156:159], v[204:207], v[100:103]
	v_mfma_f32_16x16x32_bf16 v[96:99], v[134:137], v[204:207], v[96:99]
	s_setprio 0
	s_barrier
	ds_read_b128 v[128:131], v138
	ds_read_b128 v[208:211], v139
	ds_read_b128 v[212:215], v140
	ds_read_b128 v[216:219], v142
	s_barrier
; #define LDA8(dst, b, h)                                                                                               \
;   _Pragma("unroll") for (int m = 0; m < 4; ++m) _Pragma("unroll") for (int k = 0; k < 2; ++k)                         \
;     dst[m][k] = *(const bf16x8*)(SA8(b, h) + la + m * 2048 + k * 1024)
; #define LDB8(dst, b, h)                                                                                               \
;   _Pragma("unroll") for (int n = 0; n < 2; ++n) _Pragma("unroll") for (int k = 0; k < 2; ++k)                         \
;     dst[n][k] = *(const bf16x8*)(SB8(b, h) + lb + n * 2048 + k * 1024)
; #define WAITV8(n) asm volatile("s_waitcnt vmcnt(" #n ")" ::: "memory")
; #define WAITL8(n) asm volatile("s_waitcnt lgkmcnt(" #n ")" ::: "memory")
; #define BAR8 __builtin_amdgcn_s_barrier()
; template <class Epi>
; DEV void gemm_tile8(char* shm, const u16* __restrict__ A, const u16* __restrict__ Bt, int K, int brow, int bcol, Epi& epi) {
;     ...
;     LDB8(B1, 0, 1); BAR8; WAITL8(0); MMA8(0, 1, At, B1); BAR8;
;     LDA8(At, 0, 1); WAITV8(4); BAR8; WAITL8(0); MMA8(1, 0, At, B0); MMA8(1, 1, At, B1); BAR8; }
;   { LDB8(B0, 1, 0); LDA8(At, 1, 0); WAITV8(2); BAR8; WAITL8(0); MMA8(0, 0, At, B0); BAR8;
	s_waitcnt lgkmcnt(0)
	s_setprio 1
	s_waitcnt lgkmcnt(3)
	v_mfma_f32_16x16x32_bf16 v[92:95], v[128:131], v[164:167], v[92:95]
	s_waitcnt lgkmcnt(1)
	v_mfma_f32_16x16x32_bf16 v[88:91], v[212:215], v[164:167], v[88:91]
	v_mfma_f32_16x16x32_bf16 v[84:87], v[128:131], v[172:175], v[84:87]
	v_mfma_f32_16x16x32_bf16 v[80:83], v[212:215], v[172:175], v[80:83]
	v_mfma_f32_16x16x32_bf16 v[76:79], v[128:131], v[180:183], v[76:79]
	v_mfma_f32_16x16x32_bf16 v[72:75], v[212:215], v[180:183], v[72:75]
	v_mfma_f32_16x16x32_bf16 v[68:71], v[128:131], v[188:191], v[68:71]
	v_mfma_f32_16x16x32_bf16 v[64:67], v[212:215], v[188:191], v[64:67]
	v_mfma_f32_16x16x32_bf16 v[220:223], v[208:211], v[168:171], v[92:95]
	s_waitcnt lgkmcnt(0)
	v_mfma_f32_16x16x32_bf16 v[164:167], v[216:219], v[168:171], v[88:91]
	v_mfma_f32_16x16x32_bf16 v[168:171], v[208:211], v[176:179], v[84:87]
	v_mfma_f32_16x16x32_bf16 v[172:175], v[216:219], v[176:179], v[80:83]
	v_mfma_f32_16x16x32_bf16 v[176:179], v[208:211], v[184:187], v[76:79]
	v_mfma_f32_16x16x32_bf16 v[180:183], v[216:219], v[184:187], v[72:75]
	v_mfma_f32_16x16x32_bf16 v[184:187], v[208:211], v[204:207], v[68:71]
	v_mfma_f32_16x16x32_bf16 v[188:191], v[216:219], v[204:207], v[64:67]
	s_setprio 0
	s_barrier
	s_nop 0
	ds_read_b128 v[64:67], v132 offset:16384
	ds_read_b128 v[68:71], v132 offset:17408
	ds_read_b128 v[72:75], v132 offset:18432
	ds_read_b128 v[76:79], v132 offset:19456
	ds_read_b128 v[80:83], v132 offset:20480
	ds_read_b128 v[84:87], v132 offset:21504
	ds_read_b128 v[88:91], v132 offset:22528
	ds_read_b128 v[92:95], v132 offset:23552
	s_waitcnt vmcnt(4)
	s_barrier
	s_waitcnt lgkmcnt(0)
	s_setprio 1
	s_waitcnt lgkmcnt(7)
	v_mfma_f32_16x16x32_bf16 v[60:63], v[152:155], v[64:67], v[60:63]
	v_mfma_f32_16x16x32_bf16 v[56:59], v[160:163], v[64:67], v[56:59]
	s_waitcnt lgkmcnt(5)
	v_mfma_f32_16x16x32_bf16 v[52:55], v[152:155], v[72:75], v[52:55]
	v_mfma_f32_16x16x32_bf16 v[48:51], v[160:163], v[72:75], v[48:51]
	s_waitcnt lgkmcnt(3)
	v_mfma_f32_16x16x32_bf16 v[44:47], v[152:155], v[80:83], v[44:47]
	v_mfma_f32_16x16x32_bf16 v[40:43], v[160:163], v[80:83], v[40:43]
	s_waitcnt lgkmcnt(1)
	v_mfma_f32_16x16x32_bf16 v[36:39], v[152:155], v[88:91], v[36:39]
	v_mfma_f32_16x16x32_bf16 v[32:35], v[160:163], v[88:91], v[32:35]
	v_mfma_f32_16x16x32_bf16 v[60:63], v[156:159], v[68:71], v[60:63]
	v_mfma_f32_16x16x32_bf16 v[56:59], v[134:137], v[68:71], v[56:59]
	v_mfma_f32_16x16x32_bf16 v[52:55], v[156:159], v[76:79], v[52:55]
	v_mfma_f32_16x16x32_bf16 v[48:51], v[134:137], v[76:79], v[48:51]
	v_mfma_f32_16x16x32_bf16 v[44:47], v[156:159], v[84:87], v[44:47]
	v_mfma_f32_16x16x32_bf16 v[40:43], v[134:137], v[84:87], v[40:43]
	s_waitcnt lgkmcnt(0)
	v_mfma_f32_16x16x32_bf16 v[36:39], v[156:159], v[92:95], v[36:39]
	v_mfma_f32_16x16x32_bf16 v[32:35], v[134:137], v[92:95], v[32:35]
	s_setprio 0
	s_setprio 1
	v_mfma_f32_16x16x32_bf16 v[28:31], v[128:131], v[64:67], v[28:31]
	v_mfma_f32_16x16x32_bf16 v[24:27], v[212:215], v[64:67], v[24:27]
	v_mfma_f32_16x16x32_bf16 v[20:23], v[128:131], v[72:75], v[20:23]
	v_mfma_f32_16x16x32_bf16 v[16:19], v[212:215], v[72:75], v[16:19]
	v_mfma_f32_16x16x32_bf16 v[12:15], v[128:131], v[80:83], v[12:15]
	v_mfma_f32_16x16x32_bf16 v[8:11], v[212:215], v[80:83], v[8:11]
	v_mfma_f32_16x16x32_bf16 v[4:7], v[128:131], v[88:91], v[4:7]
	v_mfma_f32_16x16x32_bf16 v[0:3], v[212:215], v[88:91], v[0:3]
	v_mfma_f32_16x16x32_bf16 v[134:137], v[208:211], v[68:71], v[28:31]
	v_mfma_f32_16x16x32_bf16 v[152:155], v[216:219], v[68:71], v[24:27]
	v_mfma_f32_16x16x32_bf16 v[156:159], v[208:211], v[76:79], v[20:23]
	v_mfma_f32_16x16x32_bf16 v[160:163], v[216:219], v[76:79], v[16:19]
	v_mfma_f32_16x16x32_bf16 v[204:207], v[208:211], v[84:87], v[12:15]
	v_mfma_f32_16x16x32_bf16 v[224:227], v[216:219], v[84:87], v[8:11]
	v_mfma_f32_16x16x32_bf16 v[128:131], v[208:211], v[92:95], v[4:7]
	v_mfma_f32_16x16x32_bf16 v[208:211], v[216:219], v[92:95], v[0:3]
	s_setprio 0
	s_barrier
	ds_read_b128 v[24:27], v143
	ds_read_b128 v[28:31], v144
	ds_read_b128 v[142:145], v145
	ds_read_b128 v[212:215], v146
	ds_read_b128 v[0:3], v132 offset:32768
	ds_read_b128 v[4:7], v132 offset:33792
	ds_read_b128 v[8:11], v132 offset:34816
	ds_read_b128 v[12:15], v132 offset:35840
	ds_read_b128 v[16:19], v132 offset:36864
	ds_read_b128 v[20:23], v132 offset:37888
	ds_read_b128 v[216:219], v132 offset:38912
	ds_read_b128 v[228:231], v132 offset:39936
	s_waitcnt vmcnt(2)
	s_barrier
; #define LDA8(dst, b, h)                                                                                               \
;   _Pragma("unroll") for (int m = 0; m < 4; ++m) _Pragma("unroll") for (int k = 0; k < 2; ++k)                         \
;     dst[m][k] = *(const bf16x8*)(SA8(b, h) + la + m * 2048 + k * 1024)
; #define LDB8(dst, b, h)                                                                                               \
;   _Pragma("unroll") for (int n = 0; n < 2; ++n) _Pragma("unroll") for (int k = 0; k < 2; ++k)                         \
;     dst[n][k] = *(const bf16x8*)(SB8(b, h) + lb + n * 2048 + k * 1024)
; #define WAITV8(n) asm volatile("s_waitcnt vmcnt(" #n ")" ::: "memory")
; #define WAITL8(n) asm volatile("s_waitcnt lgkmcnt(" #n ")" ::: "memory")
; #define BAR8 __builtin_amdgcn_s_barrier()
; template <class Epi>
; DEV void gemm_tile8(char* shm, const u16* __restrict__ A, const u16* __restrict__ Bt, int K, int brow, int bcol, Epi& epi) {
;     ...
;   { LDB8(B0, 1, 0); LDA8(At, 1, 0); WAITV8(2); BAR8; WAITL8(0); MMA8(0, 0, At, B0); BAR8;
;     LDB8(B1, 1, 1); WAITV8(0); BAR8; WAITL8(0); MMA8(0, 1, At, B1); BAR8;
;     LDA8(At, 1, 1); BAR8; WAITL8(0); MMA8(1, 0, At, B0); MMA8(1, 1, At, B1); BAR8; }
;   if (wrs == 0) BAR8;
	s_waitcnt lgkmcnt(0)
	s_setprio 1
	s_waitcnt lgkmcnt(7)
	v_mfma_f32_16x16x32_bf16 v[64:67], v[24:27], v[0:3], v[124:127]
	s_waitcnt lgkmcnt(6)
	v_mfma_f32_16x16x32_bf16 v[72:75], v[28:31], v[4:7], v[64:67]
	v_mfma_f32_16x16x32_bf16 v[64:67], v[142:145], v[0:3], v[120:123]
	s_waitcnt lgkmcnt(5)
	v_mfma_f32_16x16x32_bf16 v[68:71], v[24:27], v[8:11], v[116:119]
	v_mfma_f32_16x16x32_bf16 v[76:79], v[142:145], v[8:11], v[112:115]
	s_waitcnt lgkmcnt(3)
	v_mfma_f32_16x16x32_bf16 v[80:83], v[24:27], v[16:19], v[108:111]
	v_mfma_f32_16x16x32_bf16 v[84:87], v[142:145], v[16:19], v[104:107]
	s_waitcnt lgkmcnt(1)
	v_mfma_f32_16x16x32_bf16 v[88:91], v[24:27], v[216:219], v[100:103]
	v_mfma_f32_16x16x32_bf16 v[92:95], v[142:145], v[216:219], v[96:99]
	v_mfma_f32_16x16x32_bf16 v[64:67], v[212:215], v[4:7], v[64:67]
	v_mfma_f32_16x16x32_bf16 v[68:71], v[28:31], v[12:15], v[68:71]
	v_mfma_f32_16x16x32_bf16 v[76:79], v[212:215], v[12:15], v[76:79]
	v_mfma_f32_16x16x32_bf16 v[80:83], v[28:31], v[20:23], v[80:83]
	v_mfma_f32_16x16x32_bf16 v[84:87], v[212:215], v[20:23], v[84:87]
	s_waitcnt lgkmcnt(0)
	v_mfma_f32_16x16x32_bf16 v[88:91], v[28:31], v[228:231], v[88:91]
	v_mfma_f32_16x16x32_bf16 v[92:95], v[212:215], v[228:231], v[92:95]
	s_setprio 0
	s_barrier
	ds_read_b128 v[232:235], v147
	ds_read_b128 v[236:239], v148
	ds_read_b128 v[146:149], v149
	ds_read_b128 v[240:243], v150
	s_waitcnt vmcnt(0)
	s_barrier
	s_waitcnt lgkmcnt(0)
	s_setprio 1
	s_waitcnt lgkmcnt(3)
	v_mfma_f32_16x16x32_bf16 v[96:99], v[232:235], v[0:3], v[220:223]
	s_waitcnt lgkmcnt(1)
	v_mfma_f32_16x16x32_bf16 v[0:3], v[146:149], v[0:3], v[164:167]
	v_mfma_f32_16x16x32_bf16 v[104:107], v[236:239], v[4:7], v[96:99]
	s_waitcnt lgkmcnt(0)
	v_mfma_f32_16x16x32_bf16 v[96:99], v[240:243], v[4:7], v[0:3]
	v_mfma_f32_16x16x32_bf16 v[0:3], v[232:235], v[8:11], v[168:171]
	v_mfma_f32_16x16x32_bf16 v[100:103], v[236:239], v[12:15], v[0:3]
	v_mfma_f32_16x16x32_bf16 v[0:3], v[146:149], v[8:11], v[172:175]
	v_mfma_f32_16x16x32_bf16 v[108:111], v[240:243], v[12:15], v[0:3]
	v_mfma_f32_16x16x32_bf16 v[0:3], v[232:235], v[16:19], v[176:179]
	v_mfma_f32_16x16x32_bf16 v[112:115], v[236:239], v[20:23], v[0:3]
	v_mfma_f32_16x16x32_bf16 v[0:3], v[146:149], v[16:19], v[180:183]
	v_mfma_f32_16x16x32_bf16 v[116:119], v[240:243], v[20:23], v[0:3]
	v_mfma_f32_16x16x32_bf16 v[0:3], v[232:235], v[216:219], v[184:187]
	v_mfma_f32_16x16x32_bf16 v[120:123], v[236:239], v[228:231], v[0:3]
	v_mfma_f32_16x16x32_bf16 v[0:3], v[146:149], v[216:219], v[188:191]
	v_mfma_f32_16x16x32_bf16 v[124:127], v[240:243], v[228:231], v[0:3]
	s_setprio 0
	s_barrier
	ds_read_b128 v[164:167], v132 offset:49152
	ds_read_b128 v[168:171], v132 offset:50176
	ds_read_b128 v[172:175], v132 offset:51200
	ds_read_b128 v[176:179], v132 offset:52224
	ds_read_b128 v[180:183], v132 offset:53248
	ds_read_b128 v[184:187], v132 offset:54272
	ds_read_b128 v[188:191], v132 offset:55296
	ds_read_b128 v[216:219], v132 offset:56320
	s_barrier
	s_waitcnt lgkmcnt(0)
	s_setprio 1
	s_waitcnt lgkmcnt(7)
	v_mfma_f32_16x16x32_bf16 v[0:3], v[24:27], v[164:167], v[60:63]
	s_waitcnt lgkmcnt(5)
	v_mfma_f32_16x16x32_bf16 v[8:11], v[24:27], v[172:175], v[52:55]
	s_waitcnt lgkmcnt(3)
	v_mfma_f32_16x16x32_bf16 v[16:19], v[24:27], v[180:183], v[44:47]
	s_waitcnt lgkmcnt(1)
	v_mfma_f32_16x16x32_bf16 v[24:27], v[24:27], v[188:191], v[36:39]
	v_mfma_f32_16x16x32_bf16 v[0:3], v[28:31], v[168:171], v[0:3]
	v_mfma_f32_16x16x32_bf16 v[4:7], v[142:145], v[164:167], v[56:59]
	v_mfma_f32_16x16x32_bf16 v[8:11], v[28:31], v[176:179], v[8:11]
	v_mfma_f32_16x16x32_bf16 v[12:15], v[142:145], v[172:175], v[48:51]
	v_mfma_f32_16x16x32_bf16 v[16:19], v[28:31], v[184:187], v[16:19]
	v_mfma_f32_16x16x32_bf16 v[20:23], v[142:145], v[180:183], v[40:43]
	s_waitcnt lgkmcnt(0)
	v_mfma_f32_16x16x32_bf16 v[24:27], v[28:31], v[216:219], v[24:27]
	v_mfma_f32_16x16x32_bf16 v[28:31], v[142:145], v[188:191], v[32:35]
	v_mfma_f32_16x16x32_bf16 v[4:7], v[212:215], v[168:171], v[4:7]
	v_mfma_f32_16x16x32_bf16 v[12:15], v[212:215], v[176:179], v[12:15]
	v_mfma_f32_16x16x32_bf16 v[20:23], v[212:215], v[184:187], v[20:23]
	v_mfma_f32_16x16x32_bf16 v[28:31], v[212:215], v[216:219], v[28:31]
	s_setprio 0
	s_setprio 1
	v_mfma_f32_16x16x32_bf16 v[32:35], v[232:235], v[164:167], v[134:137]
	v_mfma_f32_16x16x32_bf16 v[36:39], v[146:149], v[164:167], v[152:155]
	v_mfma_f32_16x16x32_bf16 v[40:43], v[232:235], v[172:175], v[156:159]
	v_mfma_f32_16x16x32_bf16 v[44:47], v[146:149], v[172:175], v[160:163]
	v_mfma_f32_16x16x32_bf16 v[48:51], v[232:235], v[180:183], v[204:207]
	v_mfma_f32_16x16x32_bf16 v[52:55], v[146:149], v[180:183], v[224:227]
	v_mfma_f32_16x16x32_bf16 v[56:59], v[232:235], v[188:191], v[128:131]
	v_mfma_f32_16x16x32_bf16 v[60:63], v[146:149], v[188:191], v[208:211]
	v_mfma_f32_16x16x32_bf16 v[32:35], v[236:239], v[168:171], v[32:35]
	v_mfma_f32_16x16x32_bf16 v[36:39], v[240:243], v[168:171], v[36:39]
	v_mfma_f32_16x16x32_bf16 v[40:43], v[236:239], v[176:179], v[40:43]
	v_mfma_f32_16x16x32_bf16 v[44:47], v[240:243], v[176:179], v[44:47]
	v_mfma_f32_16x16x32_bf16 v[48:51], v[236:239], v[184:187], v[48:51]
	v_mfma_f32_16x16x32_bf16 v[52:55], v[240:243], v[184:187], v[52:55]
	v_mfma_f32_16x16x32_bf16 v[56:59], v[236:239], v[216:219], v[56:59]
	v_mfma_f32_16x16x32_bf16 v[60:63], v[240:243], v[216:219], v[60:63]
	s_setprio 0
	s_cmp_lg_u32 s7, 0
	s_barrier
	s_cbranch_scc1 .LBB0_566
	s_barrier

; #define LDA8(dst, b, h)                                                                                               \
;   _Pragma("unroll") for (int m = 0; m < 4; ++m) _Pragma("unroll") for (int k = 0; k < 2; ++k)                         \
;     dst[m][k] = *(const bf16x8*)(SA8(b, h) + la + m * 2048 + k * 1024)
; #define LDB8(dst, b, h)                                                                                               \
;   _Pragma("unroll") for (int n = 0; n < 2; ++n) _Pragma("unroll") for (int k = 0; k < 2; ++k)                         \
;     dst[n][k] = *(const bf16x8*)(SB8(b, h) + lb + n * 2048 + k * 1024)
; #define WAITL8(n) asm volatile("s_waitcnt lgkmcnt(" #n ")" ::: "memory")
; #define BAR8 __builtin_amdgcn_s_barrier()
; #define SCHED8 __builtin_amdgcn_sched_barrier(0)
; template <class Epi>
; DEV void gemm_tile8(char* shm, const u16* __restrict__ A, const u16* __restrict__ Bt, int K, int brow, int bcol, Epi& epi) {
;     ...
;   for (int t = 0; t < nt - 2; t += 2) {
;     LDB8(B0, 0, 0); SCHED8; LDA8(At, 0, 0); STAGE8(SA8(1, 1), A, brow + HALF, t + 1);
;     WAITL8(8); BAR8; WAITL8(0); MMA8(0, 0, At, B0); BAR8; SCHED8;
;     LDB8(B1, 0, 1); STAGE8(SB8(0, 0), Bt, bcol, t + 2);
;     BAR8; WAITL8(0); MMA8(0, 1, At, B1); BAR8;
;     LDA8(At, 0, 1); STAGE8(SA8(0, 0), A, brow, t + 2);
;     BAR8; WAITL8(0); MMA8(1, 0, At, B0); BAR8; SCHED8;
;     STAGE8(SB8(0, 1), Bt, bcol + HALF, t + 2);
.LBB0_599:
	v_or_b32_e32 v134, 0x10000, v133
	v_add_u32_e32 v136, 0x10800, v133
	v_add_u32_e32 v135, 0x10400, v133
	ds_read_b128 v[144:147], v134
	ds_read_b128 v[148:151], v135
	v_add_u32_e32 v137, 0x10c00, v133
	ds_read_b128 v[152:155], v136
	ds_read_b128 v[156:159], v137
	v_lshl_add_u64 v[228:229], s[18:19], 0, v[130:131]
	s_mov_b64 s[92:93], 0x1aca0080
	s_add_i32 s91, s40, 0xc000
	v_lshl_add_u64 v[138:139], v[228:229], 0, s[92:93]
	s_mov_b32 m0, s91
	s_mov_b64 s[92:93], 0x1acb0080
	s_add_i32 s23, s40, 0xe000
	ds_read_b128 v[160:163], v132
	ds_read_b128 v[164:167], v132 offset:1024
	ds_read_b128 v[168:171], v132 offset:2048
	ds_read_b128 v[172:175], v132 offset:3072
	ds_read_b128 v[176:179], v132 offset:4096
	ds_read_b128 v[180:183], v132 offset:5120
	ds_read_b128 v[184:187], v132 offset:6144
	ds_read_b128 v[188:191], v132 offset:7168
	global_load_lds_dwordx4 v[138:139], off
	v_lshl_add_u64 v[138:139], v[228:229], 0, s[92:93]
	s_mov_b32 m0, s23
	s_nop 0
	global_load_lds_dwordx4 v[138:139], off
	s_waitcnt lgkmcnt(8)
	s_barrier
	s_waitcnt lgkmcnt(0)
	s_setprio 1
	s_waitcnt lgkmcnt(0)
	v_mfma_f32_16x16x32_bf16 v[124:127], v[144:147], v[160:163], v[124:127]
	v_mfma_f32_16x16x32_bf16 v[120:123], v[152:155], v[160:163], v[120:123]
	v_mfma_f32_16x16x32_bf16 v[116:119], v[144:147], v[168:171], v[116:119]
	v_mfma_f32_16x16x32_bf16 v[112:115], v[152:155], v[168:171], v[112:115]
	v_mfma_f32_16x16x32_bf16 v[108:111], v[144:147], v[176:179], v[108:111]
	v_mfma_f32_16x16x32_bf16 v[104:107], v[152:155], v[176:179], v[104:107]
	v_mfma_f32_16x16x32_bf16 v[100:103], v[144:147], v[184:187], v[100:103]
	v_mfma_f32_16x16x32_bf16 v[96:99], v[152:155], v[184:187], v[96:99]
	v_mfma_f32_16x16x32_bf16 v[124:127], v[148:151], v[164:167], v[124:127]
	v_mfma_f32_16x16x32_bf16 v[120:123], v[156:159], v[164:167], v[120:123]
	v_mfma_f32_16x16x32_bf16 v[116:119], v[148:151], v[172:175], v[116:119]
	v_mfma_f32_16x16x32_bf16 v[112:115], v[156:159], v[172:175], v[112:115]
	v_mfma_f32_16x16x32_bf16 v[108:111], v[148:151], v[180:183], v[108:111]
	v_mfma_f32_16x16x32_bf16 v[104:107], v[156:159], v[180:183], v[104:107]
	v_mfma_f32_16x16x32_bf16 v[100:103], v[148:151], v[188:191], v[100:103]
	v_mfma_f32_16x16x32_bf16 v[96:99], v[156:159], v[188:191], v[96:99]
	s_setprio 0
	s_barrier
	v_lshl_add_u64 v[230:231], s[20:21], 0, v[130:131]
	s_mov_b64 s[92:93], 0xb00100
	s_mov_b32 m0, s41
	v_or_b32_e32 v138, 0x14000, v133
	v_add_u32_e32 v140, 0x14800, v133
	v_lshl_add_u64 v[220:221], v[230:231], 0, s[92:93]
	s_mov_b64 s[92:93], 0xb10100
	v_add_u32_e32 v139, 0x14400, v133
	ds_read_b128 v[204:207], v138
	ds_read_b128 v[208:211], v139
	v_add_u32_e32 v142, 0x14c00, v133
	ds_read_b128 v[212:215], v140
	ds_read_b128 v[216:219], v142
	global_load_lds_dwordx4 v[220:221], off
	v_lshl_add_u64 v[220:221], v[230:231], 0, s[92:93]
	s_mov_b32 m0, s45
	s_nop 0
	global_load_lds_dwordx4 v[220:221], off
	s_barrier
	s_waitcnt lgkmcnt(0)
	s_setprio 1
	s_waitcnt lgkmcnt(0)
	v_mfma_f32_16x16x32_bf16 v[92:95], v[204:207], v[160:163], v[92:95]
	v_mfma_f32_16x16x32_bf16 v[88:91], v[212:215], v[160:163], v[88:91]
	v_mfma_f32_16x16x32_bf16 v[84:87], v[204:207], v[168:171], v[84:87]
	v_mfma_f32_16x16x32_bf16 v[80:83], v[212:215], v[168:171], v[80:83]
	v_mfma_f32_16x16x32_bf16 v[76:79], v[204:207], v[176:179], v[76:79]
	v_mfma_f32_16x16x32_bf16 v[72:75], v[212:215], v[176:179], v[72:75]
	v_mfma_f32_16x16x32_bf16 v[68:71], v[204:207], v[184:187], v[68:71]
	v_mfma_f32_16x16x32_bf16 v[64:67], v[212:215], v[184:187], v[64:67]
	v_mfma_f32_16x16x32_bf16 v[92:95], v[208:211], v[164:167], v[92:95]
	v_mfma_f32_16x16x32_bf16 v[88:91], v[216:219], v[164:167], v[88:91]
	v_mfma_f32_16x16x32_bf16 v[84:87], v[208:211], v[172:175], v[84:87]
	v_mfma_f32_16x16x32_bf16 v[80:83], v[216:219], v[172:175], v[80:83]
	v_mfma_f32_16x16x32_bf16 v[76:79], v[208:211], v[180:183], v[76:79]
	v_mfma_f32_16x16x32_bf16 v[72:75], v[216:219], v[180:183], v[72:75]
	v_mfma_f32_16x16x32_bf16 v[68:71], v[208:211], v[188:191], v[68:71]
	v_mfma_f32_16x16x32_bf16 v[64:67], v[216:219], v[188:191], v[64:67]
	s_setprio 0
	s_mov_b64 s[92:93], 0x1ac80100
	s_mov_b32 m0, s40
	v_lshl_add_u64 v[220:221], v[228:229], 0, s[92:93]
	s_mov_b64 s[92:93], 0x1ac90100
	s_barrier
	ds_read_b128 v[160:163], v132 offset:16384
	ds_read_b128 v[164:167], v132 offset:17408
	ds_read_b128 v[168:171], v132 offset:18432
	ds_read_b128 v[172:175], v132 offset:19456
	ds_read_b128 v[176:179], v132 offset:20480
	ds_read_b128 v[180:183], v132 offset:21504
	ds_read_b128 v[184:187], v132 offset:22528
	ds_read_b128 v[188:191], v132 offset:23552
	global_load_lds_dwordx4 v[220:221], off
	v_lshl_add_u64 v[220:221], v[228:229], 0, s[92:93]
	s_mov_b32 m0, s48
	s_nop 0
	global_load_lds_dwordx4 v[220:221], off
	s_barrier
	s_waitcnt lgkmcnt(0)
	s_setprio 1
	s_waitcnt lgkmcnt(0)
	v_mfma_f32_16x16x32_bf16 v[60:63], v[144:147], v[160:163], v[60:63]
	v_mfma_f32_16x16x32_bf16 v[56:59], v[152:155], v[160:163], v[56:59]
	v_mfma_f32_16x16x32_bf16 v[52:55], v[144:147], v[168:171], v[52:55]
	v_mfma_f32_16x16x32_bf16 v[48:51], v[152:155], v[168:171], v[48:51]
	v_mfma_f32_16x16x32_bf16 v[44:47], v[144:147], v[176:179], v[44:47]
	v_mfma_f32_16x16x32_bf16 v[40:43], v[152:155], v[176:179], v[40:43]
	v_mfma_f32_16x16x32_bf16 v[36:39], v[144:147], v[184:187], v[36:39]
	v_mfma_f32_16x16x32_bf16 v[32:35], v[152:155], v[184:187], v[32:35]
	v_mfma_f32_16x16x32_bf16 v[60:63], v[148:151], v[164:167], v[60:63]
	v_mfma_f32_16x16x32_bf16 v[56:59], v[156:159], v[164:167], v[56:59]
	v_mfma_f32_16x16x32_bf16 v[52:55], v[148:151], v[172:175], v[52:55]
	v_mfma_f32_16x16x32_bf16 v[48:51], v[156:159], v[172:175], v[48:51]
	v_mfma_f32_16x16x32_bf16 v[44:47], v[148:151], v[180:183], v[44:47]
	v_mfma_f32_16x16x32_bf16 v[40:43], v[156:159], v[180:183], v[40:43]
	v_mfma_f32_16x16x32_bf16 v[36:39], v[148:151], v[188:191], v[36:39]
	v_mfma_f32_16x16x32_bf16 v[32:35], v[156:159], v[188:191], v[32:35]
	s_setprio 0
	s_barrier
; #define LDA8(dst, b, h)                                                                                               \
;   _Pragma("unroll") for (int m = 0; m < 4; ++m) _Pragma("unroll") for (int k = 0; k < 2; ++k)                         \
;     dst[m][k] = *(const bf16x8*)(SA8(b, h) + la + m * 2048 + k * 1024)
; #define LDB8(dst, b, h)                                                                                               \
;   _Pragma("unroll") for (int n = 0; n < 2; ++n) _Pragma("unroll") for (int k = 0; k < 2; ++k)                         \
;     dst[n][k] = *(const bf16x8*)(SB8(b, h) + lb + n * 2048 + k * 1024)
; #define WAITV8(n) asm volatile("s_waitcnt vmcnt(" #n ")" ::: "memory")
; #define WAITL8(n) asm volatile("s_waitcnt lgkmcnt(" #n ")" ::: "memory")
; #define BAR8 __builtin_amdgcn_s_barrier()
; #define SCHED8 __builtin_amdgcn_sched_barrier(0)
; template <class Epi>
; DEV void gemm_tile8(char* shm, const u16* __restrict__ A, const u16* __restrict__ Bt, int K, int brow, int bcol, Epi& epi) {
;     ...
;     STAGE8(SB8(0, 1), Bt, bcol + HALF, t + 2);
;     WAITV8(6); BAR8; MMA8(1, 1, At, B1); BAR8;
;     LDB8(B0, 1, 0); SCHED8; LDA8(At, 1, 0); STAGE8(SA8(0, 1), A, brow + HALF, t + 2);
;     WAITL8(8); BAR8; WAITL8(0); MMA8(0, 0, At, B0); BAR8; SCHED8;
;     LDB8(B1, 1, 1); STAGE8(SB8(1, 0), Bt, bcol, t + 3);
;     BAR8; WAITL8(0); MMA8(0, 1, At, B1); BAR8;
;     LDA8(At, 1, 1); STAGE8(SA8(1, 0), A, brow, t + 3);
	s_mov_b64 s[92:93], 0xb20100
	s_mov_b32 m0, s54
	v_lshl_add_u64 v[144:145], v[230:231], 0, s[92:93]
	s_mov_b64 s[92:93], 0xb30100
	global_load_lds_dwordx4 v[144:145], off
	v_lshl_add_u64 v[144:145], v[230:231], 0, s[92:93]
	s_mov_b32 m0, s55
	s_nop 0
	global_load_lds_dwordx4 v[144:145], off
	s_waitcnt vmcnt(6)
	s_barrier
	s_setprio 1
	v_mfma_f32_16x16x32_bf16 v[28:31], v[204:207], v[160:163], v[28:31]
	v_mfma_f32_16x16x32_bf16 v[24:27], v[212:215], v[160:163], v[24:27]
	v_mfma_f32_16x16x32_bf16 v[20:23], v[204:207], v[168:171], v[20:23]
	v_mfma_f32_16x16x32_bf16 v[16:19], v[212:215], v[168:171], v[16:19]
	v_mfma_f32_16x16x32_bf16 v[12:15], v[204:207], v[176:179], v[12:15]
	v_mfma_f32_16x16x32_bf16 v[8:11], v[212:215], v[176:179], v[8:11]
	v_mfma_f32_16x16x32_bf16 v[4:7], v[204:207], v[184:187], v[4:7]
	v_mfma_f32_16x16x32_bf16 v[0:3], v[212:215], v[184:187], v[0:3]
	v_mfma_f32_16x16x32_bf16 v[28:31], v[208:211], v[164:167], v[28:31]
	v_mfma_f32_16x16x32_bf16 v[24:27], v[216:219], v[164:167], v[24:27]
	v_mfma_f32_16x16x32_bf16 v[20:23], v[208:211], v[172:175], v[20:23]
	v_mfma_f32_16x16x32_bf16 v[16:19], v[216:219], v[172:175], v[16:19]
	v_mfma_f32_16x16x32_bf16 v[12:15], v[208:211], v[180:183], v[12:15]
	v_mfma_f32_16x16x32_bf16 v[8:11], v[216:219], v[180:183], v[8:11]
	v_mfma_f32_16x16x32_bf16 v[4:7], v[208:211], v[188:191], v[4:7]
	v_mfma_f32_16x16x32_bf16 v[0:3], v[216:219], v[188:191], v[0:3]
	s_setprio 0
	v_or_b32_e32 v143, 0x18000, v133
	v_add_u32_e32 v145, 0x18800, v133
	s_barrier
	v_add_u32_e32 v144, 0x18400, v133
	ds_read_b128 v[152:155], v143
	ds_read_b128 v[156:159], v144
	v_add_u32_e32 v146, 0x18c00, v133
	ds_read_b128 v[160:163], v145
	ds_read_b128 v[164:167], v146
	s_mov_b64 s[92:93], 0x1aca0100
	s_mov_b32 m0, s70
	v_lshl_add_u64 v[148:149], v[228:229], 0, s[92:93]
	s_mov_b64 s[92:93], 0x1acb0100
	ds_read_b128 v[168:171], v132 offset:32768
	ds_read_b128 v[172:175], v132 offset:33792
	ds_read_b128 v[176:179], v132 offset:34816
	ds_read_b128 v[180:183], v132 offset:35840
	ds_read_b128 v[184:187], v132 offset:36864
	ds_read_b128 v[188:191], v132 offset:37888
	ds_read_b128 v[204:207], v132 offset:38912
	ds_read_b128 v[208:211], v132 offset:39936
	global_load_lds_dwordx4 v[148:149], off
	v_lshl_add_u64 v[148:149], v[228:229], 0, s[92:93]
	s_mov_b32 m0, s71
	s_nop 0
	global_load_lds_dwordx4 v[148:149], off
	s_waitcnt lgkmcnt(8)
	s_barrier
	s_waitcnt lgkmcnt(0)
	s_setprio 1
	s_waitcnt lgkmcnt(0)
	v_mfma_f32_16x16x32_bf16 v[124:127], v[152:155], v[168:171], v[124:127]
	v_mfma_f32_16x16x32_bf16 v[120:123], v[160:163], v[168:171], v[120:123]
	v_mfma_f32_16x16x32_bf16 v[116:119], v[152:155], v[176:179], v[116:119]
	v_mfma_f32_16x16x32_bf16 v[112:115], v[160:163], v[176:179], v[112:115]
	v_mfma_f32_16x16x32_bf16 v[108:111], v[152:155], v[184:187], v[108:111]
	v_mfma_f32_16x16x32_bf16 v[104:107], v[160:163], v[184:187], v[104:107]
	v_mfma_f32_16x16x32_bf16 v[100:103], v[152:155], v[204:207], v[100:103]
	v_mfma_f32_16x16x32_bf16 v[96:99], v[160:163], v[204:207], v[96:99]
	v_mfma_f32_16x16x32_bf16 v[124:127], v[156:159], v[172:175], v[124:127]
	v_mfma_f32_16x16x32_bf16 v[120:123], v[164:167], v[172:175], v[120:123]
	v_mfma_f32_16x16x32_bf16 v[116:119], v[156:159], v[180:183], v[116:119]
	v_mfma_f32_16x16x32_bf16 v[112:115], v[164:167], v[180:183], v[112:115]
	v_mfma_f32_16x16x32_bf16 v[108:111], v[156:159], v[188:191], v[108:111]
	v_mfma_f32_16x16x32_bf16 v[104:107], v[164:167], v[188:191], v[104:107]
	v_mfma_f32_16x16x32_bf16 v[100:103], v[156:159], v[208:211], v[100:103]
	v_mfma_f32_16x16x32_bf16 v[96:99], v[164:167], v[208:211], v[96:99]
	s_setprio 0
	s_barrier
	s_mov_b64 s[92:93], 0xb00180
	s_mov_b32 m0, s72
	v_or_b32_e32 v147, 0x1c000, v133
	v_add_u32_e32 v149, 0x1c800, v133
	v_lshl_add_u64 v[232:233], v[230:231], 0, s[92:93]
	s_mov_b64 s[92:93], 0xb10180
	v_add_u32_e32 v148, 0x1c400, v133
	ds_read_b128 v[212:215], v147
	ds_read_b128 v[216:219], v148
	v_add_u32_e32 v150, 0x1cc00, v133
	ds_read_b128 v[220:223], v149
	ds_read_b128 v[224:227], v150
	global_load_lds_dwordx4 v[232:233], off
	v_lshl_add_u64 v[232:233], v[230:231], 0, s[92:93]
	s_mov_b32 m0, s73
	s_nop 0
	global_load_lds_dwordx4 v[232:233], off
	s_barrier
	s_waitcnt lgkmcnt(0)
	s_setprio 1
	s_waitcnt lgkmcnt(0)
	v_mfma_f32_16x16x32_bf16 v[92:95], v[212:215], v[168:171], v[92:95]
	v_mfma_f32_16x16x32_bf16 v[88:91], v[220:223], v[168:171], v[88:91]
	v_mfma_f32_16x16x32_bf16 v[84:87], v[212:215], v[176:179], v[84:87]
	v_mfma_f32_16x16x32_bf16 v[80:83], v[220:223], v[176:179], v[80:83]
	v_mfma_f32_16x16x32_bf16 v[76:79], v[212:215], v[184:187], v[76:79]
	v_mfma_f32_16x16x32_bf16 v[72:75], v[220:223], v[184:187], v[72:75]
	v_mfma_f32_16x16x32_bf16 v[68:71], v[212:215], v[204:207], v[68:71]
	v_mfma_f32_16x16x32_bf16 v[64:67], v[220:223], v[204:207], v[64:67]
	v_mfma_f32_16x16x32_bf16 v[92:95], v[216:219], v[172:175], v[92:95]
	v_mfma_f32_16x16x32_bf16 v[88:91], v[224:227], v[172:175], v[88:91]
	v_mfma_f32_16x16x32_bf16 v[84:87], v[216:219], v[180:183], v[84:87]
	v_mfma_f32_16x16x32_bf16 v[80:83], v[224:227], v[180:183], v[80:83]
	v_mfma_f32_16x16x32_bf16 v[76:79], v[216:219], v[188:191], v[76:79]
	v_mfma_f32_16x16x32_bf16 v[72:75], v[224:227], v[188:191], v[72:75]
	v_mfma_f32_16x16x32_bf16 v[68:71], v[216:219], v[208:211], v[68:71]
	v_mfma_f32_16x16x32_bf16 v[64:67], v[224:227], v[208:211], v[64:67]
	s_setprio 0
	s_mov_b64 s[92:93], 0x1ac80180
	s_mov_b32 m0, s81
	v_lshl_add_u64 v[232:233], v[228:229], 0, s[92:93]
	s_mov_b64 s[92:93], 0x1ac90180
	s_barrier
; #define LDA8(dst, b, h)                                                                                               \
;   _Pragma("unroll") for (int m = 0; m < 4; ++m) _Pragma("unroll") for (int k = 0; k < 2; ++k)                         \
;     dst[m][k] = *(const bf16x8*)(SA8(b, h) + la + m * 2048 + k * 1024)
; #define LDB8(dst, b, h)                                                                                               \
;   _Pragma("unroll") for (int n = 0; n < 2; ++n) _Pragma("unroll") for (int k = 0; k < 2; ++k)                         \
;     dst[n][k] = *(const bf16x8*)(SB8(b, h) + lb + n * 2048 + k * 1024)
; #define WAITV8(n) asm volatile("s_waitcnt vmcnt(" #n ")" ::: "memory")
; #define WAITL8(n) asm volatile("s_waitcnt lgkmcnt(" #n ")" ::: "memory")
; #define BAR8 __builtin_amdgcn_s_barrier()
; #define SCHED8 __builtin_amdgcn_sched_barrier(0)
; template <class Epi>
; DEV void gemm_tile8(char* shm, const u16* __restrict__ A, const u16* __restrict__ Bt, int K, int brow, int bcol, Epi& epi) {
;     ...
;     LDA8(At, 1, 1); STAGE8(SA8(1, 0), A, brow, t + 3);
;     BAR8; WAITL8(0); MMA8(1, 0, At, B0); BAR8; SCHED8;
;     STAGE8(SB8(1, 1), Bt, bcol + HALF, t + 3);
;     WAITV8(6); BAR8; MMA8(1, 1, At, B1); BAR8;
;   }
;   { LDB8(B0, 0, 0); LDA8(At, 0, 0); STAGE8(SA8(1, 1), A, brow + HALF, nt - 1);
;     BAR8; WAITL8(0); MMA8(0, 0, At, B0); BAR8;
;     LDB8(B1, 0, 1); BAR8; WAITL8(0); MMA8(0, 1, At, B1); BAR8;
	ds_read_b128 v[168:171], v132 offset:49152
	ds_read_b128 v[172:175], v132 offset:50176
	ds_read_b128 v[176:179], v132 offset:51200
	ds_read_b128 v[180:183], v132 offset:52224
	ds_read_b128 v[184:187], v132 offset:53248
	ds_read_b128 v[188:191], v132 offset:54272
	ds_read_b128 v[204:207], v132 offset:55296
	ds_read_b128 v[208:211], v132 offset:56320
	global_load_lds_dwordx4 v[232:233], off
	v_lshl_add_u64 v[228:229], v[228:229], 0, s[92:93]
	s_mov_b32 m0, s84
	s_nop 0
	global_load_lds_dwordx4 v[228:229], off
	s_barrier
	s_waitcnt lgkmcnt(0)
	s_setprio 1
	s_waitcnt lgkmcnt(0)
	v_mfma_f32_16x16x32_bf16 v[60:63], v[152:155], v[168:171], v[60:63]
	v_mfma_f32_16x16x32_bf16 v[56:59], v[160:163], v[168:171], v[56:59]
	v_mfma_f32_16x16x32_bf16 v[52:55], v[152:155], v[176:179], v[52:55]
	v_mfma_f32_16x16x32_bf16 v[48:51], v[160:163], v[176:179], v[48:51]
	v_mfma_f32_16x16x32_bf16 v[44:47], v[152:155], v[184:187], v[44:47]
	v_mfma_f32_16x16x32_bf16 v[40:43], v[160:163], v[184:187], v[40:43]
	v_mfma_f32_16x16x32_bf16 v[36:39], v[152:155], v[204:207], v[36:39]
	v_mfma_f32_16x16x32_bf16 v[32:35], v[160:163], v[204:207], v[32:35]
	v_mfma_f32_16x16x32_bf16 v[60:63], v[156:159], v[172:175], v[60:63]
	v_mfma_f32_16x16x32_bf16 v[56:59], v[164:167], v[172:175], v[56:59]
	v_mfma_f32_16x16x32_bf16 v[52:55], v[156:159], v[180:183], v[52:55]
	v_mfma_f32_16x16x32_bf16 v[48:51], v[164:167], v[180:183], v[48:51]
	v_mfma_f32_16x16x32_bf16 v[44:47], v[156:159], v[188:191], v[44:47]
	v_mfma_f32_16x16x32_bf16 v[40:43], v[164:167], v[188:191], v[40:43]
	v_mfma_f32_16x16x32_bf16 v[36:39], v[156:159], v[208:211], v[36:39]
	v_mfma_f32_16x16x32_bf16 v[32:35], v[164:167], v[208:211], v[32:35]
	s_setprio 0
	s_barrier
	s_mov_b64 s[92:93], 0xb20180
	s_mov_b32 m0, s85
	v_lshl_add_u64 v[152:153], v[230:231], 0, s[92:93]
	s_mov_b64 s[92:93], 0xb30180
	global_load_lds_dwordx4 v[152:153], off
	v_lshl_add_u64 v[152:153], v[230:231], 0, s[92:93]
	s_mov_b32 m0, s90
	s_nop 0
	global_load_lds_dwordx4 v[152:153], off
	s_waitcnt vmcnt(6)
	s_barrier
	s_setprio 1
	v_mfma_f32_16x16x32_bf16 v[28:31], v[212:215], v[168:171], v[28:31]
	v_mfma_f32_16x16x32_bf16 v[24:27], v[220:223], v[168:171], v[24:27]
	v_mfma_f32_16x16x32_bf16 v[20:23], v[212:215], v[176:179], v[20:23]
	v_mfma_f32_16x16x32_bf16 v[16:19], v[220:223], v[176:179], v[16:19]
	v_mfma_f32_16x16x32_bf16 v[12:15], v[212:215], v[184:187], v[12:15]
	v_mfma_f32_16x16x32_bf16 v[8:11], v[220:223], v[184:187], v[8:11]
	v_mfma_f32_16x16x32_bf16 v[4:7], v[212:215], v[204:207], v[4:7]
	v_mfma_f32_16x16x32_bf16 v[0:3], v[220:223], v[204:207], v[0:3]
	v_mfma_f32_16x16x32_bf16 v[28:31], v[216:219], v[172:175], v[28:31]
	v_mfma_f32_16x16x32_bf16 v[24:27], v[224:227], v[172:175], v[24:27]
	v_mfma_f32_16x16x32_bf16 v[20:23], v[216:219], v[180:183], v[20:23]
	v_mfma_f32_16x16x32_bf16 v[16:19], v[224:227], v[180:183], v[16:19]
	v_mfma_f32_16x16x32_bf16 v[12:15], v[216:219], v[188:191], v[12:15]
	v_mfma_f32_16x16x32_bf16 v[8:11], v[224:227], v[188:191], v[8:11]
	v_mfma_f32_16x16x32_bf16 v[4:7], v[216:219], v[208:211], v[4:7]
	v_mfma_f32_16x16x32_bf16 v[0:3], v[224:227], v[208:211], v[0:3]
	s_setprio 0
	s_add_i32 s22, s22, 2
	s_add_u32 s18, s18, 0x100
	s_addc_u32 s19, s19, 0
	s_add_u32 s20, s20, 0x100
	s_addc_u32 s21, s21, 0
	s_cmp_lt_u32 s22, 4
	s_barrier
	s_cbranch_scc1 .LBB0_599
	s_mov_b64 s[18:19], 0x380
	s_mov_b32 m0, s91
	v_lshl_add_u64 v[130:131], v[128:129], 0, s[18:19]
	s_mov_b64 s[18:19], 0x10380
	ds_read_b128 v[152:155], v134
	ds_read_b128 v[156:159], v135
	ds_read_b128 v[160:163], v136
	ds_read_b128 v[134:137], v137
	ds_read_b128 v[164:167], v132
	ds_read_b128 v[168:171], v132 offset:1024
	ds_read_b128 v[172:175], v132 offset:2048
	ds_read_b128 v[176:179], v132 offset:3072
	ds_read_b128 v[180:183], v132 offset:4096
	ds_read_b128 v[184:187], v132 offset:5120
	ds_read_b128 v[188:191], v132 offset:6144
	ds_read_b128 v[204:207], v132 offset:7168
	global_load_lds_dwordx4 v[130:131], off
	v_lshl_add_u64 v[128:129], v[128:129], 0, s[18:19]
	s_mov_b32 m0, s23
	s_nop 0
	global_load_lds_dwordx4 v[128:129], off
	s_barrier
	s_waitcnt lgkmcnt(0)
	s_setprio 1
	s_waitcnt lgkmcnt(0)
	v_mfma_f32_16x16x32_bf16 v[124:127], v[152:155], v[164:167], v[124:127]
	v_mfma_f32_16x16x32_bf16 v[120:123], v[160:163], v[164:167], v[120:123]
	v_mfma_f32_16x16x32_bf16 v[116:119], v[152:155], v[172:175], v[116:119]
	v_mfma_f32_16x16x32_bf16 v[112:115], v[160:163], v[172:175], v[112:115]
	v_mfma_f32_16x16x32_bf16 v[108:111], v[152:155], v[180:183], v[108:111]
	v_mfma_f32_16x16x32_bf16 v[104:107], v[160:163], v[180:183], v[104:107]
	v_mfma_f32_16x16x32_bf16 v[100:103], v[152:155], v[188:191], v[100:103]
	v_mfma_f32_16x16x32_bf16 v[96:99], v[160:163], v[188:191], v[96:99]
	v_mfma_f32_16x16x32_bf16 v[124:127], v[156:159], v[168:171], v[124:127]
	v_mfma_f32_16x16x32_bf16 v[120:123], v[134:137], v[168:171], v[120:123]
	v_mfma_f32_16x16x32_bf16 v[116:119], v[156:159], v[176:179], v[116:119]
	v_mfma_f32_16x16x32_bf16 v[112:115], v[134:137], v[176:179], v[112:115]
	v_mfma_f32_16x16x32_bf16 v[108:111], v[156:159], v[184:187], v[108:111]
	v_mfma_f32_16x16x32_bf16 v[104:107], v[134:137], v[184:187], v[104:107]
	v_mfma_f32_16x16x32_bf16 v[100:103], v[156:159], v[204:207], v[100:103]
	v_mfma_f32_16x16x32_bf16 v[96:99], v[134:137], v[204:207], v[96:99]
	s_setprio 0
	s_barrier
	ds_read_b128 v[128:131], v138
	ds_read_b128 v[208:211], v139
	ds_read_b128 v[212:215], v140
	ds_read_b128 v[216:219], v142
	s_barrier
; #define LDA8(dst, b, h)                                                                                               \
;   _Pragma("unroll") for (int m = 0; m < 4; ++m) _Pragma("unroll") for (int k = 0; k < 2; ++k)                         \
;     dst[m][k] = *(const bf16x8*)(SA8(b, h) + la + m * 2048 + k * 1024)
; #define LDB8(dst, b, h)                                                                                               \
;   _Pragma("unroll") for (int n = 0; n < 2; ++n) _Pragma("unroll") for (int k = 0; k < 2; ++k)                         \
;     dst[n][k] = *(const bf16x8*)(SB8(b, h) + lb + n * 2048 + k * 1024)
; #define WAITV8(n) asm volatile("s_waitcnt vmcnt(" #n ")" ::: "memory")
; #define WAITL8(n) asm volatile("s_waitcnt lgkmcnt(" #n ")" ::: "memory")
; #define BAR8 __builtin_amdgcn_s_barrier()
; template <class Epi>
; DEV void gemm_tile8(char* shm, const u16* __restrict__ A, const u16* __restrict__ Bt, int K, int brow, int bcol, Epi& epi) {
;     ...
;     LDB8(B1, 0, 1); BAR8; WAITL8(0); MMA8(0, 1, At, B1); BAR8;
;     LDA8(At, 0, 1); WAITV8(4); BAR8; WAITL8(0); MMA8(1, 0, At, B0); MMA8(1, 1, At, B1); BAR8; }
;   { LDB8(B0, 1, 0); LDA8(At, 1, 0); WAITV8(2); BAR8; WAITL8(0); MMA8(0, 0, At, B0); BAR8;
	s_waitcnt lgkmcnt(0)
	s_setprio 1
	s_waitcnt lgkmcnt(3)
	v_mfma_f32_16x16x32_bf16 v[92:95], v[128:131], v[164:167], v[92:95]
	s_waitcnt lgkmcnt(1)
	v_mfma_f32_16x16x32_bf16 v[88:91], v[212:215], v[164:167], v[88:91]
	v_mfma_f32_16x16x32_bf16 v[84:87], v[128:131], v[172:175], v[84:87]
	v_mfma_f32_16x16x32_bf16 v[80:83], v[212:215], v[172:175], v[80:83]
	v_mfma_f32_16x16x32_bf16 v[76:79], v[128:131], v[180:183], v[76:79]
	v_mfma_f32_16x16x32_bf16 v[72:75], v[212:215], v[180:183], v[72:75]
	v_mfma_f32_16x16x32_bf16 v[68:71], v[128:131], v[188:191], v[68:71]
	v_mfma_f32_16x16x32_bf16 v[64:67], v[212:215], v[188:191], v[64:67]
	v_mfma_f32_16x16x32_bf16 v[220:223], v[208:211], v[168:171], v[92:95]
	s_waitcnt lgkmcnt(0)
	v_mfma_f32_16x16x32_bf16 v[164:167], v[216:219], v[168:171], v[88:91]
	v_mfma_f32_16x16x32_bf16 v[168:171], v[208:211], v[176:179], v[84:87]
	v_mfma_f32_16x16x32_bf16 v[172:175], v[216:219], v[176:179], v[80:83]
	v_mfma_f32_16x16x32_bf16 v[176:179], v[208:211], v[184:187], v[76:79]
	v_mfma_f32_16x16x32_bf16 v[180:183], v[216:219], v[184:187], v[72:75]
	v_mfma_f32_16x16x32_bf16 v[184:187], v[208:211], v[204:207], v[68:71]
	v_mfma_f32_16x16x32_bf16 v[188:191], v[216:219], v[204:207], v[64:67]
	s_setprio 0
	s_barrier
	s_nop 0
	ds_read_b128 v[64:67], v132 offset:16384
	ds_read_b128 v[68:71], v132 offset:17408
	ds_read_b128 v[72:75], v132 offset:18432
	ds_read_b128 v[76:79], v132 offset:19456
	ds_read_b128 v[80:83], v132 offset:20480
	ds_read_b128 v[84:87], v132 offset:21504
	ds_read_b128 v[88:91], v132 offset:22528
	ds_read_b128 v[92:95], v132 offset:23552
	s_waitcnt vmcnt(4)
	s_barrier
	s_waitcnt lgkmcnt(0)
	s_setprio 1
	s_waitcnt lgkmcnt(7)
	v_mfma_f32_16x16x32_bf16 v[60:63], v[152:155], v[64:67], v[60:63]
	v_mfma_f32_16x16x32_bf16 v[56:59], v[160:163], v[64:67], v[56:59]
	s_waitcnt lgkmcnt(5)
	v_mfma_f32_16x16x32_bf16 v[52:55], v[152:155], v[72:75], v[52:55]
	v_mfma_f32_16x16x32_bf16 v[48:51], v[160:163], v[72:75], v[48:51]
	s_waitcnt lgkmcnt(3)
	v_mfma_f32_16x16x32_bf16 v[44:47], v[152:155], v[80:83], v[44:47]
	v_mfma_f32_16x16x32_bf16 v[40:43], v[160:163], v[80:83], v[40:43]
	s_waitcnt lgkmcnt(1)
	v_mfma_f32_16x16x32_bf16 v[36:39], v[152:155], v[88:91], v[36:39]
	v_mfma_f32_16x16x32_bf16 v[32:35], v[160:163], v[88:91], v[32:35]
	v_mfma_f32_16x16x32_bf16 v[60:63], v[156:159], v[68:71], v[60:63]
	v_mfma_f32_16x16x32_bf16 v[56:59], v[134:137], v[68:71], v[56:59]
	v_mfma_f32_16x16x32_bf16 v[52:55], v[156:159], v[76:79], v[52:55]
	v_mfma_f32_16x16x32_bf16 v[48:51], v[134:137], v[76:79], v[48:51]
	v_mfma_f32_16x16x32_bf16 v[44:47], v[156:159], v[84:87], v[44:47]
	v_mfma_f32_16x16x32_bf16 v[40:43], v[134:137], v[84:87], v[40:43]
	s_waitcnt lgkmcnt(0)
	v_mfma_f32_16x16x32_bf16 v[36:39], v[156:159], v[92:95], v[36:39]
	v_mfma_f32_16x16x32_bf16 v[32:35], v[134:137], v[92:95], v[32:35]
	s_setprio 0
	s_setprio 1
	v_mfma_f32_16x16x32_bf16 v[28:31], v[128:131], v[64:67], v[28:31]
	v_mfma_f32_16x16x32_bf16 v[24:27], v[212:215], v[64:67], v[24:27]
	v_mfma_f32_16x16x32_bf16 v[20:23], v[128:131], v[72:75], v[20:23]
	v_mfma_f32_16x16x32_bf16 v[16:19], v[212:215], v[72:75], v[16:19]
	v_mfma_f32_16x16x32_bf16 v[12:15], v[128:131], v[80:83], v[12:15]
	v_mfma_f32_16x16x32_bf16 v[8:11], v[212:215], v[80:83], v[8:11]
	v_mfma_f32_16x16x32_bf16 v[4:7], v[128:131], v[88:91], v[4:7]
	v_mfma_f32_16x16x32_bf16 v[0:3], v[212:215], v[88:91], v[0:3]
	v_mfma_f32_16x16x32_bf16 v[134:137], v[208:211], v[68:71], v[28:31]
	v_mfma_f32_16x16x32_bf16 v[152:155], v[216:219], v[68:71], v[24:27]
	v_mfma_f32_16x16x32_bf16 v[156:159], v[208:211], v[76:79], v[20:23]
	v_mfma_f32_16x16x32_bf16 v[160:163], v[216:219], v[76:79], v[16:19]
	v_mfma_f32_16x16x32_bf16 v[204:207], v[208:211], v[84:87], v[12:15]
	v_mfma_f32_16x16x32_bf16 v[224:227], v[216:219], v[84:87], v[8:11]
	v_mfma_f32_16x16x32_bf16 v[128:131], v[208:211], v[92:95], v[4:7]
	v_mfma_f32_16x16x32_bf16 v[208:211], v[216:219], v[92:95], v[0:3]
	s_setprio 0
	s_barrier
	ds_read_b128 v[24:27], v143
	ds_read_b128 v[28:31], v144
	ds_read_b128 v[142:145], v145
	ds_read_b128 v[212:215], v146
	ds_read_b128 v[0:3], v132 offset:32768
	ds_read_b128 v[4:7], v132 offset:33792
	ds_read_b128 v[8:11], v132 offset:34816
	ds_read_b128 v[12:15], v132 offset:35840
	ds_read_b128 v[16:19], v132 offset:36864
	ds_read_b128 v[20:23], v132 offset:37888
	ds_read_b128 v[216:219], v132 offset:38912
	ds_read_b128 v[228:231], v132 offset:39936
	s_waitcnt vmcnt(2)
	s_barrier
; #define LDA8(dst, b, h)                                                                                               \
;   _Pragma("unroll") for (int m = 0; m < 4; ++m) _Pragma("unroll") for (int k = 0; k < 2; ++k)                         \
;     dst[m][k] = *(const bf16x8*)(SA8(b, h) + la + m * 2048 + k * 1024)
; #define LDB8(dst, b, h)                                                                                               \
;   _Pragma("unroll") for (int n = 0; n < 2; ++n) _Pragma("unroll") for (int k = 0; k < 2; ++k)                         \
;     dst[n][k] = *(const bf16x8*)(SB8(b, h) + lb + n * 2048 + k * 1024)
; #define WAITV8(n) asm volatile("s_waitcnt vmcnt(" #n ")" ::: "memory")
; #define WAITL8(n) asm volatile("s_waitcnt lgkmcnt(" #n ")" ::: "memory")
; #define BAR8 __builtin_amdgcn_s_barrier()
; template <class Epi>
; DEV void gemm_tile8(char* shm, const u16* __restrict__ A, const u16* __restrict__ Bt, int K, int brow, int bcol, Epi& epi) {
;     ...
;   { LDB8(B0, 1, 0); LDA8(At, 1, 0); WAITV8(2); BAR8; WAITL8(0); MMA8(0, 0, At, B0); BAR8;
;     LDB8(B1, 1, 1); WAITV8(0); BAR8; WAITL8(0); MMA8(0, 1, At, B1); BAR8;
;     LDA8(At, 1, 1); BAR8; WAITL8(0); MMA8(1, 0, At, B0); MMA8(1, 1, At, B1); BAR8; }
;   if (wrs == 0) BAR8;
	s_waitcnt lgkmcnt(0)
	s_setprio 1
	s_waitcnt lgkmcnt(7)
	v_mfma_f32_16x16x32_bf16 v[64:67], v[24:27], v[0:3], v[124:127]
	s_waitcnt lgkmcnt(6)
	v_mfma_f32_16x16x32_bf16 v[72:75], v[28:31], v[4:7], v[64:67]
	v_mfma_f32_16x16x32_bf16 v[64:67], v[142:145], v[0:3], v[120:123]
	s_waitcnt lgkmcnt(5)
	v_mfma_f32_16x16x32_bf16 v[68:71], v[24:27], v[8:11], v[116:119]
	v_mfma_f32_16x16x32_bf16 v[76:79], v[142:145], v[8:11], v[112:115]
	s_waitcnt lgkmcnt(3)
	v_mfma_f32_16x16x32_bf16 v[80:83], v[24:27], v[16:19], v[108:111]
	v_mfma_f32_16x16x32_bf16 v[84:87], v[142:145], v[16:19], v[104:107]
	s_waitcnt lgkmcnt(1)
	v_mfma_f32_16x16x32_bf16 v[88:91], v[24:27], v[216:219], v[100:103]
	v_mfma_f32_16x16x32_bf16 v[92:95], v[142:145], v[216:219], v[96:99]
	v_mfma_f32_16x16x32_bf16 v[64:67], v[212:215], v[4:7], v[64:67]
	v_mfma_f32_16x16x32_bf16 v[68:71], v[28:31], v[12:15], v[68:71]
	v_mfma_f32_16x16x32_bf16 v[76:79], v[212:215], v[12:15], v[76:79]
	v_mfma_f32_16x16x32_bf16 v[80:83], v[28:31], v[20:23], v[80:83]
	v_mfma_f32_16x16x32_bf16 v[84:87], v[212:215], v[20:23], v[84:87]
	s_waitcnt lgkmcnt(0)
	v_mfma_f32_16x16x32_bf16 v[88:91], v[28:31], v[228:231], v[88:91]
	v_mfma_f32_16x16x32_bf16 v[92:95], v[212:215], v[228:231], v[92:95]
	s_setprio 0
	s_barrier
	ds_read_b128 v[232:235], v147
	ds_read_b128 v[236:239], v148
	ds_read_b128 v[146:149], v149
	ds_read_b128 v[240:243], v150
	s_waitcnt vmcnt(0)
	s_barrier
	s_waitcnt lgkmcnt(0)
	s_setprio 1
	s_waitcnt lgkmcnt(3)
	v_mfma_f32_16x16x32_bf16 v[96:99], v[232:235], v[0:3], v[220:223]
	s_waitcnt lgkmcnt(1)
	v_mfma_f32_16x16x32_bf16 v[0:3], v[146:149], v[0:3], v[164:167]
	v_mfma_f32_16x16x32_bf16 v[104:107], v[236:239], v[4:7], v[96:99]
	s_waitcnt lgkmcnt(0)
	v_mfma_f32_16x16x32_bf16 v[96:99], v[240:243], v[4:7], v[0:3]
	v_mfma_f32_16x16x32_bf16 v[0:3], v[232:235], v[8:11], v[168:171]
	v_mfma_f32_16x16x32_bf16 v[100:103], v[236:239], v[12:15], v[0:3]
	v_mfma_f32_16x16x32_bf16 v[0:3], v[146:149], v[8:11], v[172:175]
	v_mfma_f32_16x16x32_bf16 v[108:111], v[240:243], v[12:15], v[0:3]
	v_mfma_f32_16x16x32_bf16 v[0:3], v[232:235], v[16:19], v[176:179]
	v_mfma_f32_16x16x32_bf16 v[112:115], v[236:239], v[20:23], v[0:3]
	v_mfma_f32_16x16x32_bf16 v[0:3], v[146:149], v[16:19], v[180:183]
	v_mfma_f32_16x16x32_bf16 v[116:119], v[240:243], v[20:23], v[0:3]
	v_mfma_f32_16x16x32_bf16 v[0:3], v[232:235], v[216:219], v[184:187]
	v_mfma_f32_16x16x32_bf16 v[120:123], v[236:239], v[228:231], v[0:3]
	v_mfma_f32_16x16x32_bf16 v[0:3], v[146:149], v[216:219], v[188:191]
	v_mfma_f32_16x16x32_bf16 v[124:127], v[240:243], v[228:231], v[0:3]
	s_setprio 0
	s_barrier
	ds_read_b128 v[164:167], v132 offset:49152
	ds_read_b128 v[168:171], v132 offset:50176
	ds_read_b128 v[172:175], v132 offset:51200
	ds_read_b128 v[176:179], v132 offset:52224
	ds_read_b128 v[180:183], v132 offset:53248
	ds_read_b128 v[184:187], v132 offset:54272
	ds_read_b128 v[188:191], v132 offset:55296
	ds_read_b128 v[216:219], v132 offset:56320
	s_barrier
	s_waitcnt lgkmcnt(0)
	s_setprio 1
	s_waitcnt lgkmcnt(7)
	v_mfma_f32_16x16x32_bf16 v[0:3], v[24:27], v[164:167], v[60:63]
	s_waitcnt lgkmcnt(5)
	v_mfma_f32_16x16x32_bf16 v[8:11], v[24:27], v[172:175], v[52:55]
	s_waitcnt lgkmcnt(3)
	v_mfma_f32_16x16x32_bf16 v[16:19], v[24:27], v[180:183], v[44:47]
	s_waitcnt lgkmcnt(1)
	v_mfma_f32_16x16x32_bf16 v[24:27], v[24:27], v[188:191], v[36:39]
	v_mfma_f32_16x16x32_bf16 v[0:3], v[28:31], v[168:171], v[0:3]
	v_mfma_f32_16x16x32_bf16 v[4:7], v[142:145], v[164:167], v[56:59]
	v_mfma_f32_16x16x32_bf16 v[8:11], v[28:31], v[176:179], v[8:11]
	v_mfma_f32_16x16x32_bf16 v[12:15], v[142:145], v[172:175], v[48:51]
	v_mfma_f32_16x16x32_bf16 v[16:19], v[28:31], v[184:187], v[16:19]
	v_mfma_f32_16x16x32_bf16 v[20:23], v[142:145], v[180:183], v[40:43]
	s_waitcnt lgkmcnt(0)
	v_mfma_f32_16x16x32_bf16 v[24:27], v[28:31], v[216:219], v[24:27]
	v_mfma_f32_16x16x32_bf16 v[28:31], v[142:145], v[188:191], v[32:35]
	v_mfma_f32_16x16x32_bf16 v[4:7], v[212:215], v[168:171], v[4:7]
	v_mfma_f32_16x16x32_bf16 v[12:15], v[212:215], v[176:179], v[12:15]
	v_mfma_f32_16x16x32_bf16 v[20:23], v[212:215], v[184:187], v[20:23]
	v_mfma_f32_16x16x32_bf16 v[28:31], v[212:215], v[216:219], v[28:31]
	s_setprio 0
	s_setprio 1
	v_mfma_f32_16x16x32_bf16 v[32:35], v[232:235], v[164:167], v[134:137]
	v_mfma_f32_16x16x32_bf16 v[36:39], v[146:149], v[164:167], v[152:155]
	v_mfma_f32_16x16x32_bf16 v[40:43], v[232:235], v[172:175], v[156:159]
	v_mfma_f32_16x16x32_bf16 v[44:47], v[146:149], v[172:175], v[160:163]
	v_mfma_f32_16x16x32_bf16 v[48:51], v[232:235], v[180:183], v[204:207]
	v_mfma_f32_16x16x32_bf16 v[52:55], v[146:149], v[180:183], v[224:227]
	v_mfma_f32_16x16x32_bf16 v[56:59], v[232:235], v[188:191], v[128:131]
	v_mfma_f32_16x16x32_bf16 v[60:63], v[146:149], v[188:191], v[208:211]
	v_mfma_f32_16x16x32_bf16 v[32:35], v[236:239], v[168:171], v[32:35]
	v_mfma_f32_16x16x32_bf16 v[36:39], v[240:243], v[168:171], v[36:39]
	v_mfma_f32_16x16x32_bf16 v[40:43], v[236:239], v[176:179], v[40:43]
	v_mfma_f32_16x16x32_bf16 v[44:47], v[240:243], v[176:179], v[44:47]
	v_mfma_f32_16x16x32_bf16 v[48:51], v[236:239], v[184:187], v[48:51]
	v_mfma_f32_16x16x32_bf16 v[52:55], v[240:243], v[184:187], v[52:55]
	v_mfma_f32_16x16x32_bf16 v[56:59], v[236:239], v[216:219], v[56:59]
	v_mfma_f32_16x16x32_bf16 v[60:63], v[240:243], v[216:219], v[60:63]
	s_setprio 0
	s_cmp_lg_u32 s7, 0
	s_barrier
	s_cbranch_scc1 .LBB0_602
	s_barrier

; #define WAIT_V0() asm volatile("s_waitcnt vmcnt(0)" ::: "memory")
; template <int MT, class Epi>
; DEV void gemm_tile(char* shm, const u16* __restrict__ Ab, const u16* __restrict__ Bb, int K, int brow, int bcol, Epi& epi) {
;     ...
;   for (int t = 0; t < nt; ++t) {
;     const int cur = t & 1;
;     if (t + 1 < nt) GLDS_STAGE_(cur ^ 1, t + 1);
;     {
;       bf16x8 At[MT], Bf0[4], Bf1[4];
; #pragma unroll
;       for (int m = 0; m < MT; ++m) At[m] = *(const bf16x8*)(SA_(cur) + lds_byte<KS>(wr * (MT * 16) + m * 16 + fr, fq * 8));
; #pragma unroll
;       for (int n = 0; n < 4; ++n) Bf0[n] = *(const bf16x8*)(SB_(cur) + lds_byte<KS>(wc * 64 + n * 16 + fr, fq * 8));
; #pragma unroll
;       for (int n = 0; n < 4; ++n) Bf1[n] = *(const bf16x8*)(SB_(cur) + lds_byte<KS>(wc * 64 + n * 16 + fr, 32 + fq * 8));
;       __builtin_amdgcn_s_setprio(1);
; #pragma unroll
;       for (int m = 0; m < MT; ++m) {
; #pragma unroll
;         for (int n = 0; n < 4; ++n) acc[m][n] = __builtin_amdgcn_mfma_f32_16x16x32_bf16(Bf0[n], At[m], acc[m][n], 0, 0, 0);
;         At[m] = *(const bf16x8*)(SA_(cur) + lds_byte<KS>(wr * (MT * 16) + m * 16 + fr, 32 + fq * 8));
;       }
; #pragma unroll
;       for (int m = 0; m < MT; ++m)
; #pragma unroll
;         for (int n = 0; n < 4; ++n) acc[m][n] = __builtin_amdgcn_mfma_f32_16x16x32_bf16(Bf1[n], At[m], acc[m][n], 0, 0, 0);
;       __builtin_amdgcn_s_setprio(0);
;       __builtin_amdgcn_sched_barrier(0);
;     }
;     WAIT_V0();
;     __syncthreads();
.LBB0_863:
	v_add3_u32 v140, s12, v85, v87
	v_add3_u32 v143, s12, v89, v90
	v_add3_u32 v120, s12, v85, v84
	v_add_u32_e32 v136, s12, v86
	v_add3_u32 v142, s12, v89, v88
	ds_read_b128 v[92:95], v140
	ds_read_b128 v[96:99], v142
	v_add3_u32 v144, s12, v89, v91
	ds_read_b128 v[100:103], v143
	ds_read_b128 v[104:107], v144
	ds_read_b128 v[108:111], v120 offset:32768
	ds_read_b128 v[112:115], v120 offset:34816
	ds_read_b128 v[116:119], v120 offset:36864
	ds_read_b128 v[120:123], v120 offset:38912
	ds_read_b128 v[124:127], v136 offset:33792
	ds_read_b128 v[128:131], v136 offset:35840
	ds_read_b128 v[132:135], v136 offset:37888
	ds_read_b128 v[136:139], v136 offset:39936
	s_setprio 1
	s_waitcnt lgkmcnt(0)
	v_mfma_f32_16x16x32_bf16 v[20:23], v[108:111], v[92:95], v[20:23]
	v_mfma_f32_16x16x32_bf16 v[8:11], v[112:115], v[92:95], v[8:11]
	v_mfma_f32_16x16x32_bf16 v[4:7], v[116:119], v[92:95], v[4:7]
	v_mfma_f32_16x16x32_bf16 v[0:3], v[120:123], v[92:95], v[0:3]
	v_mfma_f32_16x16x32_bf16 v[12:15], v[108:111], v[96:99], v[12:15]
	v_mfma_f32_16x16x32_bf16 v[16:19], v[112:115], v[96:99], v[16:19]
	v_mfma_f32_16x16x32_bf16 v[24:27], v[116:119], v[96:99], v[24:27]
	v_mfma_f32_16x16x32_bf16 v[28:31], v[120:123], v[96:99], v[28:31]
	ds_read_b128 v[92:95], v140 offset:1024
	ds_read_b128 v[96:99], v142 offset:1024
	s_waitcnt lgkmcnt(1)
	v_mfma_f32_16x16x32_bf16 v[20:23], v[124:127], v[92:95], v[20:23]
	v_mfma_f32_16x16x32_bf16 v[8:11], v[128:131], v[92:95], v[8:11]
	v_mfma_f32_16x16x32_bf16 v[4:7], v[132:135], v[92:95], v[4:7]
	v_mfma_f32_16x16x32_bf16 v[0:3], v[136:139], v[92:95], v[0:3]
	s_waitcnt lgkmcnt(0)
	v_mfma_f32_16x16x32_bf16 v[12:15], v[124:127], v[96:99], v[12:15]
	v_mfma_f32_16x16x32_bf16 v[16:19], v[128:131], v[96:99], v[16:19]
	v_mfma_f32_16x16x32_bf16 v[24:27], v[132:135], v[96:99], v[24:27]
	v_mfma_f32_16x16x32_bf16 v[28:31], v[136:139], v[96:99], v[28:31]
	ds_read_b128 v[92:95], v143 offset:1024
	ds_read_b128 v[96:99], v144 offset:1024
	v_mfma_f32_16x16x32_bf16 v[32:35], v[108:111], v[100:103], v[32:35]
	v_mfma_f32_16x16x32_bf16 v[36:39], v[112:115], v[100:103], v[36:39]
	v_mfma_f32_16x16x32_bf16 v[40:43], v[116:119], v[100:103], v[40:43]
	v_mfma_f32_16x16x32_bf16 v[44:47], v[120:123], v[100:103], v[44:47]
	v_mfma_f32_16x16x32_bf16 v[48:51], v[108:111], v[104:107], v[48:51]
	v_mfma_f32_16x16x32_bf16 v[52:55], v[112:115], v[104:107], v[52:55]
	v_mfma_f32_16x16x32_bf16 v[56:59], v[116:119], v[104:107], v[56:59]
	v_mfma_f32_16x16x32_bf16 v[60:63], v[120:123], v[104:107], v[60:63]
	s_waitcnt lgkmcnt(1)
	v_mfma_f32_16x16x32_bf16 v[32:35], v[124:127], v[92:95], v[32:35]
	v_mfma_f32_16x16x32_bf16 v[36:39], v[128:131], v[92:95], v[36:39]
	v_mfma_f32_16x16x32_bf16 v[40:43], v[132:135], v[92:95], v[40:43]
	v_mfma_f32_16x16x32_bf16 v[44:47], v[136:139], v[92:95], v[44:47]
	s_waitcnt lgkmcnt(0)
	v_mfma_f32_16x16x32_bf16 v[48:51], v[124:127], v[96:99], v[48:51]
	v_mfma_f32_16x16x32_bf16 v[52:55], v[128:131], v[96:99], v[52:55]
	v_mfma_f32_16x16x32_bf16 v[56:59], v[132:135], v[96:99], v[56:59]
	v_mfma_f32_16x16x32_bf16 v[60:63], v[136:139], v[96:99], v[60:63]
	s_setprio 0
	s_add_i32 s7, s7, 0x10000
	s_waitcnt vmcnt(0)
	s_add_u32 s10, s10, 0x80
	s_addc_u32 s11, s11, 0
	s_cmpk_eq_i32 s10, 0x800
	s_barrier
	s_cbranch_scc1 .LBB0_866

; #define LDA8(dst, b, h)                                                                                               \
;   _Pragma("unroll") for (int m = 0; m < 4; ++m) _Pragma("unroll") for (int k = 0; k < 2; ++k)                         \
;     dst[m][k] = *(const bf16x8*)(SA8(b, h) + la + m * 2048 + k * 1024)
; #define LDB8(dst, b, h)                                                                                               \
;   _Pragma("unroll") for (int n = 0; n < 2; ++n) _Pragma("unroll") for (int k = 0; k < 2; ++k)                         \
;     dst[n][k] = *(const bf16x8*)(SB8(b, h) + lb + n * 2048 + k * 1024)
; #define WAITL8(n) asm volatile("s_waitcnt lgkmcnt(" #n ")" ::: "memory")
; #define BAR8 __builtin_amdgcn_s_barrier()
; #define SCHED8 __builtin_amdgcn_sched_barrier(0)
; template <class Epi>
; DEV void gemm_tile8(char* shm, const u16* __restrict__ A, const u16* __restrict__ Bt, int K, int brow, int bcol, Epi& epi) {
;     ...
;     LDB8(B0, 0, 0); SCHED8; LDA8(At, 0, 0); STAGE8(SA8(1, 1), A, brow + HALF, t + 1);
;     WAITL8(8); BAR8; WAITL8(0); MMA8(0, 0, At, B0); BAR8; SCHED8;
;     LDB8(B1, 0, 1); STAGE8(SB8(0, 0), Bt, bcol, t + 2);
;     BAR8; WAITL8(0); MMA8(0, 1, At, B1); BAR8;
;     LDA8(At, 0, 1); STAGE8(SA8(0, 0), A, brow, t + 2);
;     BAR8; WAITL8(0); MMA8(1, 0, At, B0); BAR8; SCHED8;
.LBB0_907:
	v_or_b32_e32 v134, 0x10000, v133
	v_add_u32_e32 v136, 0x10800, v133
	v_add_u32_e32 v135, 0x10400, v133
	ds_read_b128 v[144:147], v134
	ds_read_b128 v[148:151], v135
	v_add_u32_e32 v137, 0x10c00, v133
	ds_read_b128 v[152:155], v136
	ds_read_b128 v[156:159], v137
	v_lshl_add_u64 v[188:189], s[10:11], 0, v[130:131]
	s_mov_b64 s[90:91], 0x40080
	v_lshl_add_u64 v[138:139], v[188:189], 0, s[90:91]
	s_add_i32 s91, s13, 0xc000
	s_mov_b32 m0, s91
	s_mov_b64 s[92:93], 0x60080
	s_add_i32 s90, s13, 0xe000
	ds_read_b128 v[160:163], v132
	ds_read_b128 v[164:167], v132 offset:1024
	ds_read_b128 v[168:171], v132 offset:2048
	ds_read_b128 v[172:175], v132 offset:3072
	ds_read_b128 v[176:179], v132 offset:4096
	ds_read_b128 v[180:183], v132 offset:5120
	ds_read_b128 v[184:187], v132 offset:6144
	ds_read_b128 v[204:207], v132 offset:7168
	global_load_lds_dwordx4 v[138:139], off
	v_lshl_add_u64 v[138:139], v[188:189], 0, s[92:93]
	s_mov_b32 m0, s90
	s_nop 0
	global_load_lds_dwordx4 v[138:139], off
	s_waitcnt lgkmcnt(8)
	s_barrier
	s_waitcnt lgkmcnt(0)
	s_setprio 1
	s_waitcnt lgkmcnt(0)
	v_mfma_f32_16x16x32_bf16 v[124:127], v[144:147], v[160:163], v[124:127]
	v_mfma_f32_16x16x32_bf16 v[120:123], v[152:155], v[160:163], v[120:123]
	v_mfma_f32_16x16x32_bf16 v[116:119], v[144:147], v[168:171], v[116:119]
	v_mfma_f32_16x16x32_bf16 v[112:115], v[152:155], v[168:171], v[112:115]
	v_mfma_f32_16x16x32_bf16 v[108:111], v[144:147], v[176:179], v[108:111]
	v_mfma_f32_16x16x32_bf16 v[104:107], v[152:155], v[176:179], v[104:107]
	v_mfma_f32_16x16x32_bf16 v[100:103], v[144:147], v[184:187], v[100:103]
	v_mfma_f32_16x16x32_bf16 v[96:99], v[152:155], v[184:187], v[96:99]
	v_mfma_f32_16x16x32_bf16 v[124:127], v[148:151], v[164:167], v[124:127]
	v_mfma_f32_16x16x32_bf16 v[120:123], v[156:159], v[164:167], v[120:123]
	v_mfma_f32_16x16x32_bf16 v[116:119], v[148:151], v[172:175], v[116:119]
	v_mfma_f32_16x16x32_bf16 v[112:115], v[156:159], v[172:175], v[112:115]
	v_mfma_f32_16x16x32_bf16 v[108:111], v[148:151], v[180:183], v[108:111]
	v_mfma_f32_16x16x32_bf16 v[104:107], v[156:159], v[180:183], v[104:107]
	v_mfma_f32_16x16x32_bf16 v[100:103], v[148:151], v[204:207], v[100:103]
	v_mfma_f32_16x16x32_bf16 v[96:99], v[156:159], v[204:207], v[96:99]
	s_setprio 0
	s_barrier
	v_lshl_add_u64 v[190:191], s[6:7], 0, v[130:131]
	s_mov_b32 m0, s14
	v_or_b32_e32 v138, 0x14000, v133
	v_add_u32_e32 v140, 0x14800, v133
	v_lshl_add_u64 v[224:225], v[190:191], 0, s[4:5]
	v_add_u32_e32 v139, 0x14400, v133
	ds_read_b128 v[208:211], v138
	ds_read_b128 v[212:215], v139
	v_add_u32_e32 v142, 0x14c00, v133
	ds_read_b128 v[216:219], v140
	ds_read_b128 v[220:223], v142
	global_load_lds_dwordx4 v[224:225], off
	v_lshl_add_u64 v[224:225], v[190:191], 0, s[60:61]
	s_mov_b32 m0, s15
	s_nop 0
	global_load_lds_dwordx4 v[224:225], off
	s_barrier
	s_waitcnt lgkmcnt(0)
	s_setprio 1
	s_waitcnt lgkmcnt(0)
	v_mfma_f32_16x16x32_bf16 v[92:95], v[208:211], v[160:163], v[92:95]
	v_mfma_f32_16x16x32_bf16 v[88:91], v[216:219], v[160:163], v[88:91]
	v_mfma_f32_16x16x32_bf16 v[84:87], v[208:211], v[168:171], v[84:87]
	v_mfma_f32_16x16x32_bf16 v[80:83], v[216:219], v[168:171], v[80:83]
	v_mfma_f32_16x16x32_bf16 v[76:79], v[208:211], v[176:179], v[76:79]
	v_mfma_f32_16x16x32_bf16 v[72:75], v[216:219], v[176:179], v[72:75]
	v_mfma_f32_16x16x32_bf16 v[68:71], v[208:211], v[184:187], v[68:71]
	v_mfma_f32_16x16x32_bf16 v[64:67], v[216:219], v[184:187], v[64:67]
	v_mfma_f32_16x16x32_bf16 v[92:95], v[212:215], v[164:167], v[92:95]
	v_mfma_f32_16x16x32_bf16 v[88:91], v[220:223], v[164:167], v[88:91]
	v_mfma_f32_16x16x32_bf16 v[84:87], v[212:215], v[172:175], v[84:87]
	v_mfma_f32_16x16x32_bf16 v[80:83], v[220:223], v[172:175], v[80:83]
	v_mfma_f32_16x16x32_bf16 v[76:79], v[212:215], v[180:183], v[76:79]
	v_mfma_f32_16x16x32_bf16 v[72:75], v[220:223], v[180:183], v[72:75]
	v_mfma_f32_16x16x32_bf16 v[68:71], v[212:215], v[204:207], v[68:71]
	v_mfma_f32_16x16x32_bf16 v[64:67], v[220:223], v[204:207], v[64:67]
	s_setprio 0
	s_mov_b32 m0, s13
	v_lshl_add_u64 v[224:225], v[188:189], 0, s[4:5]
	s_barrier
	ds_read_b128 v[160:163], v132 offset:16384
	ds_read_b128 v[164:167], v132 offset:17408
	ds_read_b128 v[168:171], v132 offset:18432
	ds_read_b128 v[172:175], v132 offset:19456
	ds_read_b128 v[176:179], v132 offset:20480
	ds_read_b128 v[180:183], v132 offset:21504
	ds_read_b128 v[184:187], v132 offset:22528
	ds_read_b128 v[204:207], v132 offset:23552
	global_load_lds_dwordx4 v[224:225], off
	v_lshl_add_u64 v[224:225], v[188:189], 0, s[60:61]
	s_mov_b32 m0, s16
	s_nop 0
	global_load_lds_dwordx4 v[224:225], off
	s_barrier
	s_waitcnt lgkmcnt(0)
	s_setprio 1
	s_waitcnt lgkmcnt(0)
	v_mfma_f32_16x16x32_bf16 v[60:63], v[144:147], v[160:163], v[60:63]
	v_mfma_f32_16x16x32_bf16 v[56:59], v[152:155], v[160:163], v[56:59]
	v_mfma_f32_16x16x32_bf16 v[52:55], v[144:147], v[168:171], v[52:55]
	v_mfma_f32_16x16x32_bf16 v[48:51], v[152:155], v[168:171], v[48:51]
	v_mfma_f32_16x16x32_bf16 v[44:47], v[144:147], v[176:179], v[44:47]
	v_mfma_f32_16x16x32_bf16 v[40:43], v[152:155], v[176:179], v[40:43]
	v_mfma_f32_16x16x32_bf16 v[36:39], v[144:147], v[184:187], v[36:39]
	v_mfma_f32_16x16x32_bf16 v[32:35], v[152:155], v[184:187], v[32:35]
	v_mfma_f32_16x16x32_bf16 v[60:63], v[148:151], v[164:167], v[60:63]
	v_mfma_f32_16x16x32_bf16 v[56:59], v[156:159], v[164:167], v[56:59]
	v_mfma_f32_16x16x32_bf16 v[52:55], v[148:151], v[172:175], v[52:55]
	v_mfma_f32_16x16x32_bf16 v[48:51], v[156:159], v[172:175], v[48:51]
	v_mfma_f32_16x16x32_bf16 v[44:47], v[148:151], v[180:183], v[44:47]
	v_mfma_f32_16x16x32_bf16 v[40:43], v[156:159], v[180:183], v[40:43]
	v_mfma_f32_16x16x32_bf16 v[36:39], v[148:151], v[204:207], v[36:39]
	v_mfma_f32_16x16x32_bf16 v[32:35], v[156:159], v[204:207], v[32:35]
	s_setprio 0
	s_barrier
; #define LDA8(dst, b, h)                                                                                               \
;   _Pragma("unroll") for (int m = 0; m < 4; ++m) _Pragma("unroll") for (int k = 0; k < 2; ++k)                         \
;     dst[m][k] = *(const bf16x8*)(SA8(b, h) + la + m * 2048 + k * 1024)
; #define LDB8(dst, b, h)                                                                                               \
;   _Pragma("unroll") for (int n = 0; n < 2; ++n) _Pragma("unroll") for (int k = 0; k < 2; ++k)                         \
;     dst[n][k] = *(const bf16x8*)(SB8(b, h) + lb + n * 2048 + k * 1024)
; #define WAITV8(n) asm volatile("s_waitcnt vmcnt(" #n ")" ::: "memory")
; #define WAITL8(n) asm volatile("s_waitcnt lgkmcnt(" #n ")" ::: "memory")
; #define BAR8 __builtin_amdgcn_s_barrier()
; #define SCHED8 __builtin_amdgcn_sched_barrier(0)
; template <class Epi>
; DEV void gemm_tile8(char* shm, const u16* __restrict__ A, const u16* __restrict__ Bt, int K, int brow, int bcol, Epi& epi) {
;     ...
;     STAGE8(SB8(0, 1), Bt, bcol + HALF, t + 2);
;     WAITV8(6); BAR8; MMA8(1, 1, At, B1); BAR8;
;     LDB8(B0, 1, 0); SCHED8; LDA8(At, 1, 0); STAGE8(SA8(0, 1), A, brow + HALF, t + 2);
;     WAITL8(8); BAR8; WAITL8(0); MMA8(0, 0, At, B0); BAR8; SCHED8;
;     LDB8(B1, 1, 1); STAGE8(SB8(1, 0), Bt, bcol, t + 3);
;     BAR8; WAITL8(0); MMA8(0, 1, At, B1); BAR8;
;     LDA8(At, 1, 1); STAGE8(SA8(1, 0), A, brow, t + 3);
	s_mov_b32 m0, s17
	v_lshl_add_u64 v[144:145], v[190:191], 0, s[76:77]
	global_load_lds_dwordx4 v[144:145], off
	v_lshl_add_u64 v[144:145], v[190:191], 0, s[46:47]
	s_mov_b32 m0, s23
	s_nop 0
	global_load_lds_dwordx4 v[144:145], off
	s_waitcnt vmcnt(6)
	s_barrier
	s_setprio 1
	v_mfma_f32_16x16x32_bf16 v[28:31], v[208:211], v[160:163], v[28:31]
	v_mfma_f32_16x16x32_bf16 v[24:27], v[216:219], v[160:163], v[24:27]
	v_mfma_f32_16x16x32_bf16 v[20:23], v[208:211], v[168:171], v[20:23]
	v_mfma_f32_16x16x32_bf16 v[16:19], v[216:219], v[168:171], v[16:19]
	v_mfma_f32_16x16x32_bf16 v[12:15], v[208:211], v[176:179], v[12:15]
	v_mfma_f32_16x16x32_bf16 v[8:11], v[216:219], v[176:179], v[8:11]
	v_mfma_f32_16x16x32_bf16 v[4:7], v[208:211], v[184:187], v[4:7]
	v_mfma_f32_16x16x32_bf16 v[0:3], v[216:219], v[184:187], v[0:3]
	v_mfma_f32_16x16x32_bf16 v[28:31], v[212:215], v[164:167], v[28:31]
	v_mfma_f32_16x16x32_bf16 v[24:27], v[220:223], v[164:167], v[24:27]
	v_mfma_f32_16x16x32_bf16 v[20:23], v[212:215], v[172:175], v[20:23]
	v_mfma_f32_16x16x32_bf16 v[16:19], v[220:223], v[172:175], v[16:19]
	v_mfma_f32_16x16x32_bf16 v[12:15], v[212:215], v[180:183], v[12:15]
	v_mfma_f32_16x16x32_bf16 v[8:11], v[220:223], v[180:183], v[8:11]
	v_mfma_f32_16x16x32_bf16 v[4:7], v[212:215], v[204:207], v[4:7]
	v_mfma_f32_16x16x32_bf16 v[0:3], v[220:223], v[204:207], v[0:3]
	s_setprio 0
	v_or_b32_e32 v143, 0x18000, v133
	v_add_u32_e32 v145, 0x18800, v133
	s_barrier
	v_add_u32_e32 v144, 0x18400, v133
	ds_read_b128 v[152:155], v143
	ds_read_b128 v[156:159], v144
	v_add_u32_e32 v146, 0x18c00, v133
	ds_read_b128 v[160:163], v145
	ds_read_b128 v[164:167], v146
	s_mov_b32 m0, s27
	v_lshl_add_u64 v[148:149], v[188:189], 0, s[76:77]
	ds_read_b128 v[168:171], v132 offset:32768
	ds_read_b128 v[172:175], v132 offset:33792
	ds_read_b128 v[176:179], v132 offset:34816
	ds_read_b128 v[180:183], v132 offset:35840
	ds_read_b128 v[184:187], v132 offset:36864
	ds_read_b128 v[204:207], v132 offset:37888
	ds_read_b128 v[208:211], v132 offset:38912
	ds_read_b128 v[212:215], v132 offset:39936
	global_load_lds_dwordx4 v[148:149], off
	v_lshl_add_u64 v[148:149], v[188:189], 0, s[46:47]
	s_mov_b32 m0, s44
	s_nop 0
	global_load_lds_dwordx4 v[148:149], off
	s_waitcnt lgkmcnt(8)
	s_barrier
	s_waitcnt lgkmcnt(0)
	s_setprio 1
	s_waitcnt lgkmcnt(0)
	v_mfma_f32_16x16x32_bf16 v[124:127], v[152:155], v[168:171], v[124:127]
	v_mfma_f32_16x16x32_bf16 v[120:123], v[160:163], v[168:171], v[120:123]
	v_mfma_f32_16x16x32_bf16 v[116:119], v[152:155], v[176:179], v[116:119]
	v_mfma_f32_16x16x32_bf16 v[112:115], v[160:163], v[176:179], v[112:115]
	v_mfma_f32_16x16x32_bf16 v[108:111], v[152:155], v[184:187], v[108:111]
	v_mfma_f32_16x16x32_bf16 v[104:107], v[160:163], v[184:187], v[104:107]
	v_mfma_f32_16x16x32_bf16 v[100:103], v[152:155], v[208:211], v[100:103]
	v_mfma_f32_16x16x32_bf16 v[96:99], v[160:163], v[208:211], v[96:99]
	v_mfma_f32_16x16x32_bf16 v[124:127], v[156:159], v[172:175], v[124:127]
	v_mfma_f32_16x16x32_bf16 v[120:123], v[164:167], v[172:175], v[120:123]
	v_mfma_f32_16x16x32_bf16 v[116:119], v[156:159], v[180:183], v[116:119]
	v_mfma_f32_16x16x32_bf16 v[112:115], v[164:167], v[180:183], v[112:115]
	v_mfma_f32_16x16x32_bf16 v[108:111], v[156:159], v[204:207], v[108:111]
	v_mfma_f32_16x16x32_bf16 v[104:107], v[164:167], v[204:207], v[104:107]
	v_mfma_f32_16x16x32_bf16 v[100:103], v[156:159], v[212:215], v[100:103]
	v_mfma_f32_16x16x32_bf16 v[96:99], v[164:167], v[212:215], v[96:99]
	s_setprio 0
	s_barrier
	s_mov_b32 m0, s45
	v_or_b32_e32 v147, 0x1c000, v133
	v_add_u32_e32 v149, 0x1c800, v133
	v_lshl_add_u64 v[232:233], v[190:191], 0, s[56:57]
	v_add_u32_e32 v148, 0x1c400, v133
	ds_read_b128 v[216:219], v147
	ds_read_b128 v[220:223], v148
	v_add_u32_e32 v150, 0x1cc00, v133
	ds_read_b128 v[224:227], v149
	ds_read_b128 v[228:231], v150
	global_load_lds_dwordx4 v[232:233], off
	v_lshl_add_u64 v[232:233], v[190:191], 0, s[68:69]
	s_mov_b32 m0, s54
	s_nop 0
	global_load_lds_dwordx4 v[232:233], off
	s_barrier
	s_waitcnt lgkmcnt(0)
	s_setprio 1
	s_waitcnt lgkmcnt(0)
	v_mfma_f32_16x16x32_bf16 v[92:95], v[216:219], v[168:171], v[92:95]
	v_mfma_f32_16x16x32_bf16 v[88:91], v[224:227], v[168:171], v[88:91]
	v_mfma_f32_16x16x32_bf16 v[84:87], v[216:219], v[176:179], v[84:87]
	v_mfma_f32_16x16x32_bf16 v[80:83], v[224:227], v[176:179], v[80:83]
	v_mfma_f32_16x16x32_bf16 v[76:79], v[216:219], v[184:187], v[76:79]
	v_mfma_f32_16x16x32_bf16 v[72:75], v[224:227], v[184:187], v[72:75]
	v_mfma_f32_16x16x32_bf16 v[68:71], v[216:219], v[208:211], v[68:71]
	v_mfma_f32_16x16x32_bf16 v[64:67], v[224:227], v[208:211], v[64:67]
	v_mfma_f32_16x16x32_bf16 v[92:95], v[220:223], v[172:175], v[92:95]
	v_mfma_f32_16x16x32_bf16 v[88:91], v[228:231], v[172:175], v[88:91]
	v_mfma_f32_16x16x32_bf16 v[84:87], v[220:223], v[180:183], v[84:87]
	v_mfma_f32_16x16x32_bf16 v[80:83], v[228:231], v[180:183], v[80:83]
	v_mfma_f32_16x16x32_bf16 v[76:79], v[220:223], v[204:207], v[76:79]
	v_mfma_f32_16x16x32_bf16 v[72:75], v[228:231], v[204:207], v[72:75]
	v_mfma_f32_16x16x32_bf16 v[68:71], v[220:223], v[212:215], v[68:71]
	v_mfma_f32_16x16x32_bf16 v[64:67], v[228:231], v[212:215], v[64:67]
	s_setprio 0
	s_mov_b32 m0, s55
	v_lshl_add_u64 v[232:233], v[188:189], 0, s[56:57]
	s_barrier
	ds_read_b128 v[168:171], v132 offset:49152
	ds_read_b128 v[172:175], v132 offset:50176
	ds_read_b128 v[176:179], v132 offset:51200
	ds_read_b128 v[180:183], v132 offset:52224
	ds_read_b128 v[184:187], v132 offset:53248
	ds_read_b128 v[204:207], v132 offset:54272
	ds_read_b128 v[208:211], v132 offset:55296
	ds_read_b128 v[212:215], v132 offset:56320
	global_load_lds_dwordx4 v[232:233], off
	v_lshl_add_u64 v[188:189], v[188:189], 0, s[68:69]
	s_mov_b32 m0, s70
	s_nop 0
	global_load_lds_dwordx4 v[188:189], off
	s_barrier
; #define LDA8(dst, b, h)                                                                                               \
;   _Pragma("unroll") for (int m = 0; m < 4; ++m) _Pragma("unroll") for (int k = 0; k < 2; ++k)                         \
;     dst[m][k] = *(const bf16x8*)(SA8(b, h) + la + m * 2048 + k * 1024)
; #define LDB8(dst, b, h)                                                                                               \
;   _Pragma("unroll") for (int n = 0; n < 2; ++n) _Pragma("unroll") for (int k = 0; k < 2; ++k)                         \
;     dst[n][k] = *(const bf16x8*)(SB8(b, h) + lb + n * 2048 + k * 1024)
; #define WAITV8(n) asm volatile("s_waitcnt vmcnt(" #n ")" ::: "memory")
; #define WAITL8(n) asm volatile("s_waitcnt lgkmcnt(" #n ")" ::: "memory")
; #define BAR8 __builtin_amdgcn_s_barrier()
; #define SCHED8 __builtin_amdgcn_sched_barrier(0)
; template <class Epi>
; DEV void gemm_tile8(char* shm, const u16* __restrict__ A, const u16* __restrict__ Bt, int K, int brow, int bcol, Epi& epi) {
;     ...
;     LDA8(At, 1, 1); STAGE8(SA8(1, 0), A, brow, t + 3);
;     BAR8; WAITL8(0); MMA8(1, 0, At, B0); BAR8; SCHED8;
;     STAGE8(SB8(1, 1), Bt, bcol + HALF, t + 3);
;     WAITV8(6); BAR8; MMA8(1, 1, At, B1); BAR8;
;   }
;   { LDB8(B0, 0, 0); LDA8(At, 0, 0); STAGE8(SA8(1, 1), A, brow + HALF, nt - 1);
;     BAR8; WAITL8(0); MMA8(0, 0, At, B0); BAR8;
;     LDB8(B1, 0, 1); BAR8; WAITL8(0); MMA8(0, 1, At, B1); BAR8;
	s_waitcnt lgkmcnt(0)
	s_setprio 1
	s_waitcnt lgkmcnt(0)
	v_mfma_f32_16x16x32_bf16 v[60:63], v[152:155], v[168:171], v[60:63]
	v_mfma_f32_16x16x32_bf16 v[56:59], v[160:163], v[168:171], v[56:59]
	v_mfma_f32_16x16x32_bf16 v[52:55], v[152:155], v[176:179], v[52:55]
	v_mfma_f32_16x16x32_bf16 v[48:51], v[160:163], v[176:179], v[48:51]
	v_mfma_f32_16x16x32_bf16 v[44:47], v[152:155], v[184:187], v[44:47]
	v_mfma_f32_16x16x32_bf16 v[40:43], v[160:163], v[184:187], v[40:43]
	v_mfma_f32_16x16x32_bf16 v[36:39], v[152:155], v[208:211], v[36:39]
	v_mfma_f32_16x16x32_bf16 v[32:35], v[160:163], v[208:211], v[32:35]
	v_mfma_f32_16x16x32_bf16 v[60:63], v[156:159], v[172:175], v[60:63]
	v_mfma_f32_16x16x32_bf16 v[56:59], v[164:167], v[172:175], v[56:59]
	v_mfma_f32_16x16x32_bf16 v[52:55], v[156:159], v[180:183], v[52:55]
	v_mfma_f32_16x16x32_bf16 v[48:51], v[164:167], v[180:183], v[48:51]
	v_mfma_f32_16x16x32_bf16 v[44:47], v[156:159], v[204:207], v[44:47]
	v_mfma_f32_16x16x32_bf16 v[40:43], v[164:167], v[204:207], v[40:43]
	v_mfma_f32_16x16x32_bf16 v[36:39], v[156:159], v[212:215], v[36:39]
	v_mfma_f32_16x16x32_bf16 v[32:35], v[164:167], v[212:215], v[32:35]
	s_setprio 0
	s_barrier
	s_mov_b64 s[92:93], 0x40180
	s_mov_b32 m0, s71
	v_lshl_add_u64 v[152:153], v[190:191], 0, s[92:93]
	s_mov_b64 s[92:93], 0x60180
	global_load_lds_dwordx4 v[152:153], off
	v_lshl_add_u64 v[152:153], v[190:191], 0, s[92:93]
	s_mov_b32 m0, s72
	s_nop 0
	global_load_lds_dwordx4 v[152:153], off
	s_waitcnt vmcnt(6)
	s_barrier
	s_setprio 1
	v_mfma_f32_16x16x32_bf16 v[28:31], v[216:219], v[168:171], v[28:31]
	v_mfma_f32_16x16x32_bf16 v[24:27], v[224:227], v[168:171], v[24:27]
	v_mfma_f32_16x16x32_bf16 v[20:23], v[216:219], v[176:179], v[20:23]
	v_mfma_f32_16x16x32_bf16 v[16:19], v[224:227], v[176:179], v[16:19]
	v_mfma_f32_16x16x32_bf16 v[12:15], v[216:219], v[184:187], v[12:15]
	v_mfma_f32_16x16x32_bf16 v[8:11], v[224:227], v[184:187], v[8:11]
	v_mfma_f32_16x16x32_bf16 v[4:7], v[216:219], v[208:211], v[4:7]
	v_mfma_f32_16x16x32_bf16 v[0:3], v[224:227], v[208:211], v[0:3]
	v_mfma_f32_16x16x32_bf16 v[28:31], v[220:223], v[172:175], v[28:31]
	v_mfma_f32_16x16x32_bf16 v[24:27], v[228:231], v[172:175], v[24:27]
	v_mfma_f32_16x16x32_bf16 v[20:23], v[220:223], v[180:183], v[20:23]
	v_mfma_f32_16x16x32_bf16 v[16:19], v[228:231], v[180:183], v[16:19]
	v_mfma_f32_16x16x32_bf16 v[12:15], v[220:223], v[204:207], v[12:15]
	v_mfma_f32_16x16x32_bf16 v[8:11], v[228:231], v[204:207], v[8:11]
	v_mfma_f32_16x16x32_bf16 v[4:7], v[220:223], v[212:215], v[4:7]
	v_mfma_f32_16x16x32_bf16 v[0:3], v[228:231], v[212:215], v[0:3]
	s_setprio 0
	s_add_i32 s73, s73, 2
	s_add_u32 s10, s10, 0x100
	s_addc_u32 s11, s11, 0
	s_add_u32 s6, s6, 0x100
	s_addc_u32 s7, s7, 0
	s_cmp_lt_u32 s73, 12
	s_barrier
	s_cbranch_scc1 .LBB0_907
	s_mov_b64 s[6:7], 0x780
	s_mov_b32 m0, s91
	v_lshl_add_u64 v[130:131], v[128:129], 0, s[6:7]
	s_mov_b64 s[6:7], 0x20780
	ds_read_b128 v[152:155], v134
	ds_read_b128 v[156:159], v135
	ds_read_b128 v[160:163], v136
	ds_read_b128 v[134:137], v137
	ds_read_b128 v[164:167], v132
	ds_read_b128 v[168:171], v132 offset:1024
	ds_read_b128 v[172:175], v132 offset:2048
	ds_read_b128 v[176:179], v132 offset:3072
	ds_read_b128 v[180:183], v132 offset:4096
	ds_read_b128 v[184:187], v132 offset:5120
	ds_read_b128 v[204:207], v132 offset:6144
	ds_read_b128 v[208:211], v132 offset:7168
	global_load_lds_dwordx4 v[130:131], off
	v_lshl_add_u64 v[128:129], v[128:129], 0, s[6:7]
	s_mov_b32 m0, s90
	s_nop 0
	global_load_lds_dwordx4 v[128:129], off
	s_barrier
	s_waitcnt lgkmcnt(0)
	s_setprio 1
	s_waitcnt lgkmcnt(0)
	v_mfma_f32_16x16x32_bf16 v[124:127], v[152:155], v[164:167], v[124:127]
	v_mfma_f32_16x16x32_bf16 v[120:123], v[160:163], v[164:167], v[120:123]
	v_mfma_f32_16x16x32_bf16 v[116:119], v[152:155], v[172:175], v[116:119]
	v_mfma_f32_16x16x32_bf16 v[112:115], v[160:163], v[172:175], v[112:115]
	v_mfma_f32_16x16x32_bf16 v[108:111], v[152:155], v[180:183], v[108:111]
	v_mfma_f32_16x16x32_bf16 v[104:107], v[160:163], v[180:183], v[104:107]
	v_mfma_f32_16x16x32_bf16 v[100:103], v[152:155], v[204:207], v[100:103]
	v_mfma_f32_16x16x32_bf16 v[96:99], v[160:163], v[204:207], v[96:99]
	v_mfma_f32_16x16x32_bf16 v[124:127], v[156:159], v[168:171], v[124:127]
	v_mfma_f32_16x16x32_bf16 v[120:123], v[134:137], v[168:171], v[120:123]
	v_mfma_f32_16x16x32_bf16 v[116:119], v[156:159], v[176:179], v[116:119]
	v_mfma_f32_16x16x32_bf16 v[112:115], v[134:137], v[176:179], v[112:115]
	v_mfma_f32_16x16x32_bf16 v[108:111], v[156:159], v[184:187], v[108:111]
	v_mfma_f32_16x16x32_bf16 v[104:107], v[134:137], v[184:187], v[104:107]
	v_mfma_f32_16x16x32_bf16 v[100:103], v[156:159], v[208:211], v[100:103]
	v_mfma_f32_16x16x32_bf16 v[96:99], v[134:137], v[208:211], v[96:99]
	s_setprio 0
	s_barrier
	ds_read_b128 v[128:131], v138
	ds_read_b128 v[212:215], v139
	ds_read_b128 v[216:219], v140
	ds_read_b128 v[220:223], v142
	s_barrier
	s_waitcnt lgkmcnt(0)
	s_setprio 1
	s_waitcnt lgkmcnt(3)
	v_mfma_f32_16x16x32_bf16 v[92:95], v[128:131], v[164:167], v[92:95]
	s_waitcnt lgkmcnt(1)
	v_mfma_f32_16x16x32_bf16 v[88:91], v[216:219], v[164:167], v[88:91]
	v_mfma_f32_16x16x32_bf16 v[84:87], v[128:131], v[172:175], v[84:87]
	v_mfma_f32_16x16x32_bf16 v[80:83], v[216:219], v[172:175], v[80:83]
	v_mfma_f32_16x16x32_bf16 v[76:79], v[128:131], v[180:183], v[76:79]
	v_mfma_f32_16x16x32_bf16 v[72:75], v[216:219], v[180:183], v[72:75]
	v_mfma_f32_16x16x32_bf16 v[68:71], v[128:131], v[204:207], v[68:71]
	v_mfma_f32_16x16x32_bf16 v[64:67], v[216:219], v[204:207], v[64:67]
	v_mfma_f32_16x16x32_bf16 v[224:227], v[212:215], v[168:171], v[92:95]
	s_waitcnt lgkmcnt(0)
	v_mfma_f32_16x16x32_bf16 v[164:167], v[220:223], v[168:171], v[88:91]
	v_mfma_f32_16x16x32_bf16 v[168:171], v[212:215], v[176:179], v[84:87]
	v_mfma_f32_16x16x32_bf16 v[172:175], v[220:223], v[176:179], v[80:83]
	v_mfma_f32_16x16x32_bf16 v[176:179], v[212:215], v[184:187], v[76:79]
	v_mfma_f32_16x16x32_bf16 v[180:183], v[220:223], v[184:187], v[72:75]
	v_mfma_f32_16x16x32_bf16 v[184:187], v[212:215], v[208:211], v[68:71]
	v_mfma_f32_16x16x32_bf16 v[204:207], v[220:223], v[208:211], v[64:67]
	s_setprio 0
	s_barrier
; #define LDA8(dst, b, h)                                                                                               \
;   _Pragma("unroll") for (int m = 0; m < 4; ++m) _Pragma("unroll") for (int k = 0; k < 2; ++k)                         \
;     dst[m][k] = *(const bf16x8*)(SA8(b, h) + la + m * 2048 + k * 1024)
; #define LDB8(dst, b, h)                                                                                               \
;   _Pragma("unroll") for (int n = 0; n < 2; ++n) _Pragma("unroll") for (int k = 0; k < 2; ++k)                         \
;     dst[n][k] = *(const bf16x8*)(SB8(b, h) + lb + n * 2048 + k * 1024)
; #define WAITV8(n) asm volatile("s_waitcnt vmcnt(" #n ")" ::: "memory")
; #define WAITL8(n) asm volatile("s_waitcnt lgkmcnt(" #n ")" ::: "memory")
; #define BAR8 __builtin_amdgcn_s_barrier()
; template <class Epi>
; DEV void gemm_tile8(char* shm, const u16* __restrict__ A, const u16* __restrict__ Bt, int K, int brow, int bcol, Epi& epi) {
;     ...
;     LDA8(At, 0, 1); WAITV8(4); BAR8; WAITL8(0); MMA8(1, 0, At, B0); MMA8(1, 1, At, B1); BAR8; }
;   { LDB8(B0, 1, 0); LDA8(At, 1, 0); WAITV8(2); BAR8; WAITL8(0); MMA8(0, 0, At, B0); BAR8;
	s_nop 0
	ds_read_b128 v[64:67], v132 offset:16384
	ds_read_b128 v[68:71], v132 offset:17408
	ds_read_b128 v[72:75], v132 offset:18432
	ds_read_b128 v[76:79], v132 offset:19456
	ds_read_b128 v[80:83], v132 offset:20480
	ds_read_b128 v[84:87], v132 offset:21504
	ds_read_b128 v[88:91], v132 offset:22528
	ds_read_b128 v[92:95], v132 offset:23552
	s_waitcnt vmcnt(4)
	s_barrier
	s_waitcnt lgkmcnt(0)
	s_setprio 1
	s_waitcnt lgkmcnt(7)
	v_mfma_f32_16x16x32_bf16 v[60:63], v[152:155], v[64:67], v[60:63]
	v_mfma_f32_16x16x32_bf16 v[56:59], v[160:163], v[64:67], v[56:59]
	s_waitcnt lgkmcnt(5)
	v_mfma_f32_16x16x32_bf16 v[52:55], v[152:155], v[72:75], v[52:55]
	v_mfma_f32_16x16x32_bf16 v[48:51], v[160:163], v[72:75], v[48:51]
	s_waitcnt lgkmcnt(3)
	v_mfma_f32_16x16x32_bf16 v[44:47], v[152:155], v[80:83], v[44:47]
	v_mfma_f32_16x16x32_bf16 v[40:43], v[160:163], v[80:83], v[40:43]
	s_waitcnt lgkmcnt(1)
	v_mfma_f32_16x16x32_bf16 v[36:39], v[152:155], v[88:91], v[36:39]
	v_mfma_f32_16x16x32_bf16 v[32:35], v[160:163], v[88:91], v[32:35]
	v_mfma_f32_16x16x32_bf16 v[60:63], v[156:159], v[68:71], v[60:63]
	v_mfma_f32_16x16x32_bf16 v[56:59], v[134:137], v[68:71], v[56:59]
	v_mfma_f32_16x16x32_bf16 v[52:55], v[156:159], v[76:79], v[52:55]
	v_mfma_f32_16x16x32_bf16 v[48:51], v[134:137], v[76:79], v[48:51]
	v_mfma_f32_16x16x32_bf16 v[44:47], v[156:159], v[84:87], v[44:47]
	v_mfma_f32_16x16x32_bf16 v[40:43], v[134:137], v[84:87], v[40:43]
	s_waitcnt lgkmcnt(0)
	v_mfma_f32_16x16x32_bf16 v[36:39], v[156:159], v[92:95], v[36:39]
	v_mfma_f32_16x16x32_bf16 v[32:35], v[134:137], v[92:95], v[32:35]
	s_setprio 0
	s_setprio 1
	v_mfma_f32_16x16x32_bf16 v[28:31], v[128:131], v[64:67], v[28:31]
	v_mfma_f32_16x16x32_bf16 v[24:27], v[216:219], v[64:67], v[24:27]
	v_mfma_f32_16x16x32_bf16 v[20:23], v[128:131], v[72:75], v[20:23]
	v_mfma_f32_16x16x32_bf16 v[16:19], v[216:219], v[72:75], v[16:19]
	v_mfma_f32_16x16x32_bf16 v[12:15], v[128:131], v[80:83], v[12:15]
	v_mfma_f32_16x16x32_bf16 v[8:11], v[216:219], v[80:83], v[8:11]
	v_mfma_f32_16x16x32_bf16 v[4:7], v[128:131], v[88:91], v[4:7]
	v_mfma_f32_16x16x32_bf16 v[0:3], v[216:219], v[88:91], v[0:3]
	v_mfma_f32_16x16x32_bf16 v[134:137], v[212:215], v[68:71], v[28:31]
	v_mfma_f32_16x16x32_bf16 v[152:155], v[220:223], v[68:71], v[24:27]
	v_mfma_f32_16x16x32_bf16 v[156:159], v[212:215], v[76:79], v[20:23]
	v_mfma_f32_16x16x32_bf16 v[160:163], v[220:223], v[76:79], v[16:19]
	v_mfma_f32_16x16x32_bf16 v[208:211], v[212:215], v[84:87], v[12:15]
	v_mfma_f32_16x16x32_bf16 v[228:231], v[220:223], v[84:87], v[8:11]
	v_mfma_f32_16x16x32_bf16 v[128:131], v[212:215], v[92:95], v[4:7]
	v_mfma_f32_16x16x32_bf16 v[212:215], v[220:223], v[92:95], v[0:3]
	s_setprio 0
	s_barrier
	ds_read_b128 v[24:27], v143
	ds_read_b128 v[28:31], v144
	ds_read_b128 v[142:145], v145
	ds_read_b128 v[216:219], v146
	ds_read_b128 v[0:3], v132 offset:32768
	ds_read_b128 v[4:7], v132 offset:33792
	ds_read_b128 v[8:11], v132 offset:34816
	ds_read_b128 v[12:15], v132 offset:35840
	ds_read_b128 v[16:19], v132 offset:36864
	ds_read_b128 v[20:23], v132 offset:37888
	ds_read_b128 v[220:223], v132 offset:38912
	ds_read_b128 v[232:235], v132 offset:39936
	s_waitcnt vmcnt(2)
	s_barrier
	s_waitcnt lgkmcnt(0)
	s_setprio 1
	s_waitcnt lgkmcnt(7)
	v_mfma_f32_16x16x32_bf16 v[64:67], v[24:27], v[0:3], v[124:127]
	s_waitcnt lgkmcnt(6)
	v_mfma_f32_16x16x32_bf16 v[72:75], v[28:31], v[4:7], v[64:67]
	v_mfma_f32_16x16x32_bf16 v[64:67], v[142:145], v[0:3], v[120:123]
	s_waitcnt lgkmcnt(5)
	v_mfma_f32_16x16x32_bf16 v[68:71], v[24:27], v[8:11], v[116:119]
	v_mfma_f32_16x16x32_bf16 v[76:79], v[142:145], v[8:11], v[112:115]
	s_waitcnt lgkmcnt(3)
	v_mfma_f32_16x16x32_bf16 v[80:83], v[24:27], v[16:19], v[108:111]
	v_mfma_f32_16x16x32_bf16 v[84:87], v[142:145], v[16:19], v[104:107]
	s_waitcnt lgkmcnt(1)
	v_mfma_f32_16x16x32_bf16 v[88:91], v[24:27], v[220:223], v[100:103]
	v_mfma_f32_16x16x32_bf16 v[92:95], v[142:145], v[220:223], v[96:99]
	v_mfma_f32_16x16x32_bf16 v[64:67], v[216:219], v[4:7], v[64:67]
	v_mfma_f32_16x16x32_bf16 v[68:71], v[28:31], v[12:15], v[68:71]
	v_mfma_f32_16x16x32_bf16 v[76:79], v[216:219], v[12:15], v[76:79]
	v_mfma_f32_16x16x32_bf16 v[80:83], v[28:31], v[20:23], v[80:83]
	v_mfma_f32_16x16x32_bf16 v[84:87], v[216:219], v[20:23], v[84:87]
	s_waitcnt lgkmcnt(0)
	v_mfma_f32_16x16x32_bf16 v[88:91], v[28:31], v[232:235], v[88:91]
	v_mfma_f32_16x16x32_bf16 v[92:95], v[216:219], v[232:235], v[92:95]
	s_setprio 0
	s_barrier
; #define LDA8(dst, b, h)                                                                                               \
;   _Pragma("unroll") for (int m = 0; m < 4; ++m) _Pragma("unroll") for (int k = 0; k < 2; ++k)                         \
;     dst[m][k] = *(const bf16x8*)(SA8(b, h) + la + m * 2048 + k * 1024)
; #define LDB8(dst, b, h)                                                                                               \
;   _Pragma("unroll") for (int n = 0; n < 2; ++n) _Pragma("unroll") for (int k = 0; k < 2; ++k)                         \
;     dst[n][k] = *(const bf16x8*)(SB8(b, h) + lb + n * 2048 + k * 1024)
; #define WAITV8(n) asm volatile("s_waitcnt vmcnt(" #n ")" ::: "memory")
; #define WAITL8(n) asm volatile("s_waitcnt lgkmcnt(" #n ")" ::: "memory")
; #define BAR8 __builtin_amdgcn_s_barrier()
; template <class Epi>
; DEV void gemm_tile8(char* shm, const u16* __restrict__ A, const u16* __restrict__ Bt, int K, int brow, int bcol, Epi& epi) {
;     ...
;     LDB8(B1, 1, 1); WAITV8(0); BAR8; WAITL8(0); MMA8(0, 1, At, B1); BAR8;
;     LDA8(At, 1, 1); BAR8; WAITL8(0); MMA8(1, 0, At, B0); MMA8(1, 1, At, B1); BAR8; }
;   if (wrs == 0) BAR8;
	ds_read_b128 v[236:239], v147
	ds_read_b128 v[240:243], v148
	ds_read_b128 v[146:149], v149
	ds_read_b128 v[244:247], v150
	s_waitcnt vmcnt(0)
	s_barrier
	s_waitcnt lgkmcnt(0)
	s_setprio 1
	s_waitcnt lgkmcnt(3)
	v_mfma_f32_16x16x32_bf16 v[96:99], v[236:239], v[0:3], v[224:227]
	s_waitcnt lgkmcnt(1)
	v_mfma_f32_16x16x32_bf16 v[0:3], v[146:149], v[0:3], v[164:167]
	v_mfma_f32_16x16x32_bf16 v[104:107], v[240:243], v[4:7], v[96:99]
	s_waitcnt lgkmcnt(0)
	v_mfma_f32_16x16x32_bf16 v[96:99], v[244:247], v[4:7], v[0:3]
	v_mfma_f32_16x16x32_bf16 v[0:3], v[236:239], v[8:11], v[168:171]
	v_mfma_f32_16x16x32_bf16 v[100:103], v[240:243], v[12:15], v[0:3]
	v_mfma_f32_16x16x32_bf16 v[0:3], v[146:149], v[8:11], v[172:175]
	v_mfma_f32_16x16x32_bf16 v[108:111], v[244:247], v[12:15], v[0:3]
	v_mfma_f32_16x16x32_bf16 v[0:3], v[236:239], v[16:19], v[176:179]
	v_mfma_f32_16x16x32_bf16 v[112:115], v[240:243], v[20:23], v[0:3]
	v_mfma_f32_16x16x32_bf16 v[0:3], v[146:149], v[16:19], v[180:183]
	v_mfma_f32_16x16x32_bf16 v[116:119], v[244:247], v[20:23], v[0:3]
	v_mfma_f32_16x16x32_bf16 v[0:3], v[236:239], v[220:223], v[184:187]
	v_mfma_f32_16x16x32_bf16 v[120:123], v[240:243], v[232:235], v[0:3]
	v_mfma_f32_16x16x32_bf16 v[0:3], v[146:149], v[220:223], v[204:207]
	v_mfma_f32_16x16x32_bf16 v[124:127], v[244:247], v[232:235], v[0:3]
	s_setprio 0
	s_barrier
	ds_read_b128 v[164:167], v132 offset:49152
	ds_read_b128 v[168:171], v132 offset:50176
	ds_read_b128 v[172:175], v132 offset:51200
	ds_read_b128 v[176:179], v132 offset:52224
	ds_read_b128 v[180:183], v132 offset:53248
	ds_read_b128 v[184:187], v132 offset:54272
	ds_read_b128 v[204:207], v132 offset:55296
	ds_read_b128 v[220:223], v132 offset:56320
	s_barrier
	s_waitcnt lgkmcnt(0)
	s_setprio 1
	s_waitcnt lgkmcnt(7)
	v_mfma_f32_16x16x32_bf16 v[0:3], v[24:27], v[164:167], v[60:63]
	s_waitcnt lgkmcnt(5)
	v_mfma_f32_16x16x32_bf16 v[8:11], v[24:27], v[172:175], v[52:55]
	s_waitcnt lgkmcnt(3)
	v_mfma_f32_16x16x32_bf16 v[16:19], v[24:27], v[180:183], v[44:47]
	s_waitcnt lgkmcnt(1)
	v_mfma_f32_16x16x32_bf16 v[24:27], v[24:27], v[204:207], v[36:39]
	v_mfma_f32_16x16x32_bf16 v[0:3], v[28:31], v[168:171], v[0:3]
	v_mfma_f32_16x16x32_bf16 v[4:7], v[142:145], v[164:167], v[56:59]
	v_mfma_f32_16x16x32_bf16 v[8:11], v[28:31], v[176:179], v[8:11]
	v_mfma_f32_16x16x32_bf16 v[12:15], v[142:145], v[172:175], v[48:51]
	v_mfma_f32_16x16x32_bf16 v[16:19], v[28:31], v[184:187], v[16:19]
	v_mfma_f32_16x16x32_bf16 v[20:23], v[142:145], v[180:183], v[40:43]
	s_waitcnt lgkmcnt(0)
	v_mfma_f32_16x16x32_bf16 v[24:27], v[28:31], v[220:223], v[24:27]
	v_mfma_f32_16x16x32_bf16 v[28:31], v[142:145], v[204:207], v[32:35]
	v_mfma_f32_16x16x32_bf16 v[4:7], v[216:219], v[168:171], v[4:7]
	v_mfma_f32_16x16x32_bf16 v[12:15], v[216:219], v[176:179], v[12:15]
	v_mfma_f32_16x16x32_bf16 v[20:23], v[216:219], v[184:187], v[20:23]
	v_mfma_f32_16x16x32_bf16 v[28:31], v[216:219], v[220:223], v[28:31]
	s_setprio 0
	s_setprio 1
	v_mfma_f32_16x16x32_bf16 v[32:35], v[236:239], v[164:167], v[134:137]
	v_mfma_f32_16x16x32_bf16 v[36:39], v[146:149], v[164:167], v[152:155]
	v_mfma_f32_16x16x32_bf16 v[40:43], v[236:239], v[172:175], v[156:159]
	v_mfma_f32_16x16x32_bf16 v[44:47], v[146:149], v[172:175], v[160:163]
	v_mfma_f32_16x16x32_bf16 v[48:51], v[236:239], v[180:183], v[208:211]
	v_mfma_f32_16x16x32_bf16 v[52:55], v[146:149], v[180:183], v[228:231]
	v_mfma_f32_16x16x32_bf16 v[56:59], v[236:239], v[204:207], v[128:131]
	v_mfma_f32_16x16x32_bf16 v[60:63], v[146:149], v[204:207], v[212:215]
	v_mfma_f32_16x16x32_bf16 v[32:35], v[240:243], v[168:171], v[32:35]
	v_mfma_f32_16x16x32_bf16 v[36:39], v[244:247], v[168:171], v[36:39]
	v_mfma_f32_16x16x32_bf16 v[40:43], v[240:243], v[176:179], v[40:43]
	v_mfma_f32_16x16x32_bf16 v[44:47], v[244:247], v[176:179], v[44:47]
	v_mfma_f32_16x16x32_bf16 v[48:51], v[240:243], v[184:187], v[48:51]
	v_mfma_f32_16x16x32_bf16 v[52:55], v[244:247], v[184:187], v[52:55]
	v_mfma_f32_16x16x32_bf16 v[56:59], v[240:243], v[220:223], v[56:59]
	v_mfma_f32_16x16x32_bf16 v[60:63], v[244:247], v[220:223], v[60:63]
	s_setprio 0
	s_cmp_lg_u32 s12, 0
	s_barrier
	s_cbranch_scc1 .LBB0_910
	s_barrier
